# residual-stream loads of the out/down epilogues regrouped to full 128-B lines (lane-pair exchange), on top of the tile hand-off and shortconv changes
# speedup vs baseline: 1.0187x; 1.0065x over previous
; __device__ __forceinline__ unsigned pk2(float lo, float hi) { return pg8::cvt_pk_bf16(lo, hi); }
;     __device__ __forceinline__ void operator()(const f32x4 (&acc)[2][2][4][2], const pg8::Unit& u, int wr, int wc, int fr, int fq) const {
;     ...
;         for (int ai = 0; ai < 2; ++ai)
; #pragma unroll
;             for (int m = 0; m < 4; ++m) {
;                 const int R = rowbase + u.pm * 256 + ai * 128 + wr * 64 + m * 16 + fr;
;                 const float* src = islat ? rin_l + (size_t)R * DM : rin_c + (size_t)(R - TL) * DM;
;                 float* dst = islat ? rout_l + (size_t)R * DM : rout_c + (size_t)(R - TL) * DM;
;                 float ss = 0.f;
; #pragma unroll
;                 for (int bj = 0; bj < 2; ++bj) { const int c = u.pn * 256 + bj * 128 + wc * 32 + 8 * fq;
;                     const f32x4 xa = *(const f32x4*)(src + c) + gv[bj][0] * acc[ai][bj][m][0];
;                     const f32x4 xb = *(const f32x4*)(src + c + 4) + gv[bj][1] * acc[ai][bj][m][1];
;                     *(f32x4*)(dst + c) = xa; *(f32x4*)(dst + c + 4) = xb;
;                     ss += (xa[0] * xa[0] + xa[1] * xa[1]) + (xa[2] * xa[2] + xa[3] * xa[3]) + (xb[0] * xb[0] + xb[1] * xb[1]) + (xb[2] * xb[2] + xb[3] * xb[3]);
;                     const f32x4 ya = xa * sv[bj][0], yb = xb * sv[bj][1];
;                     u32x4 w; w.x = pk2(ya[0], ya[1]); w.y = pk2(ya[2], ya[3]); w.z = pk2(yb[0], yb[1]); w.w = pk2(yb[2], yb[3]);
;                     *(u32x4*)(Hn + (size_t)R * DM + c) = w; }
.LBB0_922:
	s_lshl_b32 s24, s24, 2
	s_ashr_i32 s25, s24, 31
	v_cndmask_b32_e64 v202, v194, v190, s[42:43]
	s_and_b64 s[8:9], s[42:43], exec
	v_ashrrev_i32_e32 v203, 31, v202
	s_cselect_b32 s69, s19, s49
	s_cselect_b32 s68, s18, s48
	v_lshlrev_b64 v[202:203], 12, v[202:203]
	v_lshl_add_u64 v[202:203], s[68:69], 0, v[202:203]
	v_lshl_add_u64 v[212:213], v[202:203], 0, v[188:189]
	s_mov_b32 s100, 0xaaaaaaaa
	s_mov_b32 s101, 0xaaaaaaaa
	v_mov_b32_e32 v222, 0x1000
	v_mov_b32_e32 v223, 16
	v_cndmask_b32_e64 v242, v222, v223, s[100:101]
	v_mov_b32_e32 v243, 0
	v_lshl_add_u64 v[226:227], v[212:213], 0, v[242:243]
	global_load_dwordx4 v[214:217], v[226:227], off offset:-4096
	global_load_dwordx4 v[218:221], v[226:227], off
	v_lshlrev_b64 v[210:211], 11, v[190:191]
	v_and_b32_e32 v200, 64, v228
	v_xor_b32_e32 v195, 16, v228
	v_add_u32_e32 v201, 64, v200
	v_cmp_lt_i32_e32 vcc, v195, v201
	s_waitcnt vmcnt(0)
	v_cndmask_b32_e64 v222, v218, v214, s[100:101]
	v_cndmask_b32_e64 v223, v219, v215, s[100:101]
	v_cndmask_b32_e64 v224, v220, v216, s[100:101]
	v_cndmask_b32_e64 v225, v221, v217, s[100:101]
	v_mov_b32_dpp v238, v222 quad_perm:[1,0,3,2] row_mask:0xf bank_mask:0xf
	v_mov_b32_dpp v239, v223 quad_perm:[1,0,3,2] row_mask:0xf bank_mask:0xf
	v_mov_b32_dpp v240, v224 quad_perm:[1,0,3,2] row_mask:0xf bank_mask:0xf
	v_mov_b32_dpp v241, v225 quad_perm:[1,0,3,2] row_mask:0xf bank_mask:0xf
	v_cndmask_b32_e64 v206, v214, v238, s[100:101]
	v_cndmask_b32_e64 v202, v238, v218, s[100:101]
	v_cndmask_b32_e64 v207, v215, v239, s[100:101]
	v_cndmask_b32_e64 v203, v239, v219, s[100:101]
	v_cndmask_b32_e64 v208, v216, v240, s[100:101]
	v_cndmask_b32_e64 v204, v240, v220, s[100:101]
	v_cndmask_b32_e64 v209, v217, v241, s[100:101]
	v_cndmask_b32_e64 v205, v241, v221, s[100:101]
	v_pk_fma_f32 v[204:205], v[156:157], v[88:89], v[204:205]
	v_pk_fma_f32 v[160:161], v[160:161], v[96:97], v[208:209]
	v_pk_fma_f32 v[158:159], v[158:159], v[94:95], v[206:207]
	v_mul_f32_e32 v157, v161, v161
	v_mul_f32_e32 v156, v159, v159
	v_pk_fma_f32 v[202:203], v[154:155], v[86:87], v[202:203]
	v_fmac_f32_e32 v156, v158, v158
	v_fmac_f32_e32 v157, v160, v160
	v_add_f32_e32 v156, v156, v157
	v_mul_f32_e32 v157, v203, v203
	v_fmac_f32_e32 v157, v202, v202
	v_add_f32_e32 v156, v156, v157
	v_mul_f32_e32 v157, v205, v205
	v_lshl_add_u64 v[154:155], v[192:193], 0, v[188:189]
	v_fmac_f32_e32 v157, v204, v204
	v_cndmask_b32_e64 v222, v202, v158, s[100:101]
	v_cndmask_b32_e64 v223, v203, v159, s[100:101]
	v_cndmask_b32_e64 v224, v204, v160, s[100:101]
	v_cndmask_b32_e64 v225, v205, v161, s[100:101]
	v_mov_b32_dpp v238, v222 quad_perm:[1,0,3,2] row_mask:0xf bank_mask:0xf
	v_mov_b32_dpp v239, v223 quad_perm:[1,0,3,2] row_mask:0xf bank_mask:0xf
	v_mov_b32_dpp v240, v224 quad_perm:[1,0,3,2] row_mask:0xf bank_mask:0xf
	v_mov_b32_dpp v241, v225 quad_perm:[1,0,3,2] row_mask:0xf bank_mask:0xf
	v_cndmask_b32_e64 v214, v158, v238, s[100:101]
	v_cndmask_b32_e64 v218, v238, v202, s[100:101]
	v_cndmask_b32_e64 v215, v159, v239, s[100:101]
	v_cndmask_b32_e64 v219, v239, v203, s[100:101]
	v_cndmask_b32_e64 v216, v160, v240, s[100:101]
	v_cndmask_b32_e64 v220, v240, v204, s[100:101]
	v_cndmask_b32_e64 v217, v161, v241, s[100:101]
	v_cndmask_b32_e64 v221, v241, v205, s[100:101]
	v_lshl_add_u64 v[226:227], v[154:155], 0, v[242:243]
	global_store_dwordx4 v[226:227], v[214:217], off offset:-4096
	global_store_dwordx4 v[226:227], v[218:221], off
	v_add_f32_e32 v194, v157, v156
	v_pk_mul_f32 v[160:161], v[92:93], v[160:161]
	v_pk_mul_f32 v[156:157], v[90:91], v[158:159]
	v_pk_mul_f32 v[192:193], v[84:85], v[204:205]
	v_pk_mul_f32 v[158:159], v[82:83], v[202:203]
	v_cvt_pk_bf16_f32 v156, v156, v157
	v_cvt_pk_bf16_f32 v157, v160, v161
	v_lshl_add_u64 v[160:161], s[60:61], 0, v[210:211]
	v_cvt_pk_bf16_f32 v158, v158, v159
	v_cvt_pk_bf16_f32 v159, v192, v193
	v_lshl_add_u64 v[160:161], v[186:187], 1, v[160:161]
	global_store_dwordx4 v[160:161], v[156:159], off
	v_lshl_add_u64 v[226:227], v[212:213], 0, v[242:243]
	global_load_dwordx4 v[214:217], v[226:227], off offset:-3584
	global_load_dwordx4 v[218:221], v[226:227], off offset:512
	s_nop 0
	v_cndmask_b32_e32 v195, v228, v195, vcc
	v_lshlrev_b32_e32 v200, 2, v195
	v_xor_b32_e32 v195, 32, v228
	v_cmp_lt_i32_e32 vcc, v195, v201
	s_waitcnt vmcnt(0)
; __device__ __forceinline__ unsigned pk2(float lo, float hi) { return pg8::cvt_pk_bf16(lo, hi); }
;     __device__ __forceinline__ void operator()(const f32x4 (&acc)[2][2][4][2], const pg8::Unit& u, int wr, int wc, int fr, int fq) const {
;     ...
;                 for (int bj = 0; bj < 2; ++bj) { const int c = u.pn * 256 + bj * 128 + wc * 32 + 8 * fq;
;                     const f32x4 xa = *(const f32x4*)(src + c) + gv[bj][0] * acc[ai][bj][m][0];
;                     const f32x4 xb = *(const f32x4*)(src + c + 4) + gv[bj][1] * acc[ai][bj][m][1];
;                     *(f32x4*)(dst + c) = xa; *(f32x4*)(dst + c + 4) = xb;
;                     ss += (xa[0] * xa[0] + xa[1] * xa[1]) + (xa[2] * xa[2] + xa[3] * xa[3]) + (xb[0] * xb[0] + xb[1] * xb[1]) + (xb[2] * xb[2] + xb[3] * xb[3]);
;                     const f32x4 ya = xa * sv[bj][0], yb = xb * sv[bj][1];
;                     u32x4 w; w.x = pk2(ya[0], ya[1]); w.y = pk2(ya[2], ya[3]); w.z = pk2(yb[0], yb[1]); w.w = pk2(yb[2], yb[3]);
;                     *(u32x4*)(Hn + (size_t)R * DM + c) = w; }
;                 ss += __shfl_xor(ss, 16); ss += __shfl_xor(ss, 32);
;                 if (fq == 0) stat[(size_t)R * 16 + u.pn * 4 + wc] = ss;
	v_cndmask_b32_e64 v222, v218, v214, s[100:101]
	v_cndmask_b32_e64 v223, v219, v215, s[100:101]
	v_cndmask_b32_e64 v224, v220, v216, s[100:101]
	v_cndmask_b32_e64 v225, v221, v217, s[100:101]
	v_mov_b32_dpp v238, v222 quad_perm:[1,0,3,2] row_mask:0xf bank_mask:0xf
	v_mov_b32_dpp v239, v223 quad_perm:[1,0,3,2] row_mask:0xf bank_mask:0xf
	v_mov_b32_dpp v240, v224 quad_perm:[1,0,3,2] row_mask:0xf bank_mask:0xf
	v_mov_b32_dpp v241, v225 quad_perm:[1,0,3,2] row_mask:0xf bank_mask:0xf
	v_cndmask_b32_e64 v202, v214, v238, s[100:101]
	v_cndmask_b32_e64 v156, v238, v218, s[100:101]
	v_cndmask_b32_e64 v203, v215, v239, s[100:101]
	v_cndmask_b32_e64 v157, v239, v219, s[100:101]
	v_cndmask_b32_e64 v204, v216, v240, s[100:101]
	v_cndmask_b32_e64 v158, v240, v220, s[100:101]
	v_cndmask_b32_e64 v205, v217, v241, s[100:101]
	v_cndmask_b32_e64 v159, v241, v221, s[100:101]
	v_pk_fma_f32 v[148:149], v[148:149], v[76:77], v[158:159]
	s_waitcnt vmcnt(0)
	v_pk_fma_f32 v[152:153], v[152:153], v[80:81], v[204:205]
	v_pk_fma_f32 v[150:151], v[150:151], v[78:79], v[202:203]
	v_pk_fma_f32 v[146:147], v[146:147], v[74:75], v[156:157]
	v_cndmask_b32_e64 v222, v146, v150, s[100:101]
	v_cndmask_b32_e64 v223, v147, v151, s[100:101]
	v_cndmask_b32_e64 v224, v148, v152, s[100:101]
	v_cndmask_b32_e64 v225, v149, v153, s[100:101]
	v_mov_b32_dpp v238, v222 quad_perm:[1,0,3,2] row_mask:0xf bank_mask:0xf
	v_mov_b32_dpp v239, v223 quad_perm:[1,0,3,2] row_mask:0xf bank_mask:0xf
	v_mov_b32_dpp v240, v224 quad_perm:[1,0,3,2] row_mask:0xf bank_mask:0xf
	v_mov_b32_dpp v241, v225 quad_perm:[1,0,3,2] row_mask:0xf bank_mask:0xf
	v_cndmask_b32_e64 v214, v150, v238, s[100:101]
	v_cndmask_b32_e64 v218, v238, v146, s[100:101]
	v_cndmask_b32_e64 v215, v151, v239, s[100:101]
	v_cndmask_b32_e64 v219, v239, v147, s[100:101]
	v_cndmask_b32_e64 v216, v152, v240, s[100:101]
	v_cndmask_b32_e64 v220, v240, v148, s[100:101]
	v_cndmask_b32_e64 v217, v153, v241, s[100:101]
	v_cndmask_b32_e64 v221, v241, v149, s[100:101]
	v_lshl_add_u64 v[226:227], v[154:155], 0, v[242:243]
	global_store_dwordx4 v[226:227], v[214:217], off offset:-3584
	global_store_dwordx4 v[226:227], v[218:221], off offset:512
	v_mul_f32_e32 v154, v151, v151
	v_mul_f32_e32 v155, v153, v153
	v_fmac_f32_e32 v154, v150, v150
	v_fmac_f32_e32 v155, v152, v152
	v_add_f32_e32 v154, v154, v155
	v_mul_f32_e32 v155, v147, v147
	v_fmac_f32_e32 v155, v146, v146
	v_add_f32_e32 v154, v154, v155
	v_mul_f32_e32 v155, v149, v149
	v_fmac_f32_e32 v155, v148, v148
	v_add_f32_e32 v154, v155, v154
	v_add_f32_e32 v156, v194, v154
	v_pk_mul_f32 v[152:153], v[64:65], v[152:153]
	v_pk_mul_f32 v[150:151], v[62:63], v[150:151]
	v_pk_mul_f32 v[154:155], v[60:61], v[148:149]
	v_pk_mul_f32 v[148:149], v[58:59], v[146:147]
	v_cvt_pk_bf16_f32 v146, v150, v151
	v_cvt_pk_bf16_f32 v147, v152, v153
	v_cvt_pk_bf16_f32 v148, v148, v149
	v_cvt_pk_bf16_f32 v149, v154, v155
	global_store_dwordx4 v[160:161], v[146:149], off offset:256
	ds_bpermute_b32 v146, v200, v156
	v_cndmask_b32_e32 v195, v228, v195, vcc
	v_lshlrev_b32_e32 v195, 2, v195
	s_waitcnt lgkmcnt(0)
	v_add_f32_e32 v146, v156, v146
	ds_bpermute_b32 v147, v195, v146
	s_and_saveexec_b64 s[34:35], s[38:39]
	s_cbranch_execz .LBB0_924
	v_lshlrev_b64 v[148:149], 6, v[190:191]
	v_lshl_add_u64 v[148:149], s[62:63], 0, v[148:149]
	v_lshl_add_u64 v[148:149], s[24:25], 2, v[148:149]
	s_lshl_b32 s0, s47, 2
	v_lshl_add_u64 v[148:149], v[148:149], 0, s[0:1]
	s_waitcnt lgkmcnt(0)
	v_add_f32_e32 v146, v146, v147
	global_store_dword v[148:149], v146, off

; __device__ __forceinline__ unsigned pk2(float lo, float hi) { return pg8::cvt_pk_bf16(lo, hi); }
;     __device__ __forceinline__ void operator()(const f32x4 (&acc)[2][2][4][2], const pg8::Unit& u, int wr, int wc, int fr, int fq) const {
;     ...
;             for (int m = 0; m < 4; ++m) {
;                 const int R = rowbase + u.pm * 256 + ai * 128 + wr * 64 + m * 16 + fr;
;                 const float* src = islat ? rin_l + (size_t)R * DM : rin_c + (size_t)(R - TL) * DM;
;                 float* dst = islat ? rout_l + (size_t)R * DM : rout_c + (size_t)(R - TL) * DM;
;                 float ss = 0.f;
; #pragma unroll
;                 for (int bj = 0; bj < 2; ++bj) { const int c = u.pn * 256 + bj * 128 + wc * 32 + 8 * fq;
;                     const f32x4 xa = *(const f32x4*)(src + c) + gv[bj][0] * acc[ai][bj][m][0];
;                     const f32x4 xb = *(const f32x4*)(src + c + 4) + gv[bj][1] * acc[ai][bj][m][1];
;                     *(f32x4*)(dst + c) = xa; *(f32x4*)(dst + c + 4) = xb;
;                     ss += (xa[0] * xa[0] + xa[1] * xa[1]) + (xa[2] * xa[2] + xa[3] * xa[3]) + (xb[0] * xb[0] + xb[1] * xb[1]) + (xb[2] * xb[2] + xb[3] * xb[3]);
;                     const f32x4 ya = xa * sv[bj][0], yb = xb * sv[bj][1];
;                     u32x4 w; w.x = pk2(ya[0], ya[1]); w.y = pk2(ya[2], ya[3]); w.z = pk2(yb[0], yb[1]); w.w = pk2(yb[2], yb[3]);
;                     *(u32x4*)(Hn + (size_t)R * DM + c) = w; }
.LBB0_928:
	v_cndmask_b32_e64 v150, v150, v146, s[42:43]
	v_ashrrev_i32_e32 v151, 31, v150
	v_lshlrev_b64 v[150:151], 12, v[150:151]
	v_lshl_add_u64 v[150:151], s[68:69], 0, v[150:151]
	v_lshl_add_u64 v[158:159], v[150:151], 0, v[188:189]
	v_lshl_add_u64 v[226:227], v[158:159], 0, v[242:243]
	global_load_dwordx4 v[214:217], v[226:227], off offset:-4096
	global_load_dwordx4 v[218:221], v[226:227], off
	v_lshlrev_b64 v[160:161], 11, v[146:147]
	v_lshl_add_u64 v[192:193], v[148:149], 0, v[188:189]
	v_lshl_add_u64 v[148:149], s[60:61], 0, v[160:161]
	v_lshl_add_u64 v[160:161], v[186:187], 1, v[148:149]
	s_waitcnt vmcnt(0)
	v_cndmask_b32_e64 v222, v218, v214, s[100:101]
	v_cndmask_b32_e64 v223, v219, v215, s[100:101]
	v_cndmask_b32_e64 v224, v220, v216, s[100:101]
	v_cndmask_b32_e64 v225, v221, v217, s[100:101]
	v_mov_b32_dpp v238, v222 quad_perm:[1,0,3,2] row_mask:0xf bank_mask:0xf
	v_mov_b32_dpp v239, v223 quad_perm:[1,0,3,2] row_mask:0xf bank_mask:0xf
	v_mov_b32_dpp v240, v224 quad_perm:[1,0,3,2] row_mask:0xf bank_mask:0xf
	v_mov_b32_dpp v241, v225 quad_perm:[1,0,3,2] row_mask:0xf bank_mask:0xf
	v_cndmask_b32_e64 v150, v214, v238, s[100:101]
	v_cndmask_b32_e64 v154, v238, v218, s[100:101]
	v_cndmask_b32_e64 v151, v215, v239, s[100:101]
	v_cndmask_b32_e64 v155, v239, v219, s[100:101]
	v_cndmask_b32_e64 v152, v216, v240, s[100:101]
	v_cndmask_b32_e64 v156, v240, v220, s[100:101]
	v_cndmask_b32_e64 v153, v217, v241, s[100:101]
	v_cndmask_b32_e64 v157, v241, v221, s[100:101]
	v_pk_fma_f32 v[144:145], v[144:145], v[96:97], v[152:153]
	v_pk_fma_f32 v[142:143], v[142:143], v[94:95], v[150:151]
	s_waitcnt vmcnt(0)
	v_pk_fma_f32 v[140:141], v[140:141], v[88:89], v[156:157]
	v_pk_fma_f32 v[138:139], v[138:139], v[86:87], v[154:155]
	v_pk_mul_f32 v[150:151], v[92:93], v[144:145]
	v_pk_mul_f32 v[148:149], v[90:91], v[142:143]
	v_pk_mul_f32 v[152:153], v[84:85], v[140:141]
	v_pk_mul_f32 v[154:155], v[82:83], v[138:139]
	v_cvt_pk_bf16_f32 v148, v148, v149
	v_cvt_pk_bf16_f32 v149, v150, v151
	v_cvt_pk_bf16_f32 v150, v154, v155
	v_cvt_pk_bf16_f32 v151, v152, v153
	v_cndmask_b32_e64 v222, v138, v142, s[100:101]
	v_cndmask_b32_e64 v223, v139, v143, s[100:101]
	v_cndmask_b32_e64 v224, v140, v144, s[100:101]
	v_cndmask_b32_e64 v225, v141, v145, s[100:101]
	v_mov_b32_dpp v238, v222 quad_perm:[1,0,3,2] row_mask:0xf bank_mask:0xf
	v_mov_b32_dpp v239, v223 quad_perm:[1,0,3,2] row_mask:0xf bank_mask:0xf
	v_mov_b32_dpp v240, v224 quad_perm:[1,0,3,2] row_mask:0xf bank_mask:0xf
	v_mov_b32_dpp v241, v225 quad_perm:[1,0,3,2] row_mask:0xf bank_mask:0xf
	v_cndmask_b32_e64 v214, v142, v238, s[100:101]
	v_cndmask_b32_e64 v218, v238, v138, s[100:101]
	v_cndmask_b32_e64 v215, v143, v239, s[100:101]
	v_cndmask_b32_e64 v219, v239, v139, s[100:101]
	v_cndmask_b32_e64 v216, v144, v240, s[100:101]
	v_cndmask_b32_e64 v220, v240, v140, s[100:101]
	v_cndmask_b32_e64 v217, v145, v241, s[100:101]
	v_cndmask_b32_e64 v221, v241, v141, s[100:101]
	v_lshl_add_u64 v[226:227], v[192:193], 0, v[242:243]
	global_store_dwordx4 v[226:227], v[214:217], off offset:-4096
	global_store_dwordx4 v[226:227], v[218:221], off
	global_store_dwordx4 v[160:161], v[148:151], off
	v_lshl_add_u64 v[226:227], v[158:159], 0, v[242:243]
	global_load_dwordx4 v[214:217], v[226:227], off offset:-3584
	global_load_dwordx4 v[218:221], v[226:227], off offset:512
	s_nop 0
	v_mul_f32_e32 v143, v143, v143
	v_mul_f32_e32 v145, v145, v145
	v_mul_f32_e32 v139, v139, v139
	v_fmac_f32_e32 v143, v142, v142
	v_fmac_f32_e32 v145, v144, v144
	v_mul_f32_e32 v141, v141, v141
	v_fmac_f32_e32 v139, v138, v138
	v_add_f32_e32 v138, v143, v145
	v_fmac_f32_e32 v141, v140, v140
	v_add_f32_e32 v138, v138, v139
	v_add_f32_e32 v138, v141, v138
	s_waitcnt vmcnt(0)
	v_cndmask_b32_e64 v222, v218, v214, s[100:101]
	v_cndmask_b32_e64 v223, v219, v215, s[100:101]
	v_cndmask_b32_e64 v224, v220, v216, s[100:101]
	v_cndmask_b32_e64 v225, v221, v217, s[100:101]
	v_mov_b32_dpp v238, v222 quad_perm:[1,0,3,2] row_mask:0xf bank_mask:0xf
	v_mov_b32_dpp v239, v223 quad_perm:[1,0,3,2] row_mask:0xf bank_mask:0xf
	v_mov_b32_dpp v240, v224 quad_perm:[1,0,3,2] row_mask:0xf bank_mask:0xf
	v_mov_b32_dpp v241, v225 quad_perm:[1,0,3,2] row_mask:0xf bank_mask:0xf
	v_cndmask_b32_e64 v148, v214, v238, s[100:101]
	v_cndmask_b32_e64 v152, v238, v218, s[100:101]
	v_cndmask_b32_e64 v149, v215, v239, s[100:101]
	v_cndmask_b32_e64 v153, v239, v219, s[100:101]
	v_cndmask_b32_e64 v150, v216, v240, s[100:101]
	v_cndmask_b32_e64 v154, v240, v220, s[100:101]
	v_cndmask_b32_e64 v151, v217, v241, s[100:101]
	v_cndmask_b32_e64 v155, v241, v221, s[100:101]
	v_pk_fma_f32 v[136:137], v[136:137], v[80:81], v[150:151]
	v_pk_fma_f32 v[134:135], v[134:135], v[78:79], v[148:149]
	s_waitcnt vmcnt(0)
	v_pk_fma_f32 v[130:131], v[130:131], v[74:75], v[152:153]
	v_mul_f32_e32 v139, v135, v135
	v_mul_f32_e32 v140, v137, v137
	v_pk_fma_f32 v[132:133], v[132:133], v[76:77], v[154:155]
	v_mul_f32_e32 v141, v131, v131
	v_fmac_f32_e32 v139, v134, v134
	v_fmac_f32_e32 v140, v136, v136
	v_mul_f32_e32 v142, v133, v133
	v_fmac_f32_e32 v141, v130, v130
	v_add_f32_e32 v139, v139, v140
	v_fmac_f32_e32 v142, v132, v132
	v_add_f32_e32 v139, v139, v141
	v_add_f32_e32 v139, v142, v139
	v_add_f32_e32 v142, v138, v139
	ds_bpermute_b32 v143, v200, v142
	v_cndmask_b32_e64 v222, v130, v134, s[100:101]
	v_cndmask_b32_e64 v223, v131, v135, s[100:101]
	v_cndmask_b32_e64 v224, v132, v136, s[100:101]
	v_cndmask_b32_e64 v225, v133, v137, s[100:101]
	v_mov_b32_dpp v238, v222 quad_perm:[1,0,3,2] row_mask:0xf bank_mask:0xf
	v_mov_b32_dpp v239, v223 quad_perm:[1,0,3,2] row_mask:0xf bank_mask:0xf
	v_mov_b32_dpp v240, v224 quad_perm:[1,0,3,2] row_mask:0xf bank_mask:0xf
	v_mov_b32_dpp v241, v225 quad_perm:[1,0,3,2] row_mask:0xf bank_mask:0xf
	v_cndmask_b32_e64 v214, v134, v238, s[100:101]
	v_cndmask_b32_e64 v218, v238, v130, s[100:101]
	v_cndmask_b32_e64 v215, v135, v239, s[100:101]
	v_cndmask_b32_e64 v219, v239, v131, s[100:101]
	v_cndmask_b32_e64 v216, v136, v240, s[100:101]
	v_cndmask_b32_e64 v220, v240, v132, s[100:101]
	v_cndmask_b32_e64 v217, v137, v241, s[100:101]
	v_cndmask_b32_e64 v221, v241, v133, s[100:101]
	v_lshl_add_u64 v[226:227], v[192:193], 0, v[242:243]
	global_store_dwordx4 v[226:227], v[214:217], off offset:-3584
	global_store_dwordx4 v[226:227], v[218:221], off offset:512
	v_pk_mul_f32 v[140:141], v[58:59], v[130:131]
	v_pk_mul_f32 v[136:137], v[64:65], v[136:137]
	v_pk_mul_f32 v[134:135], v[62:63], v[134:135]
	s_waitcnt lgkmcnt(0)
	v_add_f32_e32 v130, v142, v143
	ds_bpermute_b32 v131, v195, v130
	v_pk_mul_f32 v[138:139], v[60:61], v[132:133]
	v_cvt_pk_bf16_f32 v132, v134, v135
	v_cvt_pk_bf16_f32 v133, v136, v137
	v_cvt_pk_bf16_f32 v134, v140, v141
	v_cvt_pk_bf16_f32 v135, v138, v139
	global_store_dwordx4 v[160:161], v[132:135], off offset:256
	s_and_saveexec_b64 s[34:35], s[38:39]
	s_cbranch_execz .LBB0_930
;     __device__ __forceinline__ void operator()(const f32x4 (&acc)[2][2][4][2], const pg8::Unit& u, int wr, int wc, int fr, int fq) const {
;     ...
;                 if (fq == 0) stat[(size_t)R * 16 + u.pn * 4 + wc] = ss;
	v_lshlrev_b64 v[132:133], 6, v[146:147]
	v_lshl_add_u64 v[132:133], s[62:63], 0, v[132:133]
	v_lshl_add_u64 v[132:133], s[24:25], 2, v[132:133]
	s_lshl_b32 s0, s47, 2
	v_lshl_add_u64 v[132:133], v[132:133], 0, s[0:1]
	s_waitcnt lgkmcnt(0)
	v_add_f32_e32 v130, v130, v131
	global_store_dword v[132:133], v130, off

; __device__ __forceinline__ unsigned pk2(float lo, float hi) { return pg8::cvt_pk_bf16(lo, hi); }
;     __device__ __forceinline__ void operator()(const f32x4 (&acc)[2][2][4][2], const pg8::Unit& u, int wr, int wc, int fr, int fq) const {
;     ...
;             for (int m = 0; m < 4; ++m) {
;                 const int R = rowbase + u.pm * 256 + ai * 128 + wr * 64 + m * 16 + fr;
;                 const float* src = islat ? rin_l + (size_t)R * DM : rin_c + (size_t)(R - TL) * DM;
;                 float* dst = islat ? rout_l + (size_t)R * DM : rout_c + (size_t)(R - TL) * DM;
;                 float ss = 0.f;
; #pragma unroll
;                 for (int bj = 0; bj < 2; ++bj) { const int c = u.pn * 256 + bj * 128 + wc * 32 + 8 * fq;
;                     const f32x4 xa = *(const f32x4*)(src + c) + gv[bj][0] * acc[ai][bj][m][0];
;                     const f32x4 xb = *(const f32x4*)(src + c + 4) + gv[bj][1] * acc[ai][bj][m][1];
;                     *(f32x4*)(dst + c) = xa; *(f32x4*)(dst + c + 4) = xb;
;                     ss += (xa[0] * xa[0] + xa[1] * xa[1]) + (xa[2] * xa[2] + xa[3] * xa[3]) + (xb[0] * xb[0] + xb[1] * xb[1]) + (xb[2] * xb[2] + xb[3] * xb[3]);
;                     const f32x4 ya = xa * sv[bj][0], yb = xb * sv[bj][1];
;                     u32x4 w; w.x = pk2(ya[0], ya[1]); w.y = pk2(ya[2], ya[3]); w.z = pk2(yb[0], yb[1]); w.w = pk2(yb[2], yb[3]);
;                     *(u32x4*)(Hn + (size_t)R * DM + c) = w; }
.LBB0_934:
	v_cndmask_b32_e64 v134, v134, v130, s[42:43]
	v_ashrrev_i32_e32 v135, 31, v134
	v_lshlrev_b64 v[134:135], 12, v[134:135]
	v_lshl_add_u64 v[134:135], s[68:69], 0, v[134:135]
	v_lshl_add_u64 v[142:143], v[134:135], 0, v[188:189]
	v_lshl_add_u64 v[226:227], v[142:143], 0, v[242:243]
	global_load_dwordx4 v[214:217], v[226:227], off offset:-4096
	global_load_dwordx4 v[218:221], v[226:227], off
	v_lshlrev_b64 v[144:145], 11, v[130:131]
	v_lshl_add_u64 v[146:147], v[132:133], 0, v[188:189]
	v_lshl_add_u64 v[132:133], s[60:61], 0, v[144:145]
	v_lshl_add_u64 v[144:145], v[186:187], 1, v[132:133]
	s_waitcnt vmcnt(0)
	v_cndmask_b32_e64 v222, v218, v214, s[100:101]
	v_cndmask_b32_e64 v223, v219, v215, s[100:101]
	v_cndmask_b32_e64 v224, v220, v216, s[100:101]
	v_cndmask_b32_e64 v225, v221, v217, s[100:101]
	v_mov_b32_dpp v238, v222 quad_perm:[1,0,3,2] row_mask:0xf bank_mask:0xf
	v_mov_b32_dpp v239, v223 quad_perm:[1,0,3,2] row_mask:0xf bank_mask:0xf
	v_mov_b32_dpp v240, v224 quad_perm:[1,0,3,2] row_mask:0xf bank_mask:0xf
	v_mov_b32_dpp v241, v225 quad_perm:[1,0,3,2] row_mask:0xf bank_mask:0xf
	v_cndmask_b32_e64 v134, v214, v238, s[100:101]
	v_cndmask_b32_e64 v138, v238, v218, s[100:101]
	v_cndmask_b32_e64 v135, v215, v239, s[100:101]
	v_cndmask_b32_e64 v139, v239, v219, s[100:101]
	v_cndmask_b32_e64 v136, v216, v240, s[100:101]
	v_cndmask_b32_e64 v140, v240, v220, s[100:101]
	v_cndmask_b32_e64 v137, v217, v241, s[100:101]
	v_cndmask_b32_e64 v141, v241, v221, s[100:101]
	v_pk_fma_f32 v[128:129], v[128:129], v[96:97], v[136:137]
	v_pk_fma_f32 v[126:127], v[126:127], v[94:95], v[134:135]
	s_waitcnt vmcnt(0)
	v_pk_fma_f32 v[124:125], v[124:125], v[88:89], v[140:141]
	v_pk_fma_f32 v[122:123], v[122:123], v[86:87], v[138:139]
	v_pk_mul_f32 v[134:135], v[92:93], v[128:129]
	v_pk_mul_f32 v[132:133], v[90:91], v[126:127]
	v_pk_mul_f32 v[136:137], v[84:85], v[124:125]
	v_pk_mul_f32 v[138:139], v[82:83], v[122:123]
	v_cvt_pk_bf16_f32 v132, v132, v133
	v_cvt_pk_bf16_f32 v133, v134, v135
	v_cvt_pk_bf16_f32 v134, v138, v139
	v_cvt_pk_bf16_f32 v135, v136, v137
	v_cndmask_b32_e64 v222, v122, v126, s[100:101]
	v_cndmask_b32_e64 v223, v123, v127, s[100:101]
	v_cndmask_b32_e64 v224, v124, v128, s[100:101]
	v_cndmask_b32_e64 v225, v125, v129, s[100:101]
	v_mov_b32_dpp v238, v222 quad_perm:[1,0,3,2] row_mask:0xf bank_mask:0xf
	v_mov_b32_dpp v239, v223 quad_perm:[1,0,3,2] row_mask:0xf bank_mask:0xf
	v_mov_b32_dpp v240, v224 quad_perm:[1,0,3,2] row_mask:0xf bank_mask:0xf
	v_mov_b32_dpp v241, v225 quad_perm:[1,0,3,2] row_mask:0xf bank_mask:0xf
	v_cndmask_b32_e64 v214, v126, v238, s[100:101]
	v_cndmask_b32_e64 v218, v238, v122, s[100:101]
	v_cndmask_b32_e64 v215, v127, v239, s[100:101]
	v_cndmask_b32_e64 v219, v239, v123, s[100:101]
	v_cndmask_b32_e64 v216, v128, v240, s[100:101]
	v_cndmask_b32_e64 v220, v240, v124, s[100:101]
	v_cndmask_b32_e64 v217, v129, v241, s[100:101]
	v_cndmask_b32_e64 v221, v241, v125, s[100:101]
	v_lshl_add_u64 v[226:227], v[146:147], 0, v[242:243]
	global_store_dwordx4 v[226:227], v[214:217], off offset:-4096
	global_store_dwordx4 v[226:227], v[218:221], off
	global_store_dwordx4 v[144:145], v[132:135], off
	v_lshl_add_u64 v[226:227], v[142:143], 0, v[242:243]
	global_load_dwordx4 v[214:217], v[226:227], off offset:-3584
	global_load_dwordx4 v[218:221], v[226:227], off offset:512
	s_nop 0
	v_mul_f32_e32 v127, v127, v127
	v_mul_f32_e32 v129, v129, v129
	v_mul_f32_e32 v123, v123, v123
	v_fmac_f32_e32 v127, v126, v126
	v_fmac_f32_e32 v129, v128, v128
	v_mul_f32_e32 v125, v125, v125
	v_fmac_f32_e32 v123, v122, v122
	v_add_f32_e32 v122, v127, v129
	v_fmac_f32_e32 v125, v124, v124
	v_add_f32_e32 v122, v122, v123
	v_add_f32_e32 v122, v125, v122
	s_waitcnt vmcnt(0)
	v_cndmask_b32_e64 v222, v218, v214, s[100:101]
	v_cndmask_b32_e64 v223, v219, v215, s[100:101]
	v_cndmask_b32_e64 v224, v220, v216, s[100:101]
	v_cndmask_b32_e64 v225, v221, v217, s[100:101]
	v_mov_b32_dpp v238, v222 quad_perm:[1,0,3,2] row_mask:0xf bank_mask:0xf
	v_mov_b32_dpp v239, v223 quad_perm:[1,0,3,2] row_mask:0xf bank_mask:0xf
	v_mov_b32_dpp v240, v224 quad_perm:[1,0,3,2] row_mask:0xf bank_mask:0xf
	v_mov_b32_dpp v241, v225 quad_perm:[1,0,3,2] row_mask:0xf bank_mask:0xf
	v_cndmask_b32_e64 v132, v214, v238, s[100:101]
	v_cndmask_b32_e64 v136, v238, v218, s[100:101]
	v_cndmask_b32_e64 v133, v215, v239, s[100:101]
	v_cndmask_b32_e64 v137, v239, v219, s[100:101]
	v_cndmask_b32_e64 v134, v216, v240, s[100:101]
	v_cndmask_b32_e64 v138, v240, v220, s[100:101]
	v_cndmask_b32_e64 v135, v217, v241, s[100:101]
	v_cndmask_b32_e64 v139, v241, v221, s[100:101]
	v_pk_fma_f32 v[120:121], v[120:121], v[80:81], v[134:135]
	v_pk_fma_f32 v[118:119], v[118:119], v[78:79], v[132:133]
	s_waitcnt vmcnt(0)
	v_pk_fma_f32 v[114:115], v[114:115], v[74:75], v[136:137]
	v_mul_f32_e32 v123, v119, v119
	v_mul_f32_e32 v124, v121, v121
	v_pk_fma_f32 v[116:117], v[116:117], v[76:77], v[138:139]
	v_mul_f32_e32 v125, v115, v115
	v_fmac_f32_e32 v123, v118, v118
	v_fmac_f32_e32 v124, v120, v120
	v_mul_f32_e32 v126, v117, v117
	v_fmac_f32_e32 v125, v114, v114
	v_add_f32_e32 v123, v123, v124
	v_fmac_f32_e32 v126, v116, v116
	v_add_f32_e32 v123, v123, v125
	v_add_f32_e32 v123, v126, v123
	v_add_f32_e32 v126, v122, v123
	ds_bpermute_b32 v127, v200, v126
	v_cndmask_b32_e64 v222, v114, v118, s[100:101]
	v_cndmask_b32_e64 v223, v115, v119, s[100:101]
	v_cndmask_b32_e64 v224, v116, v120, s[100:101]
	v_cndmask_b32_e64 v225, v117, v121, s[100:101]
	v_mov_b32_dpp v238, v222 quad_perm:[1,0,3,2] row_mask:0xf bank_mask:0xf
	v_mov_b32_dpp v239, v223 quad_perm:[1,0,3,2] row_mask:0xf bank_mask:0xf
	v_mov_b32_dpp v240, v224 quad_perm:[1,0,3,2] row_mask:0xf bank_mask:0xf
	v_mov_b32_dpp v241, v225 quad_perm:[1,0,3,2] row_mask:0xf bank_mask:0xf
	v_cndmask_b32_e64 v214, v118, v238, s[100:101]
	v_cndmask_b32_e64 v218, v238, v114, s[100:101]
	v_cndmask_b32_e64 v215, v119, v239, s[100:101]
	v_cndmask_b32_e64 v219, v239, v115, s[100:101]
	v_cndmask_b32_e64 v216, v120, v240, s[100:101]
	v_cndmask_b32_e64 v220, v240, v116, s[100:101]
	v_cndmask_b32_e64 v217, v121, v241, s[100:101]
	v_cndmask_b32_e64 v221, v241, v117, s[100:101]
	v_lshl_add_u64 v[226:227], v[146:147], 0, v[242:243]
	global_store_dwordx4 v[226:227], v[214:217], off offset:-3584
	global_store_dwordx4 v[226:227], v[218:221], off offset:512
	v_pk_mul_f32 v[124:125], v[58:59], v[114:115]
	v_pk_mul_f32 v[120:121], v[64:65], v[120:121]
	v_pk_mul_f32 v[118:119], v[62:63], v[118:119]
	s_waitcnt lgkmcnt(0)
	v_add_f32_e32 v114, v126, v127
	ds_bpermute_b32 v115, v195, v114
	v_pk_mul_f32 v[122:123], v[60:61], v[116:117]
	v_cvt_pk_bf16_f32 v116, v118, v119
	v_cvt_pk_bf16_f32 v117, v120, v121
	v_cvt_pk_bf16_f32 v118, v124, v125
	v_cvt_pk_bf16_f32 v119, v122, v123
	global_store_dwordx4 v[144:145], v[116:119], off offset:256
	s_and_saveexec_b64 s[34:35], s[38:39]
	s_cbranch_execz .LBB0_936
;     __device__ __forceinline__ void operator()(const f32x4 (&acc)[2][2][4][2], const pg8::Unit& u, int wr, int wc, int fr, int fq) const {
;     ...
;                 if (fq == 0) stat[(size_t)R * 16 + u.pn * 4 + wc] = ss;
	v_lshlrev_b64 v[116:117], 6, v[130:131]
	v_lshl_add_u64 v[116:117], s[62:63], 0, v[116:117]
	v_lshl_add_u64 v[116:117], s[24:25], 2, v[116:117]
	s_lshl_b32 s0, s47, 2
	v_lshl_add_u64 v[116:117], v[116:117], 0, s[0:1]
	s_waitcnt lgkmcnt(0)
	v_add_f32_e32 v114, v114, v115
	global_store_dword v[116:117], v114, off

; __device__ __forceinline__ unsigned pk2(float lo, float hi) { return pg8::cvt_pk_bf16(lo, hi); }
;     __device__ __forceinline__ void operator()(const f32x4 (&acc)[2][2][4][2], const pg8::Unit& u, int wr, int wc, int fr, int fq) const {
;     ...
;             for (int m = 0; m < 4; ++m) {
;                 const int R = rowbase + u.pm * 256 + ai * 128 + wr * 64 + m * 16 + fr;
;                 const float* src = islat ? rin_l + (size_t)R * DM : rin_c + (size_t)(R - TL) * DM;
;                 float* dst = islat ? rout_l + (size_t)R * DM : rout_c + (size_t)(R - TL) * DM;
;                 float ss = 0.f;
; #pragma unroll
;                 for (int bj = 0; bj < 2; ++bj) { const int c = u.pn * 256 + bj * 128 + wc * 32 + 8 * fq;
;                     const f32x4 xa = *(const f32x4*)(src + c) + gv[bj][0] * acc[ai][bj][m][0];
;                     const f32x4 xb = *(const f32x4*)(src + c + 4) + gv[bj][1] * acc[ai][bj][m][1];
;                     *(f32x4*)(dst + c) = xa; *(f32x4*)(dst + c + 4) = xb;
;                     ss += (xa[0] * xa[0] + xa[1] * xa[1]) + (xa[2] * xa[2] + xa[3] * xa[3]) + (xb[0] * xb[0] + xb[1] * xb[1]) + (xb[2] * xb[2] + xb[3] * xb[3]);
;                     const f32x4 ya = xa * sv[bj][0], yb = xb * sv[bj][1];
;                     u32x4 w; w.x = pk2(ya[0], ya[1]); w.y = pk2(ya[2], ya[3]); w.z = pk2(yb[0], yb[1]); w.w = pk2(yb[2], yb[3]);
;                     *(u32x4*)(Hn + (size_t)R * DM + c) = w; }
.LBB0_940:
	v_cndmask_b32_e64 v118, v118, v114, s[42:43]
	v_ashrrev_i32_e32 v119, 31, v118
	v_lshlrev_b64 v[118:119], 12, v[118:119]
	v_lshl_add_u64 v[118:119], s[68:69], 0, v[118:119]
	v_lshl_add_u64 v[126:127], v[118:119], 0, v[188:189]
	v_lshl_add_u64 v[226:227], v[126:127], 0, v[242:243]
	global_load_dwordx4 v[214:217], v[226:227], off offset:-4096
	global_load_dwordx4 v[218:221], v[226:227], off
	v_lshlrev_b64 v[128:129], 11, v[114:115]
	v_lshl_add_u64 v[130:131], v[116:117], 0, v[188:189]
	v_lshl_add_u64 v[116:117], s[60:61], 0, v[128:129]
	v_lshl_add_u64 v[128:129], v[186:187], 1, v[116:117]
	s_waitcnt vmcnt(0)
	v_cndmask_b32_e64 v222, v218, v214, s[100:101]
	v_cndmask_b32_e64 v223, v219, v215, s[100:101]
	v_cndmask_b32_e64 v224, v220, v216, s[100:101]
	v_cndmask_b32_e64 v225, v221, v217, s[100:101]
	v_mov_b32_dpp v238, v222 quad_perm:[1,0,3,2] row_mask:0xf bank_mask:0xf
	v_mov_b32_dpp v239, v223 quad_perm:[1,0,3,2] row_mask:0xf bank_mask:0xf
	v_mov_b32_dpp v240, v224 quad_perm:[1,0,3,2] row_mask:0xf bank_mask:0xf
	v_mov_b32_dpp v241, v225 quad_perm:[1,0,3,2] row_mask:0xf bank_mask:0xf
	v_cndmask_b32_e64 v118, v214, v238, s[100:101]
	v_cndmask_b32_e64 v122, v238, v218, s[100:101]
	v_cndmask_b32_e64 v119, v215, v239, s[100:101]
	v_cndmask_b32_e64 v123, v239, v219, s[100:101]
	v_cndmask_b32_e64 v120, v216, v240, s[100:101]
	v_cndmask_b32_e64 v124, v240, v220, s[100:101]
	v_cndmask_b32_e64 v121, v217, v241, s[100:101]
	v_cndmask_b32_e64 v125, v241, v221, s[100:101]
	v_pk_fma_f32 v[112:113], v[112:113], v[96:97], v[120:121]
	v_pk_fma_f32 v[110:111], v[110:111], v[94:95], v[118:119]
	s_waitcnt vmcnt(0)
	v_pk_fma_f32 v[108:109], v[108:109], v[88:89], v[124:125]
	v_pk_fma_f32 v[106:107], v[106:107], v[86:87], v[122:123]
	v_pk_mul_f32 v[118:119], v[92:93], v[112:113]
	v_pk_mul_f32 v[116:117], v[90:91], v[110:111]
	v_pk_mul_f32 v[120:121], v[84:85], v[108:109]
	v_pk_mul_f32 v[122:123], v[82:83], v[106:107]
	v_cvt_pk_bf16_f32 v116, v116, v117
	v_cvt_pk_bf16_f32 v117, v118, v119
	v_cvt_pk_bf16_f32 v118, v122, v123
	v_cvt_pk_bf16_f32 v119, v120, v121
	v_cndmask_b32_e64 v222, v106, v110, s[100:101]
	v_cndmask_b32_e64 v223, v107, v111, s[100:101]
	v_cndmask_b32_e64 v224, v108, v112, s[100:101]
	v_cndmask_b32_e64 v225, v109, v113, s[100:101]
	v_mov_b32_dpp v238, v222 quad_perm:[1,0,3,2] row_mask:0xf bank_mask:0xf
	v_mov_b32_dpp v239, v223 quad_perm:[1,0,3,2] row_mask:0xf bank_mask:0xf
	v_mov_b32_dpp v240, v224 quad_perm:[1,0,3,2] row_mask:0xf bank_mask:0xf
	v_mov_b32_dpp v241, v225 quad_perm:[1,0,3,2] row_mask:0xf bank_mask:0xf
	v_cndmask_b32_e64 v214, v110, v238, s[100:101]
	v_cndmask_b32_e64 v218, v238, v106, s[100:101]
	v_cndmask_b32_e64 v215, v111, v239, s[100:101]
	v_cndmask_b32_e64 v219, v239, v107, s[100:101]
	v_cndmask_b32_e64 v216, v112, v240, s[100:101]
	v_cndmask_b32_e64 v220, v240, v108, s[100:101]
	v_cndmask_b32_e64 v217, v113, v241, s[100:101]
	v_cndmask_b32_e64 v221, v241, v109, s[100:101]
	v_lshl_add_u64 v[226:227], v[130:131], 0, v[242:243]
	global_store_dwordx4 v[226:227], v[214:217], off offset:-4096
	global_store_dwordx4 v[226:227], v[218:221], off
	global_store_dwordx4 v[128:129], v[116:119], off
	v_lshl_add_u64 v[226:227], v[126:127], 0, v[242:243]
	global_load_dwordx4 v[214:217], v[226:227], off offset:-3584
	global_load_dwordx4 v[218:221], v[226:227], off offset:512
	s_nop 0
	v_mul_f32_e32 v111, v111, v111
	v_mul_f32_e32 v113, v113, v113
	v_mul_f32_e32 v107, v107, v107
	v_fmac_f32_e32 v111, v110, v110
	v_fmac_f32_e32 v113, v112, v112
	v_mul_f32_e32 v109, v109, v109
	v_fmac_f32_e32 v107, v106, v106
	v_add_f32_e32 v106, v111, v113
	v_fmac_f32_e32 v109, v108, v108
	v_add_f32_e32 v106, v106, v107
	v_add_f32_e32 v106, v109, v106
	s_waitcnt vmcnt(0)
	v_cndmask_b32_e64 v222, v218, v214, s[100:101]
	v_cndmask_b32_e64 v223, v219, v215, s[100:101]
	v_cndmask_b32_e64 v224, v220, v216, s[100:101]
	v_cndmask_b32_e64 v225, v221, v217, s[100:101]
	v_mov_b32_dpp v238, v222 quad_perm:[1,0,3,2] row_mask:0xf bank_mask:0xf
	v_mov_b32_dpp v239, v223 quad_perm:[1,0,3,2] row_mask:0xf bank_mask:0xf
	v_mov_b32_dpp v240, v224 quad_perm:[1,0,3,2] row_mask:0xf bank_mask:0xf
	v_mov_b32_dpp v241, v225 quad_perm:[1,0,3,2] row_mask:0xf bank_mask:0xf
	v_cndmask_b32_e64 v116, v214, v238, s[100:101]
	v_cndmask_b32_e64 v120, v238, v218, s[100:101]
	v_cndmask_b32_e64 v117, v215, v239, s[100:101]
	v_cndmask_b32_e64 v121, v239, v219, s[100:101]
	v_cndmask_b32_e64 v118, v216, v240, s[100:101]
	v_cndmask_b32_e64 v122, v240, v220, s[100:101]
	v_cndmask_b32_e64 v119, v217, v241, s[100:101]
	v_cndmask_b32_e64 v123, v241, v221, s[100:101]
	v_pk_fma_f32 v[104:105], v[104:105], v[80:81], v[118:119]
	v_pk_fma_f32 v[102:103], v[102:103], v[78:79], v[116:117]
	s_waitcnt vmcnt(0)
	v_pk_fma_f32 v[98:99], v[98:99], v[74:75], v[120:121]
	v_mul_f32_e32 v107, v103, v103
	v_mul_f32_e32 v108, v105, v105
	v_pk_fma_f32 v[100:101], v[100:101], v[76:77], v[122:123]
	v_mul_f32_e32 v109, v99, v99
	v_fmac_f32_e32 v107, v102, v102
	v_fmac_f32_e32 v108, v104, v104
	v_mul_f32_e32 v110, v101, v101
	v_fmac_f32_e32 v109, v98, v98
	v_add_f32_e32 v107, v107, v108
	v_fmac_f32_e32 v110, v100, v100
	v_add_f32_e32 v107, v107, v109
	v_add_f32_e32 v107, v110, v107
	v_add_f32_e32 v110, v106, v107
	ds_bpermute_b32 v111, v200, v110
	v_cndmask_b32_e64 v222, v98, v102, s[100:101]
	v_cndmask_b32_e64 v223, v99, v103, s[100:101]
	v_cndmask_b32_e64 v224, v100, v104, s[100:101]
	v_cndmask_b32_e64 v225, v101, v105, s[100:101]
	v_mov_b32_dpp v238, v222 quad_perm:[1,0,3,2] row_mask:0xf bank_mask:0xf
	v_mov_b32_dpp v239, v223 quad_perm:[1,0,3,2] row_mask:0xf bank_mask:0xf
	v_mov_b32_dpp v240, v224 quad_perm:[1,0,3,2] row_mask:0xf bank_mask:0xf
	v_mov_b32_dpp v241, v225 quad_perm:[1,0,3,2] row_mask:0xf bank_mask:0xf
	v_cndmask_b32_e64 v214, v102, v238, s[100:101]
	v_cndmask_b32_e64 v218, v238, v98, s[100:101]
	v_cndmask_b32_e64 v215, v103, v239, s[100:101]
	v_cndmask_b32_e64 v219, v239, v99, s[100:101]
	v_cndmask_b32_e64 v216, v104, v240, s[100:101]
	v_cndmask_b32_e64 v220, v240, v100, s[100:101]
	v_cndmask_b32_e64 v217, v105, v241, s[100:101]
	v_cndmask_b32_e64 v221, v241, v101, s[100:101]
	v_lshl_add_u64 v[226:227], v[130:131], 0, v[242:243]
	global_store_dwordx4 v[226:227], v[214:217], off offset:-3584
	global_store_dwordx4 v[226:227], v[218:221], off offset:512
	v_pk_mul_f32 v[108:109], v[58:59], v[98:99]
	v_pk_mul_f32 v[104:105], v[64:65], v[104:105]
	v_pk_mul_f32 v[102:103], v[62:63], v[102:103]
	s_waitcnt lgkmcnt(0)
	v_add_f32_e32 v98, v110, v111
	ds_bpermute_b32 v99, v195, v98
	v_pk_mul_f32 v[106:107], v[60:61], v[100:101]
	v_cvt_pk_bf16_f32 v100, v102, v103
	v_cvt_pk_bf16_f32 v101, v104, v105
	v_cvt_pk_bf16_f32 v102, v108, v109
	v_cvt_pk_bf16_f32 v103, v106, v107
	global_store_dwordx4 v[128:129], v[100:103], off offset:256
	s_and_saveexec_b64 s[34:35], s[38:39]
	s_cbranch_execz .LBB0_942
;     __device__ __forceinline__ void operator()(const f32x4 (&acc)[2][2][4][2], const pg8::Unit& u, int wr, int wc, int fr, int fq) const {
;     ...
;                 if (fq == 0) stat[(size_t)R * 16 + u.pn * 4 + wc] = ss;
	v_lshlrev_b64 v[100:101], 6, v[114:115]
	v_lshl_add_u64 v[100:101], s[62:63], 0, v[100:101]
	v_lshl_add_u64 v[100:101], s[24:25], 2, v[100:101]
	s_lshl_b32 s0, s47, 2
	v_lshl_add_u64 v[100:101], v[100:101], 0, s[0:1]
	s_waitcnt lgkmcnt(0)
	v_add_f32_e32 v98, v98, v99
	global_store_dword v[100:101], v98, off

; __device__ __forceinline__ unsigned pk2(float lo, float hi) { return pg8::cvt_pk_bf16(lo, hi); }
;     __device__ __forceinline__ void operator()(const f32x4 (&acc)[2][2][4][2], const pg8::Unit& u, int wr, int wc, int fr, int fq) const {
;     ...
;             for (int m = 0; m < 4; ++m) {
;                 const int R = rowbase + u.pm * 256 + ai * 128 + wr * 64 + m * 16 + fr;
;                 const float* src = islat ? rin_l + (size_t)R * DM : rin_c + (size_t)(R - TL) * DM;
;                 float* dst = islat ? rout_l + (size_t)R * DM : rout_c + (size_t)(R - TL) * DM;
;                 float ss = 0.f;
; #pragma unroll
;                 for (int bj = 0; bj < 2; ++bj) { const int c = u.pn * 256 + bj * 128 + wc * 32 + 8 * fq;
;                     const f32x4 xa = *(const f32x4*)(src + c) + gv[bj][0] * acc[ai][bj][m][0];
;                     const f32x4 xb = *(const f32x4*)(src + c + 4) + gv[bj][1] * acc[ai][bj][m][1];
;                     *(f32x4*)(dst + c) = xa; *(f32x4*)(dst + c + 4) = xb;
;                     ss += (xa[0] * xa[0] + xa[1] * xa[1]) + (xa[2] * xa[2] + xa[3] * xa[3]) + (xb[0] * xb[0] + xb[1] * xb[1]) + (xb[2] * xb[2] + xb[3] * xb[3]);
;                     const f32x4 ya = xa * sv[bj][0], yb = xb * sv[bj][1];
;                     u32x4 w; w.x = pk2(ya[0], ya[1]); w.y = pk2(ya[2], ya[3]); w.z = pk2(yb[0], yb[1]); w.w = pk2(yb[2], yb[3]);
;                     *(u32x4*)(Hn + (size_t)R * DM + c) = w; }
;                 ss += __shfl_xor(ss, 16); ss += __shfl_xor(ss, 32);
;                 if (fq == 0) stat[(size_t)R * 16 + u.pn * 4 + wc] = ss;
.LBB0_946:
	v_cndmask_b32_e64 v102, v102, v98, s[42:43]
	v_ashrrev_i32_e32 v103, 31, v102
	v_lshlrev_b64 v[102:103], 12, v[102:103]
	v_lshl_add_u64 v[102:103], s[68:69], 0, v[102:103]
	v_lshl_add_u64 v[110:111], v[102:103], 0, v[188:189]
	v_lshl_add_u64 v[226:227], v[110:111], 0, v[242:243]
	global_load_dwordx4 v[214:217], v[226:227], off offset:-4096
	global_load_dwordx4 v[218:221], v[226:227], off
	v_lshlrev_b64 v[112:113], 11, v[98:99]
	v_lshl_add_u64 v[114:115], v[100:101], 0, v[188:189]
	v_lshl_add_u64 v[100:101], s[60:61], 0, v[112:113]
	v_lshl_add_u64 v[112:113], v[186:187], 1, v[100:101]
	s_waitcnt vmcnt(0)
	v_cndmask_b32_e64 v222, v218, v214, s[100:101]
	v_cndmask_b32_e64 v223, v219, v215, s[100:101]
	v_cndmask_b32_e64 v224, v220, v216, s[100:101]
	v_cndmask_b32_e64 v225, v221, v217, s[100:101]
	v_mov_b32_dpp v238, v222 quad_perm:[1,0,3,2] row_mask:0xf bank_mask:0xf
	v_mov_b32_dpp v239, v223 quad_perm:[1,0,3,2] row_mask:0xf bank_mask:0xf
	v_mov_b32_dpp v240, v224 quad_perm:[1,0,3,2] row_mask:0xf bank_mask:0xf
	v_mov_b32_dpp v241, v225 quad_perm:[1,0,3,2] row_mask:0xf bank_mask:0xf
	v_cndmask_b32_e64 v102, v214, v238, s[100:101]
	v_cndmask_b32_e64 v106, v238, v218, s[100:101]
	v_cndmask_b32_e64 v103, v215, v239, s[100:101]
	v_cndmask_b32_e64 v107, v239, v219, s[100:101]
	v_cndmask_b32_e64 v104, v216, v240, s[100:101]
	v_cndmask_b32_e64 v108, v240, v220, s[100:101]
	v_cndmask_b32_e64 v105, v217, v241, s[100:101]
	v_cndmask_b32_e64 v109, v241, v221, s[100:101]
	v_pk_fma_f32 v[72:73], v[72:73], v[96:97], v[104:105]
	v_pk_fma_f32 v[70:71], v[70:71], v[94:95], v[102:103]
	s_waitcnt vmcnt(0)
	v_pk_fma_f32 v[68:69], v[68:69], v[88:89], v[108:109]
	v_pk_fma_f32 v[66:67], v[66:67], v[86:87], v[106:107]
	v_pk_mul_f32 v[102:103], v[92:93], v[72:73]
	v_pk_mul_f32 v[100:101], v[90:91], v[70:71]
	v_pk_mul_f32 v[104:105], v[84:85], v[68:69]
	v_pk_mul_f32 v[106:107], v[82:83], v[66:67]
	v_cvt_pk_bf16_f32 v100, v100, v101
	v_cvt_pk_bf16_f32 v101, v102, v103
	v_cvt_pk_bf16_f32 v102, v106, v107
	v_cvt_pk_bf16_f32 v103, v104, v105
	v_cndmask_b32_e64 v222, v66, v70, s[100:101]
	v_cndmask_b32_e64 v223, v67, v71, s[100:101]
	v_cndmask_b32_e64 v224, v68, v72, s[100:101]
	v_cndmask_b32_e64 v225, v69, v73, s[100:101]
	v_mov_b32_dpp v238, v222 quad_perm:[1,0,3,2] row_mask:0xf bank_mask:0xf
	v_mov_b32_dpp v239, v223 quad_perm:[1,0,3,2] row_mask:0xf bank_mask:0xf
	v_mov_b32_dpp v240, v224 quad_perm:[1,0,3,2] row_mask:0xf bank_mask:0xf
	v_mov_b32_dpp v241, v225 quad_perm:[1,0,3,2] row_mask:0xf bank_mask:0xf
	v_cndmask_b32_e64 v214, v70, v238, s[100:101]
	v_cndmask_b32_e64 v218, v238, v66, s[100:101]
	v_cndmask_b32_e64 v215, v71, v239, s[100:101]
	v_cndmask_b32_e64 v219, v239, v67, s[100:101]
	v_cndmask_b32_e64 v216, v72, v240, s[100:101]
	v_cndmask_b32_e64 v220, v240, v68, s[100:101]
	v_cndmask_b32_e64 v217, v73, v241, s[100:101]
	v_cndmask_b32_e64 v221, v241, v69, s[100:101]
	v_lshl_add_u64 v[226:227], v[114:115], 0, v[242:243]
	global_store_dwordx4 v[226:227], v[214:217], off offset:-4096
	global_store_dwordx4 v[226:227], v[218:221], off
	global_store_dwordx4 v[112:113], v[100:103], off
	v_lshl_add_u64 v[226:227], v[110:111], 0, v[242:243]
	global_load_dwordx4 v[214:217], v[226:227], off offset:-3584
	global_load_dwordx4 v[218:221], v[226:227], off offset:512
	s_nop 0
	v_mul_f32_e32 v71, v71, v71
	v_mul_f32_e32 v73, v73, v73
	v_mul_f32_e32 v67, v67, v67
	v_fmac_f32_e32 v71, v70, v70
	v_fmac_f32_e32 v73, v72, v72
	v_mul_f32_e32 v69, v69, v69
	v_fmac_f32_e32 v67, v66, v66
	v_add_f32_e32 v66, v71, v73
	v_fmac_f32_e32 v69, v68, v68
	v_add_f32_e32 v66, v66, v67
	v_add_f32_e32 v66, v69, v66
	s_waitcnt vmcnt(0)
	v_cndmask_b32_e64 v222, v218, v214, s[100:101]
	v_cndmask_b32_e64 v223, v219, v215, s[100:101]
	v_cndmask_b32_e64 v224, v220, v216, s[100:101]
	v_cndmask_b32_e64 v225, v221, v217, s[100:101]
	v_mov_b32_dpp v238, v222 quad_perm:[1,0,3,2] row_mask:0xf bank_mask:0xf
	v_mov_b32_dpp v239, v223 quad_perm:[1,0,3,2] row_mask:0xf bank_mask:0xf
	v_mov_b32_dpp v240, v224 quad_perm:[1,0,3,2] row_mask:0xf bank_mask:0xf
	v_mov_b32_dpp v241, v225 quad_perm:[1,0,3,2] row_mask:0xf bank_mask:0xf
	v_cndmask_b32_e64 v100, v214, v238, s[100:101]
	v_cndmask_b32_e64 v104, v238, v218, s[100:101]
	v_cndmask_b32_e64 v101, v215, v239, s[100:101]
	v_cndmask_b32_e64 v105, v239, v219, s[100:101]
	v_cndmask_b32_e64 v102, v216, v240, s[100:101]
	v_cndmask_b32_e64 v106, v240, v220, s[100:101]
	v_cndmask_b32_e64 v103, v217, v241, s[100:101]
	v_cndmask_b32_e64 v107, v241, v221, s[100:101]
	v_pk_fma_f32 v[56:57], v[56:57], v[80:81], v[102:103]
	v_pk_fma_f32 v[54:55], v[54:55], v[78:79], v[100:101]
	s_waitcnt vmcnt(0)
	v_pk_fma_f32 v[50:51], v[50:51], v[74:75], v[104:105]
	v_mul_f32_e32 v67, v55, v55
	v_mul_f32_e32 v68, v57, v57
	v_pk_fma_f32 v[52:53], v[52:53], v[76:77], v[106:107]
	v_mul_f32_e32 v69, v51, v51
	v_fmac_f32_e32 v67, v54, v54
	v_fmac_f32_e32 v68, v56, v56
	v_mul_f32_e32 v70, v53, v53
	v_fmac_f32_e32 v69, v50, v50
	v_add_f32_e32 v67, v67, v68
	v_fmac_f32_e32 v70, v52, v52
	v_add_f32_e32 v67, v67, v69
	v_add_f32_e32 v67, v70, v67
	v_add_f32_e32 v70, v66, v67
	ds_bpermute_b32 v71, v200, v70
	v_cndmask_b32_e64 v222, v50, v54, s[100:101]
	v_cndmask_b32_e64 v223, v51, v55, s[100:101]
	v_cndmask_b32_e64 v224, v52, v56, s[100:101]
	v_cndmask_b32_e64 v225, v53, v57, s[100:101]
	v_mov_b32_dpp v238, v222 quad_perm:[1,0,3,2] row_mask:0xf bank_mask:0xf
	v_mov_b32_dpp v239, v223 quad_perm:[1,0,3,2] row_mask:0xf bank_mask:0xf
	v_mov_b32_dpp v240, v224 quad_perm:[1,0,3,2] row_mask:0xf bank_mask:0xf
	v_mov_b32_dpp v241, v225 quad_perm:[1,0,3,2] row_mask:0xf bank_mask:0xf
	v_cndmask_b32_e64 v214, v54, v238, s[100:101]
	v_cndmask_b32_e64 v218, v238, v50, s[100:101]
	v_cndmask_b32_e64 v215, v55, v239, s[100:101]
	v_cndmask_b32_e64 v219, v239, v51, s[100:101]
	v_cndmask_b32_e64 v216, v56, v240, s[100:101]
	v_cndmask_b32_e64 v220, v240, v52, s[100:101]
	v_cndmask_b32_e64 v217, v57, v241, s[100:101]
	v_cndmask_b32_e64 v221, v241, v53, s[100:101]
	v_lshl_add_u64 v[226:227], v[114:115], 0, v[242:243]
	global_store_dwordx4 v[226:227], v[214:217], off offset:-3584
	global_store_dwordx4 v[226:227], v[218:221], off offset:512
	v_pk_mul_f32 v[68:69], v[58:59], v[50:51]
	v_pk_mul_f32 v[56:57], v[64:65], v[56:57]
	v_pk_mul_f32 v[54:55], v[62:63], v[54:55]
	s_waitcnt lgkmcnt(0)
	v_add_f32_e32 v50, v70, v71
	ds_bpermute_b32 v51, v195, v50
	v_pk_mul_f32 v[66:67], v[60:61], v[52:53]
	v_cvt_pk_bf16_f32 v52, v54, v55
	v_cvt_pk_bf16_f32 v53, v56, v57
	v_cvt_pk_bf16_f32 v54, v68, v69
	v_cvt_pk_bf16_f32 v55, v66, v67
	global_store_dwordx4 v[112:113], v[52:55], off offset:256
	s_and_saveexec_b64 s[34:35], s[38:39]
	s_cbranch_execz .LBB0_948
	v_lshlrev_b64 v[52:53], 6, v[98:99]
	v_lshl_add_u64 v[52:53], s[62:63], 0, v[52:53]
	v_lshl_add_u64 v[52:53], s[24:25], 2, v[52:53]
	s_lshl_b32 s0, s47, 2
	v_lshl_add_u64 v[52:53], v[52:53], 0, s[0:1]
	s_waitcnt lgkmcnt(0)
	v_add_f32_e32 v50, v50, v51
	global_store_dword v[52:53], v50, off

; __device__ __forceinline__ unsigned pk2(float lo, float hi) { return pg8::cvt_pk_bf16(lo, hi); }
;     __device__ __forceinline__ void operator()(const f32x4 (&acc)[2][2][4][2], const pg8::Unit& u, int wr, int wc, int fr, int fq) const {
;     ...
;             for (int m = 0; m < 4; ++m) {
;                 const int R = rowbase + u.pm * 256 + ai * 128 + wr * 64 + m * 16 + fr;
;                 const float* src = islat ? rin_l + (size_t)R * DM : rin_c + (size_t)(R - TL) * DM;
;                 float* dst = islat ? rout_l + (size_t)R * DM : rout_c + (size_t)(R - TL) * DM;
;                 float ss = 0.f;
; #pragma unroll
;                 for (int bj = 0; bj < 2; ++bj) { const int c = u.pn * 256 + bj * 128 + wc * 32 + 8 * fq;
;                     const f32x4 xa = *(const f32x4*)(src + c) + gv[bj][0] * acc[ai][bj][m][0];
;                     const f32x4 xb = *(const f32x4*)(src + c + 4) + gv[bj][1] * acc[ai][bj][m][1];
;                     *(f32x4*)(dst + c) = xa; *(f32x4*)(dst + c + 4) = xb;
;                     ss += (xa[0] * xa[0] + xa[1] * xa[1]) + (xa[2] * xa[2] + xa[3] * xa[3]) + (xb[0] * xb[0] + xb[1] * xb[1]) + (xb[2] * xb[2] + xb[3] * xb[3]);
;                     const f32x4 ya = xa * sv[bj][0], yb = xb * sv[bj][1];
;                     u32x4 w; w.x = pk2(ya[0], ya[1]); w.y = pk2(ya[2], ya[3]); w.z = pk2(yb[0], yb[1]); w.w = pk2(yb[2], yb[3]);
;                     *(u32x4*)(Hn + (size_t)R * DM + c) = w; }
;                 ss += __shfl_xor(ss, 16); ss += __shfl_xor(ss, 32);
;                 if (fq == 0) stat[(size_t)R * 16 + u.pn * 4 + wc] = ss;
.LBB0_952:
	v_cndmask_b32_e64 v54, v54, v50, s[42:43]
	v_ashrrev_i32_e32 v55, 31, v54
	v_lshlrev_b64 v[54:55], 12, v[54:55]
	v_lshl_add_u64 v[54:55], s[68:69], 0, v[54:55]
	v_lshl_add_u64 v[70:71], v[54:55], 0, v[188:189]
	v_lshl_add_u64 v[226:227], v[70:71], 0, v[242:243]
	global_load_dwordx4 v[214:217], v[226:227], off offset:-4096
	global_load_dwordx4 v[218:221], v[226:227], off
	v_lshlrev_b64 v[72:73], 11, v[50:51]
	v_lshl_add_u64 v[98:99], v[52:53], 0, v[188:189]
	v_lshl_add_u64 v[52:53], s[60:61], 0, v[72:73]
	v_lshl_add_u64 v[72:73], v[186:187], 1, v[52:53]
	s_waitcnt vmcnt(0)
	v_cndmask_b32_e64 v222, v218, v214, s[100:101]
	v_cndmask_b32_e64 v223, v219, v215, s[100:101]
	v_cndmask_b32_e64 v224, v220, v216, s[100:101]
	v_cndmask_b32_e64 v225, v221, v217, s[100:101]
	v_mov_b32_dpp v238, v222 quad_perm:[1,0,3,2] row_mask:0xf bank_mask:0xf
	v_mov_b32_dpp v239, v223 quad_perm:[1,0,3,2] row_mask:0xf bank_mask:0xf
	v_mov_b32_dpp v240, v224 quad_perm:[1,0,3,2] row_mask:0xf bank_mask:0xf
	v_mov_b32_dpp v241, v225 quad_perm:[1,0,3,2] row_mask:0xf bank_mask:0xf
	v_cndmask_b32_e64 v54, v214, v238, s[100:101]
	v_cndmask_b32_e64 v66, v238, v218, s[100:101]
	v_cndmask_b32_e64 v55, v215, v239, s[100:101]
	v_cndmask_b32_e64 v67, v239, v219, s[100:101]
	v_cndmask_b32_e64 v56, v216, v240, s[100:101]
	v_cndmask_b32_e64 v68, v240, v220, s[100:101]
	v_cndmask_b32_e64 v57, v217, v241, s[100:101]
	v_cndmask_b32_e64 v69, v241, v221, s[100:101]
	v_pk_fma_f32 v[48:49], v[48:49], v[96:97], v[56:57]
	v_pk_fma_f32 v[46:47], v[46:47], v[94:95], v[54:55]
	s_waitcnt vmcnt(0)
	v_pk_fma_f32 v[44:45], v[44:45], v[88:89], v[68:69]
	v_pk_fma_f32 v[42:43], v[42:43], v[86:87], v[66:67]
	v_pk_mul_f32 v[54:55], v[92:93], v[48:49]
	v_pk_mul_f32 v[52:53], v[90:91], v[46:47]
	v_pk_mul_f32 v[56:57], v[84:85], v[44:45]
	v_pk_mul_f32 v[66:67], v[82:83], v[42:43]
	v_cvt_pk_bf16_f32 v52, v52, v53
	v_cvt_pk_bf16_f32 v53, v54, v55
	v_cvt_pk_bf16_f32 v54, v66, v67
	v_cvt_pk_bf16_f32 v55, v56, v57
	v_cndmask_b32_e64 v222, v42, v46, s[100:101]
	v_cndmask_b32_e64 v223, v43, v47, s[100:101]
	v_cndmask_b32_e64 v224, v44, v48, s[100:101]
	v_cndmask_b32_e64 v225, v45, v49, s[100:101]
	v_mov_b32_dpp v238, v222 quad_perm:[1,0,3,2] row_mask:0xf bank_mask:0xf
	v_mov_b32_dpp v239, v223 quad_perm:[1,0,3,2] row_mask:0xf bank_mask:0xf
	v_mov_b32_dpp v240, v224 quad_perm:[1,0,3,2] row_mask:0xf bank_mask:0xf
	v_mov_b32_dpp v241, v225 quad_perm:[1,0,3,2] row_mask:0xf bank_mask:0xf
	v_cndmask_b32_e64 v214, v46, v238, s[100:101]
	v_cndmask_b32_e64 v218, v238, v42, s[100:101]
	v_cndmask_b32_e64 v215, v47, v239, s[100:101]
	v_cndmask_b32_e64 v219, v239, v43, s[100:101]
	v_cndmask_b32_e64 v216, v48, v240, s[100:101]
	v_cndmask_b32_e64 v220, v240, v44, s[100:101]
	v_cndmask_b32_e64 v217, v49, v241, s[100:101]
	v_cndmask_b32_e64 v221, v241, v45, s[100:101]
	v_lshl_add_u64 v[226:227], v[98:99], 0, v[242:243]
	global_store_dwordx4 v[226:227], v[214:217], off offset:-4096
	global_store_dwordx4 v[226:227], v[218:221], off
	global_store_dwordx4 v[72:73], v[52:55], off
	v_lshl_add_u64 v[226:227], v[70:71], 0, v[242:243]
	global_load_dwordx4 v[214:217], v[226:227], off offset:-3584
	global_load_dwordx4 v[218:221], v[226:227], off offset:512
	s_nop 0
	v_mul_f32_e32 v47, v47, v47
	v_mul_f32_e32 v49, v49, v49
	v_mul_f32_e32 v43, v43, v43
	v_fmac_f32_e32 v47, v46, v46
	v_fmac_f32_e32 v49, v48, v48
	v_mul_f32_e32 v45, v45, v45
	v_fmac_f32_e32 v43, v42, v42
	v_add_f32_e32 v42, v47, v49
	v_fmac_f32_e32 v45, v44, v44
	v_add_f32_e32 v42, v42, v43
	v_add_f32_e32 v42, v45, v42
	s_waitcnt vmcnt(0)
	v_cndmask_b32_e64 v222, v218, v214, s[100:101]
	v_cndmask_b32_e64 v223, v219, v215, s[100:101]
	v_cndmask_b32_e64 v224, v220, v216, s[100:101]
	v_cndmask_b32_e64 v225, v221, v217, s[100:101]
	v_mov_b32_dpp v238, v222 quad_perm:[1,0,3,2] row_mask:0xf bank_mask:0xf
	v_mov_b32_dpp v239, v223 quad_perm:[1,0,3,2] row_mask:0xf bank_mask:0xf
	v_mov_b32_dpp v240, v224 quad_perm:[1,0,3,2] row_mask:0xf bank_mask:0xf
	v_mov_b32_dpp v241, v225 quad_perm:[1,0,3,2] row_mask:0xf bank_mask:0xf
	v_cndmask_b32_e64 v52, v214, v238, s[100:101]
	v_cndmask_b32_e64 v66, v238, v218, s[100:101]
	v_cndmask_b32_e64 v53, v215, v239, s[100:101]
	v_cndmask_b32_e64 v67, v239, v219, s[100:101]
	v_cndmask_b32_e64 v54, v216, v240, s[100:101]
	v_cndmask_b32_e64 v68, v240, v220, s[100:101]
	v_cndmask_b32_e64 v55, v217, v241, s[100:101]
	v_cndmask_b32_e64 v69, v241, v221, s[100:101]
	v_pk_fma_f32 v[40:41], v[40:41], v[80:81], v[54:55]
	v_pk_fma_f32 v[38:39], v[38:39], v[78:79], v[52:53]
	s_waitcnt vmcnt(0)
	v_pk_fma_f32 v[34:35], v[34:35], v[74:75], v[66:67]
	v_mul_f32_e32 v43, v39, v39
	v_mul_f32_e32 v44, v41, v41
	v_pk_fma_f32 v[36:37], v[36:37], v[76:77], v[68:69]
	v_mul_f32_e32 v45, v35, v35
	v_fmac_f32_e32 v43, v38, v38
	v_fmac_f32_e32 v44, v40, v40
	v_mul_f32_e32 v46, v37, v37
	v_fmac_f32_e32 v45, v34, v34
	v_add_f32_e32 v43, v43, v44
	v_fmac_f32_e32 v46, v36, v36
	v_add_f32_e32 v43, v43, v45
	v_add_f32_e32 v43, v46, v43
	v_add_f32_e32 v46, v42, v43
	ds_bpermute_b32 v47, v200, v46
	v_cndmask_b32_e64 v222, v34, v38, s[100:101]
	v_cndmask_b32_e64 v223, v35, v39, s[100:101]
	v_cndmask_b32_e64 v224, v36, v40, s[100:101]
	v_cndmask_b32_e64 v225, v37, v41, s[100:101]
	v_mov_b32_dpp v238, v222 quad_perm:[1,0,3,2] row_mask:0xf bank_mask:0xf
	v_mov_b32_dpp v239, v223 quad_perm:[1,0,3,2] row_mask:0xf bank_mask:0xf
	v_mov_b32_dpp v240, v224 quad_perm:[1,0,3,2] row_mask:0xf bank_mask:0xf
	v_mov_b32_dpp v241, v225 quad_perm:[1,0,3,2] row_mask:0xf bank_mask:0xf
	v_cndmask_b32_e64 v214, v38, v238, s[100:101]
	v_cndmask_b32_e64 v218, v238, v34, s[100:101]
	v_cndmask_b32_e64 v215, v39, v239, s[100:101]
	v_cndmask_b32_e64 v219, v239, v35, s[100:101]
	v_cndmask_b32_e64 v216, v40, v240, s[100:101]
	v_cndmask_b32_e64 v220, v240, v36, s[100:101]
	v_cndmask_b32_e64 v217, v41, v241, s[100:101]
	v_cndmask_b32_e64 v221, v241, v37, s[100:101]
	v_lshl_add_u64 v[226:227], v[98:99], 0, v[242:243]
	global_store_dwordx4 v[226:227], v[214:217], off offset:-3584
	global_store_dwordx4 v[226:227], v[218:221], off offset:512
	v_pk_mul_f32 v[44:45], v[58:59], v[34:35]
	v_pk_mul_f32 v[40:41], v[64:65], v[40:41]
	v_pk_mul_f32 v[38:39], v[62:63], v[38:39]
	s_waitcnt lgkmcnt(0)
	v_add_f32_e32 v34, v46, v47
	ds_bpermute_b32 v35, v195, v34
	v_pk_mul_f32 v[42:43], v[60:61], v[36:37]
	v_cvt_pk_bf16_f32 v36, v38, v39
	v_cvt_pk_bf16_f32 v37, v40, v41
	v_cvt_pk_bf16_f32 v38, v44, v45
	v_cvt_pk_bf16_f32 v39, v42, v43
	global_store_dwordx4 v[72:73], v[36:39], off offset:256
	s_and_saveexec_b64 s[34:35], s[38:39]
	s_cbranch_execz .LBB0_954
	v_lshlrev_b64 v[36:37], 6, v[50:51]
	v_lshl_add_u64 v[36:37], s[62:63], 0, v[36:37]
	v_lshl_add_u64 v[36:37], s[24:25], 2, v[36:37]
	s_lshl_b32 s0, s47, 2
	v_lshl_add_u64 v[36:37], v[36:37], 0, s[0:1]
	s_waitcnt lgkmcnt(0)
	v_add_f32_e32 v34, v34, v35
	global_store_dword v[36:37], v34, off

; __device__ __forceinline__ unsigned pk2(float lo, float hi) { return pg8::cvt_pk_bf16(lo, hi); }
;     __device__ __forceinline__ void operator()(const f32x4 (&acc)[2][2][4][2], const pg8::Unit& u, int wr, int wc, int fr, int fq) const {
;     ...
;             for (int m = 0; m < 4; ++m) {
;                 const int R = rowbase + u.pm * 256 + ai * 128 + wr * 64 + m * 16 + fr;
;                 const float* src = islat ? rin_l + (size_t)R * DM : rin_c + (size_t)(R - TL) * DM;
;                 float* dst = islat ? rout_l + (size_t)R * DM : rout_c + (size_t)(R - TL) * DM;
;                 float ss = 0.f;
; #pragma unroll
;                 for (int bj = 0; bj < 2; ++bj) { const int c = u.pn * 256 + bj * 128 + wc * 32 + 8 * fq;
;                     const f32x4 xa = *(const f32x4*)(src + c) + gv[bj][0] * acc[ai][bj][m][0];
;                     const f32x4 xb = *(const f32x4*)(src + c + 4) + gv[bj][1] * acc[ai][bj][m][1];
;                     *(f32x4*)(dst + c) = xa; *(f32x4*)(dst + c + 4) = xb;
;                     ss += (xa[0] * xa[0] + xa[1] * xa[1]) + (xa[2] * xa[2] + xa[3] * xa[3]) + (xb[0] * xb[0] + xb[1] * xb[1]) + (xb[2] * xb[2] + xb[3] * xb[3]);
;                     const f32x4 ya = xa * sv[bj][0], yb = xb * sv[bj][1];
;                     u32x4 w; w.x = pk2(ya[0], ya[1]); w.y = pk2(ya[2], ya[3]); w.z = pk2(yb[0], yb[1]); w.w = pk2(yb[2], yb[3]);
;                     *(u32x4*)(Hn + (size_t)R * DM + c) = w; }
;                 ss += __shfl_xor(ss, 16); ss += __shfl_xor(ss, 32);
;                 if (fq == 0) stat[(size_t)R * 16 + u.pn * 4 + wc] = ss;
.LBB0_958:
	v_cndmask_b32_e64 v38, v38, v34, s[42:43]
	v_ashrrev_i32_e32 v39, 31, v38
	v_lshlrev_b64 v[38:39], 12, v[38:39]
	v_lshl_add_u64 v[38:39], s[68:69], 0, v[38:39]
	v_lshl_add_u64 v[46:47], v[38:39], 0, v[188:189]
	v_lshl_add_u64 v[226:227], v[46:47], 0, v[242:243]
	global_load_dwordx4 v[214:217], v[226:227], off offset:-4096
	global_load_dwordx4 v[218:221], v[226:227], off
	v_lshlrev_b64 v[48:49], 11, v[34:35]
	v_lshl_add_u64 v[50:51], v[36:37], 0, v[188:189]
	v_lshl_add_u64 v[36:37], s[60:61], 0, v[48:49]
	v_lshl_add_u64 v[48:49], v[186:187], 1, v[36:37]
	s_waitcnt vmcnt(0)
	v_cndmask_b32_e64 v222, v218, v214, s[100:101]
	v_cndmask_b32_e64 v223, v219, v215, s[100:101]
	v_cndmask_b32_e64 v224, v220, v216, s[100:101]
	v_cndmask_b32_e64 v225, v221, v217, s[100:101]
	v_mov_b32_dpp v238, v222 quad_perm:[1,0,3,2] row_mask:0xf bank_mask:0xf
	v_mov_b32_dpp v239, v223 quad_perm:[1,0,3,2] row_mask:0xf bank_mask:0xf
	v_mov_b32_dpp v240, v224 quad_perm:[1,0,3,2] row_mask:0xf bank_mask:0xf
	v_mov_b32_dpp v241, v225 quad_perm:[1,0,3,2] row_mask:0xf bank_mask:0xf
	v_cndmask_b32_e64 v38, v214, v238, s[100:101]
	v_cndmask_b32_e64 v42, v238, v218, s[100:101]
	v_cndmask_b32_e64 v39, v215, v239, s[100:101]
	v_cndmask_b32_e64 v43, v239, v219, s[100:101]
	v_cndmask_b32_e64 v40, v216, v240, s[100:101]
	v_cndmask_b32_e64 v44, v240, v220, s[100:101]
	v_cndmask_b32_e64 v41, v217, v241, s[100:101]
	v_cndmask_b32_e64 v45, v241, v221, s[100:101]
	v_pk_fma_f32 v[32:33], v[32:33], v[96:97], v[40:41]
	v_pk_fma_f32 v[30:31], v[30:31], v[94:95], v[38:39]
	s_waitcnt vmcnt(0)
	v_pk_fma_f32 v[28:29], v[28:29], v[88:89], v[44:45]
	v_pk_fma_f32 v[26:27], v[26:27], v[86:87], v[42:43]
	v_pk_mul_f32 v[38:39], v[92:93], v[32:33]
	v_pk_mul_f32 v[36:37], v[90:91], v[30:31]
	v_pk_mul_f32 v[40:41], v[84:85], v[28:29]
	v_pk_mul_f32 v[42:43], v[82:83], v[26:27]
	v_cvt_pk_bf16_f32 v36, v36, v37
	v_cvt_pk_bf16_f32 v37, v38, v39
	v_cvt_pk_bf16_f32 v38, v42, v43
	v_cvt_pk_bf16_f32 v39, v40, v41
	v_cndmask_b32_e64 v222, v26, v30, s[100:101]
	v_cndmask_b32_e64 v223, v27, v31, s[100:101]
	v_cndmask_b32_e64 v224, v28, v32, s[100:101]
	v_cndmask_b32_e64 v225, v29, v33, s[100:101]
	v_mov_b32_dpp v238, v222 quad_perm:[1,0,3,2] row_mask:0xf bank_mask:0xf
	v_mov_b32_dpp v239, v223 quad_perm:[1,0,3,2] row_mask:0xf bank_mask:0xf
	v_mov_b32_dpp v240, v224 quad_perm:[1,0,3,2] row_mask:0xf bank_mask:0xf
	v_mov_b32_dpp v241, v225 quad_perm:[1,0,3,2] row_mask:0xf bank_mask:0xf
	v_cndmask_b32_e64 v214, v30, v238, s[100:101]
	v_cndmask_b32_e64 v218, v238, v26, s[100:101]
	v_cndmask_b32_e64 v215, v31, v239, s[100:101]
	v_cndmask_b32_e64 v219, v239, v27, s[100:101]
	v_cndmask_b32_e64 v216, v32, v240, s[100:101]
	v_cndmask_b32_e64 v220, v240, v28, s[100:101]
	v_cndmask_b32_e64 v217, v33, v241, s[100:101]
	v_cndmask_b32_e64 v221, v241, v29, s[100:101]
	v_lshl_add_u64 v[226:227], v[50:51], 0, v[242:243]
	global_store_dwordx4 v[226:227], v[214:217], off offset:-4096
	global_store_dwordx4 v[226:227], v[218:221], off
	global_store_dwordx4 v[48:49], v[36:39], off
	v_lshl_add_u64 v[226:227], v[46:47], 0, v[242:243]
	global_load_dwordx4 v[214:217], v[226:227], off offset:-3584
	global_load_dwordx4 v[218:221], v[226:227], off offset:512
	s_nop 0
	v_mul_f32_e32 v31, v31, v31
	v_mul_f32_e32 v33, v33, v33
	v_mul_f32_e32 v27, v27, v27
	v_fmac_f32_e32 v31, v30, v30
	v_fmac_f32_e32 v33, v32, v32
	v_mul_f32_e32 v29, v29, v29
	v_fmac_f32_e32 v27, v26, v26
	v_add_f32_e32 v26, v31, v33
	v_fmac_f32_e32 v29, v28, v28
	v_add_f32_e32 v26, v26, v27
	v_add_f32_e32 v26, v29, v26
	s_waitcnt vmcnt(0)
	v_cndmask_b32_e64 v222, v218, v214, s[100:101]
	v_cndmask_b32_e64 v223, v219, v215, s[100:101]
	v_cndmask_b32_e64 v224, v220, v216, s[100:101]
	v_cndmask_b32_e64 v225, v221, v217, s[100:101]
	v_mov_b32_dpp v238, v222 quad_perm:[1,0,3,2] row_mask:0xf bank_mask:0xf
	v_mov_b32_dpp v239, v223 quad_perm:[1,0,3,2] row_mask:0xf bank_mask:0xf
	v_mov_b32_dpp v240, v224 quad_perm:[1,0,3,2] row_mask:0xf bank_mask:0xf
	v_mov_b32_dpp v241, v225 quad_perm:[1,0,3,2] row_mask:0xf bank_mask:0xf
	v_cndmask_b32_e64 v36, v214, v238, s[100:101]
	v_cndmask_b32_e64 v40, v238, v218, s[100:101]
	v_cndmask_b32_e64 v37, v215, v239, s[100:101]
	v_cndmask_b32_e64 v41, v239, v219, s[100:101]
	v_cndmask_b32_e64 v38, v216, v240, s[100:101]
	v_cndmask_b32_e64 v42, v240, v220, s[100:101]
	v_cndmask_b32_e64 v39, v217, v241, s[100:101]
	v_cndmask_b32_e64 v43, v241, v221, s[100:101]
	v_pk_fma_f32 v[24:25], v[24:25], v[80:81], v[38:39]
	v_pk_fma_f32 v[22:23], v[22:23], v[78:79], v[36:37]
	s_waitcnt vmcnt(0)
	v_pk_fma_f32 v[18:19], v[18:19], v[74:75], v[40:41]
	v_mul_f32_e32 v27, v23, v23
	v_mul_f32_e32 v28, v25, v25
	v_pk_fma_f32 v[20:21], v[20:21], v[76:77], v[42:43]
	v_mul_f32_e32 v29, v19, v19
	v_fmac_f32_e32 v27, v22, v22
	v_fmac_f32_e32 v28, v24, v24
	v_mul_f32_e32 v30, v21, v21
	v_fmac_f32_e32 v29, v18, v18
	v_add_f32_e32 v27, v27, v28
	v_fmac_f32_e32 v30, v20, v20
	v_add_f32_e32 v27, v27, v29
	v_add_f32_e32 v27, v30, v27
	v_add_f32_e32 v30, v26, v27
	ds_bpermute_b32 v31, v200, v30
	v_cndmask_b32_e64 v222, v18, v22, s[100:101]
	v_cndmask_b32_e64 v223, v19, v23, s[100:101]
	v_cndmask_b32_e64 v224, v20, v24, s[100:101]
	v_cndmask_b32_e64 v225, v21, v25, s[100:101]
	v_mov_b32_dpp v238, v222 quad_perm:[1,0,3,2] row_mask:0xf bank_mask:0xf
	v_mov_b32_dpp v239, v223 quad_perm:[1,0,3,2] row_mask:0xf bank_mask:0xf
	v_mov_b32_dpp v240, v224 quad_perm:[1,0,3,2] row_mask:0xf bank_mask:0xf
	v_mov_b32_dpp v241, v225 quad_perm:[1,0,3,2] row_mask:0xf bank_mask:0xf
	v_cndmask_b32_e64 v214, v22, v238, s[100:101]
	v_cndmask_b32_e64 v218, v238, v18, s[100:101]
	v_cndmask_b32_e64 v215, v23, v239, s[100:101]
	v_cndmask_b32_e64 v219, v239, v19, s[100:101]
	v_cndmask_b32_e64 v216, v24, v240, s[100:101]
	v_cndmask_b32_e64 v220, v240, v20, s[100:101]
	v_cndmask_b32_e64 v217, v25, v241, s[100:101]
	v_cndmask_b32_e64 v221, v241, v21, s[100:101]
	v_lshl_add_u64 v[226:227], v[50:51], 0, v[242:243]
	global_store_dwordx4 v[226:227], v[214:217], off offset:-3584
	global_store_dwordx4 v[226:227], v[218:221], off offset:512
	v_pk_mul_f32 v[28:29], v[58:59], v[18:19]
	v_pk_mul_f32 v[24:25], v[64:65], v[24:25]
	v_pk_mul_f32 v[22:23], v[62:63], v[22:23]
	s_waitcnt lgkmcnt(0)
	v_add_f32_e32 v18, v30, v31
	ds_bpermute_b32 v19, v195, v18
	v_pk_mul_f32 v[26:27], v[60:61], v[20:21]
	v_cvt_pk_bf16_f32 v20, v22, v23
	v_cvt_pk_bf16_f32 v21, v24, v25
	v_cvt_pk_bf16_f32 v22, v28, v29
	v_cvt_pk_bf16_f32 v23, v26, v27
	global_store_dwordx4 v[48:49], v[20:23], off offset:256
	s_and_saveexec_b64 s[34:35], s[38:39]
	s_cbranch_execz .LBB0_960
	v_lshlrev_b64 v[20:21], 6, v[34:35]
	v_lshl_add_u64 v[20:21], s[62:63], 0, v[20:21]
	v_lshl_add_u64 v[20:21], s[24:25], 2, v[20:21]
	s_lshl_b32 s0, s47, 2
	v_lshl_add_u64 v[20:21], v[20:21], 0, s[0:1]
	s_waitcnt lgkmcnt(0)
	v_add_f32_e32 v18, v18, v19
	global_store_dword v[20:21], v18, off

; __device__ __forceinline__ unsigned pk2(float lo, float hi) { return pg8::cvt_pk_bf16(lo, hi); }
;     __device__ __forceinline__ void operator()(const f32x4 (&acc)[2][2][4][2], const pg8::Unit& u, int wr, int wc, int fr, int fq) const {
;     ...
;             for (int m = 0; m < 4; ++m) {
;                 const int R = rowbase + u.pm * 256 + ai * 128 + wr * 64 + m * 16 + fr;
;                 const float* src = islat ? rin_l + (size_t)R * DM : rin_c + (size_t)(R - TL) * DM;
;                 float* dst = islat ? rout_l + (size_t)R * DM : rout_c + (size_t)(R - TL) * DM;
;                 float ss = 0.f;
; #pragma unroll
;                 for (int bj = 0; bj < 2; ++bj) { const int c = u.pn * 256 + bj * 128 + wc * 32 + 8 * fq;
;                     const f32x4 xa = *(const f32x4*)(src + c) + gv[bj][0] * acc[ai][bj][m][0];
;                     const f32x4 xb = *(const f32x4*)(src + c + 4) + gv[bj][1] * acc[ai][bj][m][1];
;                     *(f32x4*)(dst + c) = xa; *(f32x4*)(dst + c + 4) = xb;
;                     ss += (xa[0] * xa[0] + xa[1] * xa[1]) + (xa[2] * xa[2] + xa[3] * xa[3]) + (xb[0] * xb[0] + xb[1] * xb[1]) + (xb[2] * xb[2] + xb[3] * xb[3]);
;                     const f32x4 ya = xa * sv[bj][0], yb = xb * sv[bj][1];
;                     u32x4 w; w.x = pk2(ya[0], ya[1]); w.y = pk2(ya[2], ya[3]); w.z = pk2(yb[0], yb[1]); w.w = pk2(yb[2], yb[3]);
;                     *(u32x4*)(Hn + (size_t)R * DM + c) = w; }
;                 ss += __shfl_xor(ss, 16); ss += __shfl_xor(ss, 32);
;                 if (fq == 0) stat[(size_t)R * 16 + u.pn * 4 + wc] = ss;
.LBB0_964:
	v_cndmask_b32_e64 v22, v22, v18, s[42:43]
	v_ashrrev_i32_e32 v23, 31, v22
	v_lshlrev_b64 v[22:23], 12, v[22:23]
	v_lshl_add_u64 v[22:23], s[68:69], 0, v[22:23]
	v_lshl_add_u64 v[30:31], v[22:23], 0, v[188:189]
	v_lshl_add_u64 v[226:227], v[30:31], 0, v[242:243]
	global_load_dwordx4 v[214:217], v[226:227], off offset:-4096
	global_load_dwordx4 v[218:221], v[226:227], off
	v_lshlrev_b64 v[32:33], 11, v[18:19]
	v_lshl_add_u64 v[34:35], v[20:21], 0, v[188:189]
	v_lshl_add_u64 v[20:21], s[60:61], 0, v[32:33]
	v_lshl_add_u64 v[32:33], v[186:187], 1, v[20:21]
	s_waitcnt vmcnt(0)
	v_cndmask_b32_e64 v222, v218, v214, s[100:101]
	v_cndmask_b32_e64 v223, v219, v215, s[100:101]
	v_cndmask_b32_e64 v224, v220, v216, s[100:101]
	v_cndmask_b32_e64 v225, v221, v217, s[100:101]
	v_mov_b32_dpp v238, v222 quad_perm:[1,0,3,2] row_mask:0xf bank_mask:0xf
	v_mov_b32_dpp v239, v223 quad_perm:[1,0,3,2] row_mask:0xf bank_mask:0xf
	v_mov_b32_dpp v240, v224 quad_perm:[1,0,3,2] row_mask:0xf bank_mask:0xf
	v_mov_b32_dpp v241, v225 quad_perm:[1,0,3,2] row_mask:0xf bank_mask:0xf
	v_cndmask_b32_e64 v22, v214, v238, s[100:101]
	v_cndmask_b32_e64 v26, v238, v218, s[100:101]
	v_cndmask_b32_e64 v23, v215, v239, s[100:101]
	v_cndmask_b32_e64 v27, v239, v219, s[100:101]
	v_cndmask_b32_e64 v24, v216, v240, s[100:101]
	v_cndmask_b32_e64 v28, v240, v220, s[100:101]
	v_cndmask_b32_e64 v25, v217, v241, s[100:101]
	v_cndmask_b32_e64 v29, v241, v221, s[100:101]
	v_pk_fma_f32 v[16:17], v[16:17], v[96:97], v[24:25]
	v_pk_fma_f32 v[14:15], v[14:15], v[94:95], v[22:23]
	s_waitcnt vmcnt(0)
	v_pk_fma_f32 v[12:13], v[12:13], v[88:89], v[28:29]
	v_pk_fma_f32 v[10:11], v[10:11], v[86:87], v[26:27]
	v_pk_mul_f32 v[22:23], v[92:93], v[16:17]
	v_pk_mul_f32 v[20:21], v[90:91], v[14:15]
	v_pk_mul_f32 v[24:25], v[84:85], v[12:13]
	v_pk_mul_f32 v[26:27], v[82:83], v[10:11]
	v_cvt_pk_bf16_f32 v20, v20, v21
	v_cvt_pk_bf16_f32 v21, v22, v23
	v_cvt_pk_bf16_f32 v22, v26, v27
	v_cvt_pk_bf16_f32 v23, v24, v25
	v_cndmask_b32_e64 v222, v10, v14, s[100:101]
	v_cndmask_b32_e64 v223, v11, v15, s[100:101]
	v_cndmask_b32_e64 v224, v12, v16, s[100:101]
	v_cndmask_b32_e64 v225, v13, v17, s[100:101]
	v_mov_b32_dpp v238, v222 quad_perm:[1,0,3,2] row_mask:0xf bank_mask:0xf
	v_mov_b32_dpp v239, v223 quad_perm:[1,0,3,2] row_mask:0xf bank_mask:0xf
	v_mov_b32_dpp v240, v224 quad_perm:[1,0,3,2] row_mask:0xf bank_mask:0xf
	v_mov_b32_dpp v241, v225 quad_perm:[1,0,3,2] row_mask:0xf bank_mask:0xf
	v_cndmask_b32_e64 v214, v14, v238, s[100:101]
	v_cndmask_b32_e64 v218, v238, v10, s[100:101]
	v_cndmask_b32_e64 v215, v15, v239, s[100:101]
	v_cndmask_b32_e64 v219, v239, v11, s[100:101]
	v_cndmask_b32_e64 v216, v16, v240, s[100:101]
	v_cndmask_b32_e64 v220, v240, v12, s[100:101]
	v_cndmask_b32_e64 v217, v17, v241, s[100:101]
	v_cndmask_b32_e64 v221, v241, v13, s[100:101]
	v_lshl_add_u64 v[226:227], v[34:35], 0, v[242:243]
	global_store_dwordx4 v[226:227], v[214:217], off offset:-4096
	global_store_dwordx4 v[226:227], v[218:221], off
	global_store_dwordx4 v[32:33], v[20:23], off
	v_lshl_add_u64 v[226:227], v[30:31], 0, v[242:243]
	global_load_dwordx4 v[214:217], v[226:227], off offset:-3584
	global_load_dwordx4 v[218:221], v[226:227], off offset:512
	s_nop 0
	v_mul_f32_e32 v15, v15, v15
	v_mul_f32_e32 v17, v17, v17
	v_mul_f32_e32 v11, v11, v11
	v_fmac_f32_e32 v15, v14, v14
	v_fmac_f32_e32 v17, v16, v16
	v_mul_f32_e32 v13, v13, v13
	v_fmac_f32_e32 v11, v10, v10
	v_add_f32_e32 v10, v15, v17
	v_fmac_f32_e32 v13, v12, v12
	v_add_f32_e32 v10, v10, v11
	v_add_f32_e32 v10, v13, v10
	s_waitcnt vmcnt(0)
	v_cndmask_b32_e64 v222, v218, v214, s[100:101]
	v_cndmask_b32_e64 v223, v219, v215, s[100:101]
	v_cndmask_b32_e64 v224, v220, v216, s[100:101]
	v_cndmask_b32_e64 v225, v221, v217, s[100:101]
	v_mov_b32_dpp v238, v222 quad_perm:[1,0,3,2] row_mask:0xf bank_mask:0xf
	v_mov_b32_dpp v239, v223 quad_perm:[1,0,3,2] row_mask:0xf bank_mask:0xf
	v_mov_b32_dpp v240, v224 quad_perm:[1,0,3,2] row_mask:0xf bank_mask:0xf
	v_mov_b32_dpp v241, v225 quad_perm:[1,0,3,2] row_mask:0xf bank_mask:0xf
	v_cndmask_b32_e64 v20, v214, v238, s[100:101]
	v_cndmask_b32_e64 v24, v238, v218, s[100:101]
	v_cndmask_b32_e64 v21, v215, v239, s[100:101]
	v_cndmask_b32_e64 v25, v239, v219, s[100:101]
	v_cndmask_b32_e64 v22, v216, v240, s[100:101]
	v_cndmask_b32_e64 v26, v240, v220, s[100:101]
	v_cndmask_b32_e64 v23, v217, v241, s[100:101]
	v_cndmask_b32_e64 v27, v241, v221, s[100:101]
	v_pk_fma_f32 v[8:9], v[8:9], v[80:81], v[22:23]
	v_pk_fma_f32 v[6:7], v[6:7], v[78:79], v[20:21]
	s_waitcnt vmcnt(0)
	v_pk_fma_f32 v[2:3], v[2:3], v[74:75], v[24:25]
	v_mul_f32_e32 v11, v7, v7
	v_mul_f32_e32 v12, v9, v9
	v_pk_fma_f32 v[4:5], v[4:5], v[76:77], v[26:27]
	v_mul_f32_e32 v13, v3, v3
	v_fmac_f32_e32 v11, v6, v6
	v_fmac_f32_e32 v12, v8, v8
	v_mul_f32_e32 v14, v5, v5
	v_fmac_f32_e32 v13, v2, v2
	v_add_f32_e32 v11, v11, v12
	v_fmac_f32_e32 v14, v4, v4
	v_add_f32_e32 v11, v11, v13
	v_add_f32_e32 v11, v14, v11
	v_add_f32_e32 v14, v10, v11
	ds_bpermute_b32 v15, v200, v14
	v_cndmask_b32_e64 v222, v2, v6, s[100:101]
	v_cndmask_b32_e64 v223, v3, v7, s[100:101]
	v_cndmask_b32_e64 v224, v4, v8, s[100:101]
	v_cndmask_b32_e64 v225, v5, v9, s[100:101]
	v_mov_b32_dpp v238, v222 quad_perm:[1,0,3,2] row_mask:0xf bank_mask:0xf
	v_mov_b32_dpp v239, v223 quad_perm:[1,0,3,2] row_mask:0xf bank_mask:0xf
	v_mov_b32_dpp v240, v224 quad_perm:[1,0,3,2] row_mask:0xf bank_mask:0xf
	v_mov_b32_dpp v241, v225 quad_perm:[1,0,3,2] row_mask:0xf bank_mask:0xf
	v_cndmask_b32_e64 v214, v6, v238, s[100:101]
	v_cndmask_b32_e64 v218, v238, v2, s[100:101]
	v_cndmask_b32_e64 v215, v7, v239, s[100:101]
	v_cndmask_b32_e64 v219, v239, v3, s[100:101]
	v_cndmask_b32_e64 v216, v8, v240, s[100:101]
	v_cndmask_b32_e64 v220, v240, v4, s[100:101]
	v_cndmask_b32_e64 v217, v9, v241, s[100:101]
	v_cndmask_b32_e64 v221, v241, v5, s[100:101]
	v_lshl_add_u64 v[226:227], v[34:35], 0, v[242:243]
	global_store_dwordx4 v[226:227], v[214:217], off offset:-3584
	global_store_dwordx4 v[226:227], v[218:221], off offset:512
	v_pk_mul_f32 v[12:13], v[58:59], v[2:3]
	v_pk_mul_f32 v[8:9], v[64:65], v[8:9]
	v_pk_mul_f32 v[6:7], v[62:63], v[6:7]
	s_waitcnt lgkmcnt(0)
	v_add_f32_e32 v2, v14, v15
	ds_bpermute_b32 v3, v195, v2
	v_pk_mul_f32 v[10:11], v[60:61], v[4:5]
	v_cvt_pk_bf16_f32 v4, v6, v7
	v_cvt_pk_bf16_f32 v5, v8, v9
	v_cvt_pk_bf16_f32 v6, v12, v13
	v_cvt_pk_bf16_f32 v7, v10, v11
	global_store_dwordx4 v[32:33], v[4:7], off offset:256
	s_and_saveexec_b64 s[34:35], s[38:39]
	s_cbranch_execz .LBB0_966
	v_lshlrev_b64 v[4:5], 6, v[18:19]
	v_lshl_add_u64 v[4:5], s[62:63], 0, v[4:5]
	v_lshl_add_u64 v[4:5], s[24:25], 2, v[4:5]
	s_lshl_b32 s0, s47, 2
	v_lshl_add_u64 v[4:5], v[4:5], 0, s[0:1]
	s_waitcnt lgkmcnt(0)
	v_add_f32_e32 v2, v2, v3
	global_store_dword v[4:5], v2, off

; __device__ __forceinline__ unsigned pk2(float lo, float hi) { return pg8::cvt_pk_bf16(lo, hi); }
;     __device__ __forceinline__ void operator()(const f32x4 (&acc)[2][2][4][2], const pg8::Unit& u, int wr, int wc, int fr, int fq) const {
;     ...
;         for (int ai = 0; ai < 2; ++ai)
; #pragma unroll
;             for (int m = 0; m < 4; ++m) {
;                 const int R = rowbase + u.pm * 256 + ai * 128 + wr * 64 + m * 16 + fr;
;                 const float* src = islat ? rin_l + (size_t)R * DM : rin_c + (size_t)(R - TL) * DM;
;                 float* dst = islat ? rout_l + (size_t)R * DM : rout_c + (size_t)(R - TL) * DM;
;                 float ss = 0.f;
; #pragma unroll
;                 for (int bj = 0; bj < 2; ++bj) { const int c = u.pn * 256 + bj * 128 + wc * 32 + 8 * fq;
;                     const f32x4 xa = *(const f32x4*)(src + c) + gv[bj][0] * acc[ai][bj][m][0];
;                     const f32x4 xb = *(const f32x4*)(src + c + 4) + gv[bj][1] * acc[ai][bj][m][1];
;                     *(f32x4*)(dst + c) = xa; *(f32x4*)(dst + c + 4) = xb;
;                     ss += (xa[0] * xa[0] + xa[1] * xa[1]) + (xa[2] * xa[2] + xa[3] * xa[3]) + (xb[0] * xb[0] + xb[1] * xb[1]) + (xb[2] * xb[2] + xb[3] * xb[3]);
;                     const f32x4 ya = xa * sv[bj][0], yb = xb * sv[bj][1];
;                     u32x4 w; w.x = pk2(ya[0], ya[1]); w.y = pk2(ya[2], ya[3]); w.z = pk2(yb[0], yb[1]); w.w = pk2(yb[2], yb[3]);
;                     *(u32x4*)(Hn + (size_t)R * DM + c) = w; }
.LBB0_1215:
	v_and_b32_e32 v200, 64, v228
	v_xor_b32_e32 v195, 16, v228
	v_add_u32_e32 v202, 64, v200
	v_cmp_lt_i32_e32 vcc, v195, v202
	s_lshl_b32 s24, s0, 2
	s_ashr_i32 s25, s24, 31
	v_cndmask_b32_e32 v195, v228, v195, vcc
	v_lshlrev_b32_e32 v200, 2, v195
	v_xor_b32_e32 v195, 32, v228
	v_cmp_lt_i32_e32 vcc, v195, v202
	v_cndmask_b32_e64 v202, v194, v190, s[42:43]
	s_and_b64 s[10:11], s[42:43], exec
	v_ashrrev_i32_e32 v203, 31, v202
	s_cselect_b32 s69, s49, s67
	s_cselect_b32 s68, s48, s66
	v_lshlrev_b64 v[202:203], 12, v[202:203]
	v_lshl_add_u64 v[202:203], s[68:69], 0, v[202:203]
	v_lshl_add_u64 v[212:213], v[202:203], 0, v[188:189]
	s_mov_b32 s100, 0xaaaaaaaa
	s_mov_b32 s101, 0xaaaaaaaa
	v_mov_b32_e32 v222, 0x1000
	v_mov_b32_e32 v223, 16
	v_cndmask_b32_e64 v242, v222, v223, s[100:101]
	v_mov_b32_e32 v243, 0
	v_lshl_add_u64 v[226:227], v[212:213], 0, v[242:243]
	global_load_dwordx4 v[214:217], v[226:227], off offset:-4096
	global_load_dwordx4 v[218:221], v[226:227], off
	v_lshlrev_b64 v[210:211], 11, v[190:191]
	v_cndmask_b32_e32 v195, v228, v195, vcc
	v_lshlrev_b32_e32 v195, 2, v195
	s_waitcnt vmcnt(0)
	v_cndmask_b32_e64 v222, v218, v214, s[100:101]
	v_cndmask_b32_e64 v223, v219, v215, s[100:101]
	v_cndmask_b32_e64 v224, v220, v216, s[100:101]
	v_cndmask_b32_e64 v225, v221, v217, s[100:101]
	v_mov_b32_dpp v238, v222 quad_perm:[1,0,3,2] row_mask:0xf bank_mask:0xf
	v_mov_b32_dpp v239, v223 quad_perm:[1,0,3,2] row_mask:0xf bank_mask:0xf
	v_mov_b32_dpp v240, v224 quad_perm:[1,0,3,2] row_mask:0xf bank_mask:0xf
	v_mov_b32_dpp v241, v225 quad_perm:[1,0,3,2] row_mask:0xf bank_mask:0xf
	v_cndmask_b32_e64 v206, v214, v238, s[100:101]
	v_cndmask_b32_e64 v202, v238, v218, s[100:101]
	v_cndmask_b32_e64 v207, v215, v239, s[100:101]
	v_cndmask_b32_e64 v203, v239, v219, s[100:101]
	v_cndmask_b32_e64 v208, v216, v240, s[100:101]
	v_cndmask_b32_e64 v204, v240, v220, s[100:101]
	v_cndmask_b32_e64 v209, v217, v241, s[100:101]
	v_cndmask_b32_e64 v205, v241, v221, s[100:101]
	v_pk_fma_f32 v[204:205], v[156:157], v[88:89], v[204:205]
	v_pk_fma_f32 v[160:161], v[160:161], v[96:97], v[208:209]
	v_pk_fma_f32 v[158:159], v[158:159], v[94:95], v[206:207]
	v_mul_f32_e32 v157, v161, v161
	v_mul_f32_e32 v156, v159, v159
	v_pk_fma_f32 v[202:203], v[154:155], v[86:87], v[202:203]
	v_fmac_f32_e32 v156, v158, v158
	v_fmac_f32_e32 v157, v160, v160
	v_add_f32_e32 v156, v156, v157
	v_mul_f32_e32 v157, v203, v203
	v_fmac_f32_e32 v157, v202, v202
	v_add_f32_e32 v156, v156, v157
	v_mul_f32_e32 v157, v205, v205
	v_lshl_add_u64 v[154:155], v[192:193], 0, v[188:189]
	v_fmac_f32_e32 v157, v204, v204
	v_cndmask_b32_e64 v222, v202, v158, s[100:101]
	v_cndmask_b32_e64 v223, v203, v159, s[100:101]
	v_cndmask_b32_e64 v224, v204, v160, s[100:101]
	v_cndmask_b32_e64 v225, v205, v161, s[100:101]
	v_mov_b32_dpp v238, v222 quad_perm:[1,0,3,2] row_mask:0xf bank_mask:0xf
	v_mov_b32_dpp v239, v223 quad_perm:[1,0,3,2] row_mask:0xf bank_mask:0xf
	v_mov_b32_dpp v240, v224 quad_perm:[1,0,3,2] row_mask:0xf bank_mask:0xf
	v_mov_b32_dpp v241, v225 quad_perm:[1,0,3,2] row_mask:0xf bank_mask:0xf
	v_cndmask_b32_e64 v214, v158, v238, s[100:101]
	v_cndmask_b32_e64 v218, v238, v202, s[100:101]
	v_cndmask_b32_e64 v215, v159, v239, s[100:101]
	v_cndmask_b32_e64 v219, v239, v203, s[100:101]
	v_cndmask_b32_e64 v216, v160, v240, s[100:101]
	v_cndmask_b32_e64 v220, v240, v204, s[100:101]
	v_cndmask_b32_e64 v217, v161, v241, s[100:101]
	v_cndmask_b32_e64 v221, v241, v205, s[100:101]
	v_lshl_add_u64 v[226:227], v[154:155], 0, v[242:243]
	global_store_dwordx4 v[226:227], v[214:217], off offset:-4096
	global_store_dwordx4 v[226:227], v[218:221], off
	v_add_f32_e32 v194, v157, v156
	v_pk_mul_f32 v[160:161], v[92:93], v[160:161]
	v_pk_mul_f32 v[156:157], v[90:91], v[158:159]
	v_pk_mul_f32 v[192:193], v[84:85], v[204:205]
	v_pk_mul_f32 v[158:159], v[82:83], v[202:203]
	v_cvt_pk_bf16_f32 v156, v156, v157
	v_cvt_pk_bf16_f32 v157, v160, v161
	v_lshl_add_u64 v[160:161], s[60:61], 0, v[210:211]
	v_cvt_pk_bf16_f32 v158, v158, v159
	v_cvt_pk_bf16_f32 v159, v192, v193
	v_lshl_add_u64 v[160:161], v[186:187], 1, v[160:161]
	global_store_dwordx4 v[160:161], v[156:159], off
	v_lshl_add_u64 v[226:227], v[212:213], 0, v[242:243]
	global_load_dwordx4 v[214:217], v[226:227], off offset:-3584
	global_load_dwordx4 v[218:221], v[226:227], off offset:512
	s_nop 0
	s_waitcnt vmcnt(0)
; __device__ __forceinline__ unsigned pk2(float lo, float hi) { return pg8::cvt_pk_bf16(lo, hi); }
;     __device__ __forceinline__ void operator()(const f32x4 (&acc)[2][2][4][2], const pg8::Unit& u, int wr, int wc, int fr, int fq) const {
;     ...
;                 for (int bj = 0; bj < 2; ++bj) { const int c = u.pn * 256 + bj * 128 + wc * 32 + 8 * fq;
;                     const f32x4 xa = *(const f32x4*)(src + c) + gv[bj][0] * acc[ai][bj][m][0];
;                     const f32x4 xb = *(const f32x4*)(src + c + 4) + gv[bj][1] * acc[ai][bj][m][1];
;                     *(f32x4*)(dst + c) = xa; *(f32x4*)(dst + c + 4) = xb;
;                     ss += (xa[0] * xa[0] + xa[1] * xa[1]) + (xa[2] * xa[2] + xa[3] * xa[3]) + (xb[0] * xb[0] + xb[1] * xb[1]) + (xb[2] * xb[2] + xb[3] * xb[3]);
;                     const f32x4 ya = xa * sv[bj][0], yb = xb * sv[bj][1];
;                     u32x4 w; w.x = pk2(ya[0], ya[1]); w.y = pk2(ya[2], ya[3]); w.z = pk2(yb[0], yb[1]); w.w = pk2(yb[2], yb[3]);
;                     *(u32x4*)(Hn + (size_t)R * DM + c) = w; }
;                 ss += __shfl_xor(ss, 16); ss += __shfl_xor(ss, 32);
;                 if (fq == 0) stat[(size_t)R * 16 + u.pn * 4 + wc] = ss;
	v_cndmask_b32_e64 v222, v218, v214, s[100:101]
	v_cndmask_b32_e64 v223, v219, v215, s[100:101]
	v_cndmask_b32_e64 v224, v220, v216, s[100:101]
	v_cndmask_b32_e64 v225, v221, v217, s[100:101]
	v_mov_b32_dpp v238, v222 quad_perm:[1,0,3,2] row_mask:0xf bank_mask:0xf
	v_mov_b32_dpp v239, v223 quad_perm:[1,0,3,2] row_mask:0xf bank_mask:0xf
	v_mov_b32_dpp v240, v224 quad_perm:[1,0,3,2] row_mask:0xf bank_mask:0xf
	v_mov_b32_dpp v241, v225 quad_perm:[1,0,3,2] row_mask:0xf bank_mask:0xf
	v_cndmask_b32_e64 v202, v214, v238, s[100:101]
	v_cndmask_b32_e64 v156, v238, v218, s[100:101]
	v_cndmask_b32_e64 v203, v215, v239, s[100:101]
	v_cndmask_b32_e64 v157, v239, v219, s[100:101]
	v_cndmask_b32_e64 v204, v216, v240, s[100:101]
	v_cndmask_b32_e64 v158, v240, v220, s[100:101]
	v_cndmask_b32_e64 v205, v217, v241, s[100:101]
	v_cndmask_b32_e64 v159, v241, v221, s[100:101]
	v_pk_fma_f32 v[148:149], v[148:149], v[76:77], v[158:159]
	s_waitcnt vmcnt(0)
	v_pk_fma_f32 v[152:153], v[152:153], v[80:81], v[204:205]
	v_pk_fma_f32 v[150:151], v[150:151], v[78:79], v[202:203]
	v_pk_fma_f32 v[146:147], v[146:147], v[74:75], v[156:157]
	v_cndmask_b32_e64 v222, v146, v150, s[100:101]
	v_cndmask_b32_e64 v223, v147, v151, s[100:101]
	v_cndmask_b32_e64 v224, v148, v152, s[100:101]
	v_cndmask_b32_e64 v225, v149, v153, s[100:101]
	v_mov_b32_dpp v238, v222 quad_perm:[1,0,3,2] row_mask:0xf bank_mask:0xf
	v_mov_b32_dpp v239, v223 quad_perm:[1,0,3,2] row_mask:0xf bank_mask:0xf
	v_mov_b32_dpp v240, v224 quad_perm:[1,0,3,2] row_mask:0xf bank_mask:0xf
	v_mov_b32_dpp v241, v225 quad_perm:[1,0,3,2] row_mask:0xf bank_mask:0xf
	v_cndmask_b32_e64 v214, v150, v238, s[100:101]
	v_cndmask_b32_e64 v218, v238, v146, s[100:101]
	v_cndmask_b32_e64 v215, v151, v239, s[100:101]
	v_cndmask_b32_e64 v219, v239, v147, s[100:101]
	v_cndmask_b32_e64 v216, v152, v240, s[100:101]
	v_cndmask_b32_e64 v220, v240, v148, s[100:101]
	v_cndmask_b32_e64 v217, v153, v241, s[100:101]
	v_cndmask_b32_e64 v221, v241, v149, s[100:101]
	v_lshl_add_u64 v[226:227], v[154:155], 0, v[242:243]
	global_store_dwordx4 v[226:227], v[214:217], off offset:-3584
	global_store_dwordx4 v[226:227], v[218:221], off offset:512
	v_mul_f32_e32 v154, v151, v151
	v_mul_f32_e32 v155, v153, v153
	v_fmac_f32_e32 v154, v150, v150
	v_fmac_f32_e32 v155, v152, v152
	v_add_f32_e32 v154, v154, v155
	v_mul_f32_e32 v155, v147, v147
	v_fmac_f32_e32 v155, v146, v146
	v_add_f32_e32 v154, v154, v155
	v_mul_f32_e32 v155, v149, v149
	v_fmac_f32_e32 v155, v148, v148
	v_add_f32_e32 v154, v155, v154
	v_add_f32_e32 v156, v194, v154
	v_pk_mul_f32 v[152:153], v[64:65], v[152:153]
	v_pk_mul_f32 v[150:151], v[62:63], v[150:151]
	v_pk_mul_f32 v[154:155], v[60:61], v[148:149]
	v_pk_mul_f32 v[148:149], v[58:59], v[146:147]
	v_cvt_pk_bf16_f32 v146, v150, v151
	v_cvt_pk_bf16_f32 v147, v152, v153
	v_cvt_pk_bf16_f32 v148, v148, v149
	v_cvt_pk_bf16_f32 v149, v154, v155
	global_store_dwordx4 v[160:161], v[146:149], off offset:256
	ds_bpermute_b32 v146, v200, v156
	s_waitcnt lgkmcnt(0)
	v_add_f32_e32 v146, v156, v146
	ds_bpermute_b32 v147, v195, v146
	s_and_saveexec_b64 s[34:35], s[38:39]
	s_cbranch_execz .LBB0_1217
	v_lshlrev_b64 v[148:149], 6, v[190:191]
	v_lshl_add_u64 v[148:149], s[62:63], 0, v[148:149]
	v_lshl_add_u64 v[148:149], s[24:25], 2, v[148:149]
	s_lshl_b32 s0, s56, 2
	v_lshl_add_u64 v[148:149], v[148:149], 0, s[0:1]
	s_waitcnt lgkmcnt(0)
	v_add_f32_e32 v146, v146, v147
	global_store_dword v[148:149], v146, off

; __device__ __forceinline__ unsigned pk2(float lo, float hi) { return pg8::cvt_pk_bf16(lo, hi); }
;     __device__ __forceinline__ void operator()(const f32x4 (&acc)[2][2][4][2], const pg8::Unit& u, int wr, int wc, int fr, int fq) const {
;     ...
;             for (int m = 0; m < 4; ++m) {
;                 const int R = rowbase + u.pm * 256 + ai * 128 + wr * 64 + m * 16 + fr;
;                 const float* src = islat ? rin_l + (size_t)R * DM : rin_c + (size_t)(R - TL) * DM;
;                 float* dst = islat ? rout_l + (size_t)R * DM : rout_c + (size_t)(R - TL) * DM;
;                 float ss = 0.f;
; #pragma unroll
;                 for (int bj = 0; bj < 2; ++bj) { const int c = u.pn * 256 + bj * 128 + wc * 32 + 8 * fq;
;                     const f32x4 xa = *(const f32x4*)(src + c) + gv[bj][0] * acc[ai][bj][m][0];
;                     const f32x4 xb = *(const f32x4*)(src + c + 4) + gv[bj][1] * acc[ai][bj][m][1];
;                     *(f32x4*)(dst + c) = xa; *(f32x4*)(dst + c + 4) = xb;
;                     ss += (xa[0] * xa[0] + xa[1] * xa[1]) + (xa[2] * xa[2] + xa[3] * xa[3]) + (xb[0] * xb[0] + xb[1] * xb[1]) + (xb[2] * xb[2] + xb[3] * xb[3]);
;                     const f32x4 ya = xa * sv[bj][0], yb = xb * sv[bj][1];
;                     u32x4 w; w.x = pk2(ya[0], ya[1]); w.y = pk2(ya[2], ya[3]); w.z = pk2(yb[0], yb[1]); w.w = pk2(yb[2], yb[3]);
;                     *(u32x4*)(Hn + (size_t)R * DM + c) = w; }
.LBB0_1221:
	v_cndmask_b32_e64 v150, v150, v146, s[42:43]
	v_ashrrev_i32_e32 v151, 31, v150
	v_lshlrev_b64 v[150:151], 12, v[150:151]
	v_lshl_add_u64 v[150:151], s[68:69], 0, v[150:151]
	v_lshl_add_u64 v[158:159], v[150:151], 0, v[188:189]
	v_lshl_add_u64 v[226:227], v[158:159], 0, v[242:243]
	global_load_dwordx4 v[214:217], v[226:227], off offset:-4096
	global_load_dwordx4 v[218:221], v[226:227], off
	v_lshlrev_b64 v[160:161], 11, v[146:147]
	v_lshl_add_u64 v[192:193], v[148:149], 0, v[188:189]
	v_lshl_add_u64 v[148:149], s[60:61], 0, v[160:161]
	v_lshl_add_u64 v[160:161], v[186:187], 1, v[148:149]
	s_waitcnt vmcnt(0)
	v_cndmask_b32_e64 v222, v218, v214, s[100:101]
	v_cndmask_b32_e64 v223, v219, v215, s[100:101]
	v_cndmask_b32_e64 v224, v220, v216, s[100:101]
	v_cndmask_b32_e64 v225, v221, v217, s[100:101]
	v_mov_b32_dpp v238, v222 quad_perm:[1,0,3,2] row_mask:0xf bank_mask:0xf
	v_mov_b32_dpp v239, v223 quad_perm:[1,0,3,2] row_mask:0xf bank_mask:0xf
	v_mov_b32_dpp v240, v224 quad_perm:[1,0,3,2] row_mask:0xf bank_mask:0xf
	v_mov_b32_dpp v241, v225 quad_perm:[1,0,3,2] row_mask:0xf bank_mask:0xf
	v_cndmask_b32_e64 v150, v214, v238, s[100:101]
	v_cndmask_b32_e64 v154, v238, v218, s[100:101]
	v_cndmask_b32_e64 v151, v215, v239, s[100:101]
	v_cndmask_b32_e64 v155, v239, v219, s[100:101]
	v_cndmask_b32_e64 v152, v216, v240, s[100:101]
	v_cndmask_b32_e64 v156, v240, v220, s[100:101]
	v_cndmask_b32_e64 v153, v217, v241, s[100:101]
	v_cndmask_b32_e64 v157, v241, v221, s[100:101]
	v_pk_fma_f32 v[144:145], v[144:145], v[96:97], v[152:153]
	v_pk_fma_f32 v[142:143], v[142:143], v[94:95], v[150:151]
	s_waitcnt vmcnt(0)
	v_pk_fma_f32 v[140:141], v[140:141], v[88:89], v[156:157]
	v_pk_fma_f32 v[138:139], v[138:139], v[86:87], v[154:155]
	v_pk_mul_f32 v[150:151], v[92:93], v[144:145]
	v_pk_mul_f32 v[148:149], v[90:91], v[142:143]
	v_pk_mul_f32 v[152:153], v[84:85], v[140:141]
	v_pk_mul_f32 v[154:155], v[82:83], v[138:139]
	v_cvt_pk_bf16_f32 v148, v148, v149
	v_cvt_pk_bf16_f32 v149, v150, v151
	v_cvt_pk_bf16_f32 v150, v154, v155
	v_cvt_pk_bf16_f32 v151, v152, v153
	v_cndmask_b32_e64 v222, v138, v142, s[100:101]
	v_cndmask_b32_e64 v223, v139, v143, s[100:101]
	v_cndmask_b32_e64 v224, v140, v144, s[100:101]
	v_cndmask_b32_e64 v225, v141, v145, s[100:101]
	v_mov_b32_dpp v238, v222 quad_perm:[1,0,3,2] row_mask:0xf bank_mask:0xf
	v_mov_b32_dpp v239, v223 quad_perm:[1,0,3,2] row_mask:0xf bank_mask:0xf
	v_mov_b32_dpp v240, v224 quad_perm:[1,0,3,2] row_mask:0xf bank_mask:0xf
	v_mov_b32_dpp v241, v225 quad_perm:[1,0,3,2] row_mask:0xf bank_mask:0xf
	v_cndmask_b32_e64 v214, v142, v238, s[100:101]
	v_cndmask_b32_e64 v218, v238, v138, s[100:101]
	v_cndmask_b32_e64 v215, v143, v239, s[100:101]
	v_cndmask_b32_e64 v219, v239, v139, s[100:101]
	v_cndmask_b32_e64 v216, v144, v240, s[100:101]
	v_cndmask_b32_e64 v220, v240, v140, s[100:101]
	v_cndmask_b32_e64 v217, v145, v241, s[100:101]
	v_cndmask_b32_e64 v221, v241, v141, s[100:101]
	v_lshl_add_u64 v[226:227], v[192:193], 0, v[242:243]
	global_store_dwordx4 v[226:227], v[214:217], off offset:-4096
	global_store_dwordx4 v[226:227], v[218:221], off
	global_store_dwordx4 v[160:161], v[148:151], off
	v_lshl_add_u64 v[226:227], v[158:159], 0, v[242:243]
	global_load_dwordx4 v[214:217], v[226:227], off offset:-3584
	global_load_dwordx4 v[218:221], v[226:227], off offset:512
	s_nop 0
	v_mul_f32_e32 v143, v143, v143
	v_mul_f32_e32 v145, v145, v145
	v_mul_f32_e32 v139, v139, v139
	v_fmac_f32_e32 v143, v142, v142
	v_fmac_f32_e32 v145, v144, v144
	v_mul_f32_e32 v141, v141, v141
	v_fmac_f32_e32 v139, v138, v138
	v_add_f32_e32 v138, v143, v145
	v_fmac_f32_e32 v141, v140, v140
	v_add_f32_e32 v138, v138, v139
	v_add_f32_e32 v138, v141, v138
	s_waitcnt vmcnt(0)
	v_cndmask_b32_e64 v222, v218, v214, s[100:101]
	v_cndmask_b32_e64 v223, v219, v215, s[100:101]
	v_cndmask_b32_e64 v224, v220, v216, s[100:101]
	v_cndmask_b32_e64 v225, v221, v217, s[100:101]
	v_mov_b32_dpp v238, v222 quad_perm:[1,0,3,2] row_mask:0xf bank_mask:0xf
	v_mov_b32_dpp v239, v223 quad_perm:[1,0,3,2] row_mask:0xf bank_mask:0xf
	v_mov_b32_dpp v240, v224 quad_perm:[1,0,3,2] row_mask:0xf bank_mask:0xf
	v_mov_b32_dpp v241, v225 quad_perm:[1,0,3,2] row_mask:0xf bank_mask:0xf
	v_cndmask_b32_e64 v148, v214, v238, s[100:101]
	v_cndmask_b32_e64 v152, v238, v218, s[100:101]
	v_cndmask_b32_e64 v149, v215, v239, s[100:101]
	v_cndmask_b32_e64 v153, v239, v219, s[100:101]
	v_cndmask_b32_e64 v150, v216, v240, s[100:101]
	v_cndmask_b32_e64 v154, v240, v220, s[100:101]
	v_cndmask_b32_e64 v151, v217, v241, s[100:101]
	v_cndmask_b32_e64 v155, v241, v221, s[100:101]
	v_pk_fma_f32 v[136:137], v[136:137], v[80:81], v[150:151]
	v_pk_fma_f32 v[134:135], v[134:135], v[78:79], v[148:149]
	s_waitcnt vmcnt(0)
	v_pk_fma_f32 v[130:131], v[130:131], v[74:75], v[152:153]
	v_mul_f32_e32 v139, v135, v135
	v_mul_f32_e32 v140, v137, v137
	v_pk_fma_f32 v[132:133], v[132:133], v[76:77], v[154:155]
	v_mul_f32_e32 v141, v131, v131
	v_fmac_f32_e32 v139, v134, v134
	v_fmac_f32_e32 v140, v136, v136
	v_mul_f32_e32 v142, v133, v133
	v_fmac_f32_e32 v141, v130, v130
	v_add_f32_e32 v139, v139, v140
	v_fmac_f32_e32 v142, v132, v132
	v_add_f32_e32 v139, v139, v141
	v_add_f32_e32 v139, v142, v139
	v_add_f32_e32 v142, v138, v139
	ds_bpermute_b32 v143, v200, v142
	v_cndmask_b32_e64 v222, v130, v134, s[100:101]
	v_cndmask_b32_e64 v223, v131, v135, s[100:101]
	v_cndmask_b32_e64 v224, v132, v136, s[100:101]
	v_cndmask_b32_e64 v225, v133, v137, s[100:101]
	v_mov_b32_dpp v238, v222 quad_perm:[1,0,3,2] row_mask:0xf bank_mask:0xf
	v_mov_b32_dpp v239, v223 quad_perm:[1,0,3,2] row_mask:0xf bank_mask:0xf
	v_mov_b32_dpp v240, v224 quad_perm:[1,0,3,2] row_mask:0xf bank_mask:0xf
	v_mov_b32_dpp v241, v225 quad_perm:[1,0,3,2] row_mask:0xf bank_mask:0xf
	v_cndmask_b32_e64 v214, v134, v238, s[100:101]
	v_cndmask_b32_e64 v218, v238, v130, s[100:101]
	v_cndmask_b32_e64 v215, v135, v239, s[100:101]
	v_cndmask_b32_e64 v219, v239, v131, s[100:101]
	v_cndmask_b32_e64 v216, v136, v240, s[100:101]
	v_cndmask_b32_e64 v220, v240, v132, s[100:101]
	v_cndmask_b32_e64 v217, v137, v241, s[100:101]
	v_cndmask_b32_e64 v221, v241, v133, s[100:101]
	v_lshl_add_u64 v[226:227], v[192:193], 0, v[242:243]
	global_store_dwordx4 v[226:227], v[214:217], off offset:-3584
	global_store_dwordx4 v[226:227], v[218:221], off offset:512
	v_pk_mul_f32 v[140:141], v[58:59], v[130:131]
	v_pk_mul_f32 v[136:137], v[64:65], v[136:137]
	v_pk_mul_f32 v[134:135], v[62:63], v[134:135]
	s_waitcnt lgkmcnt(0)
	v_add_f32_e32 v130, v142, v143
	ds_bpermute_b32 v131, v195, v130
	v_pk_mul_f32 v[138:139], v[60:61], v[132:133]
	v_cvt_pk_bf16_f32 v132, v134, v135
	v_cvt_pk_bf16_f32 v133, v136, v137
	v_cvt_pk_bf16_f32 v134, v140, v141
	v_cvt_pk_bf16_f32 v135, v138, v139
	global_store_dwordx4 v[160:161], v[132:135], off offset:256
	s_and_saveexec_b64 s[34:35], s[38:39]
	s_cbranch_execz .LBB0_1223
;     __device__ __forceinline__ void operator()(const f32x4 (&acc)[2][2][4][2], const pg8::Unit& u, int wr, int wc, int fr, int fq) const {
;     ...
;                 if (fq == 0) stat[(size_t)R * 16 + u.pn * 4 + wc] = ss;
	v_lshlrev_b64 v[132:133], 6, v[146:147]
	v_lshl_add_u64 v[132:133], s[62:63], 0, v[132:133]
	v_lshl_add_u64 v[132:133], s[24:25], 2, v[132:133]
	s_lshl_b32 s0, s56, 2
	v_lshl_add_u64 v[132:133], v[132:133], 0, s[0:1]
	s_waitcnt lgkmcnt(0)
	v_add_f32_e32 v130, v130, v131
	global_store_dword v[132:133], v130, off

; __device__ __forceinline__ unsigned pk2(float lo, float hi) { return pg8::cvt_pk_bf16(lo, hi); }
;     __device__ __forceinline__ void operator()(const f32x4 (&acc)[2][2][4][2], const pg8::Unit& u, int wr, int wc, int fr, int fq) const {
;     ...
;             for (int m = 0; m < 4; ++m) {
;                 const int R = rowbase + u.pm * 256 + ai * 128 + wr * 64 + m * 16 + fr;
;                 const float* src = islat ? rin_l + (size_t)R * DM : rin_c + (size_t)(R - TL) * DM;
;                 float* dst = islat ? rout_l + (size_t)R * DM : rout_c + (size_t)(R - TL) * DM;
;                 float ss = 0.f;
; #pragma unroll
;                 for (int bj = 0; bj < 2; ++bj) { const int c = u.pn * 256 + bj * 128 + wc * 32 + 8 * fq;
;                     const f32x4 xa = *(const f32x4*)(src + c) + gv[bj][0] * acc[ai][bj][m][0];
;                     const f32x4 xb = *(const f32x4*)(src + c + 4) + gv[bj][1] * acc[ai][bj][m][1];
;                     *(f32x4*)(dst + c) = xa; *(f32x4*)(dst + c + 4) = xb;
;                     ss += (xa[0] * xa[0] + xa[1] * xa[1]) + (xa[2] * xa[2] + xa[3] * xa[3]) + (xb[0] * xb[0] + xb[1] * xb[1]) + (xb[2] * xb[2] + xb[3] * xb[3]);
;                     const f32x4 ya = xa * sv[bj][0], yb = xb * sv[bj][1];
;                     u32x4 w; w.x = pk2(ya[0], ya[1]); w.y = pk2(ya[2], ya[3]); w.z = pk2(yb[0], yb[1]); w.w = pk2(yb[2], yb[3]);
;                     *(u32x4*)(Hn + (size_t)R * DM + c) = w; }
;                 ss += __shfl_xor(ss, 16); ss += __shfl_xor(ss, 32);
;                 if (fq == 0) stat[(size_t)R * 16 + u.pn * 4 + wc] = ss;
;             }
.LBB0_1227:
	v_cndmask_b32_e64 v134, v134, v130, s[42:43]
	v_ashrrev_i32_e32 v135, 31, v134
	v_lshlrev_b64 v[134:135], 12, v[134:135]
	v_lshl_add_u64 v[134:135], s[68:69], 0, v[134:135]
	v_lshl_add_u64 v[142:143], v[134:135], 0, v[188:189]
	v_lshl_add_u64 v[226:227], v[142:143], 0, v[242:243]
	global_load_dwordx4 v[214:217], v[226:227], off offset:-4096
	global_load_dwordx4 v[218:221], v[226:227], off
	v_lshlrev_b64 v[144:145], 11, v[130:131]
	v_lshl_add_u64 v[146:147], v[132:133], 0, v[188:189]
	v_lshl_add_u64 v[132:133], s[60:61], 0, v[144:145]
	v_lshl_add_u64 v[144:145], v[186:187], 1, v[132:133]
	s_waitcnt vmcnt(0)
	v_cndmask_b32_e64 v222, v218, v214, s[100:101]
	v_cndmask_b32_e64 v223, v219, v215, s[100:101]
	v_cndmask_b32_e64 v224, v220, v216, s[100:101]
	v_cndmask_b32_e64 v225, v221, v217, s[100:101]
	v_mov_b32_dpp v238, v222 quad_perm:[1,0,3,2] row_mask:0xf bank_mask:0xf
	v_mov_b32_dpp v239, v223 quad_perm:[1,0,3,2] row_mask:0xf bank_mask:0xf
	v_mov_b32_dpp v240, v224 quad_perm:[1,0,3,2] row_mask:0xf bank_mask:0xf
	v_mov_b32_dpp v241, v225 quad_perm:[1,0,3,2] row_mask:0xf bank_mask:0xf
	v_cndmask_b32_e64 v134, v214, v238, s[100:101]
	v_cndmask_b32_e64 v138, v238, v218, s[100:101]
	v_cndmask_b32_e64 v135, v215, v239, s[100:101]
	v_cndmask_b32_e64 v139, v239, v219, s[100:101]
	v_cndmask_b32_e64 v136, v216, v240, s[100:101]
	v_cndmask_b32_e64 v140, v240, v220, s[100:101]
	v_cndmask_b32_e64 v137, v217, v241, s[100:101]
	v_cndmask_b32_e64 v141, v241, v221, s[100:101]
	v_pk_fma_f32 v[128:129], v[128:129], v[96:97], v[136:137]
	v_pk_fma_f32 v[126:127], v[126:127], v[94:95], v[134:135]
	s_waitcnt vmcnt(0)
	v_pk_fma_f32 v[124:125], v[124:125], v[88:89], v[140:141]
	v_pk_fma_f32 v[122:123], v[122:123], v[86:87], v[138:139]
	v_pk_mul_f32 v[134:135], v[92:93], v[128:129]
	v_pk_mul_f32 v[132:133], v[90:91], v[126:127]
	v_pk_mul_f32 v[136:137], v[84:85], v[124:125]
	v_pk_mul_f32 v[138:139], v[82:83], v[122:123]
	v_cvt_pk_bf16_f32 v132, v132, v133
	v_cvt_pk_bf16_f32 v133, v134, v135
	v_cvt_pk_bf16_f32 v134, v138, v139
	v_cvt_pk_bf16_f32 v135, v136, v137
	v_cndmask_b32_e64 v222, v122, v126, s[100:101]
	v_cndmask_b32_e64 v223, v123, v127, s[100:101]
	v_cndmask_b32_e64 v224, v124, v128, s[100:101]
	v_cndmask_b32_e64 v225, v125, v129, s[100:101]
	v_mov_b32_dpp v238, v222 quad_perm:[1,0,3,2] row_mask:0xf bank_mask:0xf
	v_mov_b32_dpp v239, v223 quad_perm:[1,0,3,2] row_mask:0xf bank_mask:0xf
	v_mov_b32_dpp v240, v224 quad_perm:[1,0,3,2] row_mask:0xf bank_mask:0xf
	v_mov_b32_dpp v241, v225 quad_perm:[1,0,3,2] row_mask:0xf bank_mask:0xf
	v_cndmask_b32_e64 v214, v126, v238, s[100:101]
	v_cndmask_b32_e64 v218, v238, v122, s[100:101]
	v_cndmask_b32_e64 v215, v127, v239, s[100:101]
	v_cndmask_b32_e64 v219, v239, v123, s[100:101]
	v_cndmask_b32_e64 v216, v128, v240, s[100:101]
	v_cndmask_b32_e64 v220, v240, v124, s[100:101]
	v_cndmask_b32_e64 v217, v129, v241, s[100:101]
	v_cndmask_b32_e64 v221, v241, v125, s[100:101]
	v_lshl_add_u64 v[226:227], v[146:147], 0, v[242:243]
	global_store_dwordx4 v[226:227], v[214:217], off offset:-4096
	global_store_dwordx4 v[226:227], v[218:221], off
	global_store_dwordx4 v[144:145], v[132:135], off
	v_lshl_add_u64 v[226:227], v[142:143], 0, v[242:243]
	global_load_dwordx4 v[214:217], v[226:227], off offset:-3584
	global_load_dwordx4 v[218:221], v[226:227], off offset:512
	s_nop 0
	v_mul_f32_e32 v127, v127, v127
	v_mul_f32_e32 v129, v129, v129
	v_mul_f32_e32 v123, v123, v123
	v_fmac_f32_e32 v127, v126, v126
	v_fmac_f32_e32 v129, v128, v128
	v_mul_f32_e32 v125, v125, v125
	v_fmac_f32_e32 v123, v122, v122
	v_add_f32_e32 v122, v127, v129
	v_fmac_f32_e32 v125, v124, v124
	v_add_f32_e32 v122, v122, v123
	v_add_f32_e32 v122, v125, v122
	s_waitcnt vmcnt(0)
	v_cndmask_b32_e64 v222, v218, v214, s[100:101]
	v_cndmask_b32_e64 v223, v219, v215, s[100:101]
	v_cndmask_b32_e64 v224, v220, v216, s[100:101]
	v_cndmask_b32_e64 v225, v221, v217, s[100:101]
	v_mov_b32_dpp v238, v222 quad_perm:[1,0,3,2] row_mask:0xf bank_mask:0xf
	v_mov_b32_dpp v239, v223 quad_perm:[1,0,3,2] row_mask:0xf bank_mask:0xf
	v_mov_b32_dpp v240, v224 quad_perm:[1,0,3,2] row_mask:0xf bank_mask:0xf
	v_mov_b32_dpp v241, v225 quad_perm:[1,0,3,2] row_mask:0xf bank_mask:0xf
	v_cndmask_b32_e64 v132, v214, v238, s[100:101]
	v_cndmask_b32_e64 v136, v238, v218, s[100:101]
	v_cndmask_b32_e64 v133, v215, v239, s[100:101]
	v_cndmask_b32_e64 v137, v239, v219, s[100:101]
	v_cndmask_b32_e64 v134, v216, v240, s[100:101]
	v_cndmask_b32_e64 v138, v240, v220, s[100:101]
	v_cndmask_b32_e64 v135, v217, v241, s[100:101]
	v_cndmask_b32_e64 v139, v241, v221, s[100:101]
	v_pk_fma_f32 v[120:121], v[120:121], v[80:81], v[134:135]
	v_pk_fma_f32 v[118:119], v[118:119], v[78:79], v[132:133]
	s_waitcnt vmcnt(0)
	v_pk_fma_f32 v[114:115], v[114:115], v[74:75], v[136:137]
	v_mul_f32_e32 v123, v119, v119
	v_mul_f32_e32 v124, v121, v121
	v_pk_fma_f32 v[116:117], v[116:117], v[76:77], v[138:139]
	v_mul_f32_e32 v125, v115, v115
	v_fmac_f32_e32 v123, v118, v118
	v_fmac_f32_e32 v124, v120, v120
	v_mul_f32_e32 v126, v117, v117
	v_fmac_f32_e32 v125, v114, v114
	v_add_f32_e32 v123, v123, v124
	v_fmac_f32_e32 v126, v116, v116
	v_add_f32_e32 v123, v123, v125
	v_add_f32_e32 v123, v126, v123
	v_add_f32_e32 v126, v122, v123
	ds_bpermute_b32 v127, v200, v126
	v_cndmask_b32_e64 v222, v114, v118, s[100:101]
	v_cndmask_b32_e64 v223, v115, v119, s[100:101]
	v_cndmask_b32_e64 v224, v116, v120, s[100:101]
	v_cndmask_b32_e64 v225, v117, v121, s[100:101]
	v_mov_b32_dpp v238, v222 quad_perm:[1,0,3,2] row_mask:0xf bank_mask:0xf
	v_mov_b32_dpp v239, v223 quad_perm:[1,0,3,2] row_mask:0xf bank_mask:0xf
	v_mov_b32_dpp v240, v224 quad_perm:[1,0,3,2] row_mask:0xf bank_mask:0xf
	v_mov_b32_dpp v241, v225 quad_perm:[1,0,3,2] row_mask:0xf bank_mask:0xf
	v_cndmask_b32_e64 v214, v118, v238, s[100:101]
	v_cndmask_b32_e64 v218, v238, v114, s[100:101]
	v_cndmask_b32_e64 v215, v119, v239, s[100:101]
	v_cndmask_b32_e64 v219, v239, v115, s[100:101]
	v_cndmask_b32_e64 v216, v120, v240, s[100:101]
	v_cndmask_b32_e64 v220, v240, v116, s[100:101]
	v_cndmask_b32_e64 v217, v121, v241, s[100:101]
	v_cndmask_b32_e64 v221, v241, v117, s[100:101]
	v_lshl_add_u64 v[226:227], v[146:147], 0, v[242:243]
	global_store_dwordx4 v[226:227], v[214:217], off offset:-3584
	global_store_dwordx4 v[226:227], v[218:221], off offset:512
	v_pk_mul_f32 v[124:125], v[58:59], v[114:115]
	v_pk_mul_f32 v[120:121], v[64:65], v[120:121]
	v_pk_mul_f32 v[118:119], v[62:63], v[118:119]
	s_waitcnt lgkmcnt(0)
	v_add_f32_e32 v114, v126, v127
	ds_bpermute_b32 v115, v195, v114
	v_pk_mul_f32 v[122:123], v[60:61], v[116:117]
	v_cvt_pk_bf16_f32 v116, v118, v119
	v_cvt_pk_bf16_f32 v117, v120, v121
	v_cvt_pk_bf16_f32 v118, v124, v125
	v_cvt_pk_bf16_f32 v119, v122, v123
	global_store_dwordx4 v[144:145], v[116:119], off offset:256
	s_and_saveexec_b64 s[34:35], s[38:39]
	s_cbranch_execz .LBB0_1229
;     __device__ __forceinline__ void operator()(const f32x4 (&acc)[2][2][4][2], const pg8::Unit& u, int wr, int wc, int fr, int fq) const {
;     ...
;                 ss += __shfl_xor(ss, 16); ss += __shfl_xor(ss, 32);
;                 if (fq == 0) stat[(size_t)R * 16 + u.pn * 4 + wc] = ss;
	v_lshlrev_b64 v[116:117], 6, v[130:131]
	v_lshl_add_u64 v[116:117], s[62:63], 0, v[116:117]
	v_lshl_add_u64 v[116:117], s[24:25], 2, v[116:117]
	s_lshl_b32 s0, s56, 2
	v_lshl_add_u64 v[116:117], v[116:117], 0, s[0:1]
	s_waitcnt lgkmcnt(0)
	v_add_f32_e32 v114, v114, v115
	global_store_dword v[116:117], v114, off

; __device__ __forceinline__ unsigned pk2(float lo, float hi) { return pg8::cvt_pk_bf16(lo, hi); }
;     __device__ __forceinline__ void operator()(const f32x4 (&acc)[2][2][4][2], const pg8::Unit& u, int wr, int wc, int fr, int fq) const {
;     ...
;             for (int m = 0; m < 4; ++m) {
;                 const int R = rowbase + u.pm * 256 + ai * 128 + wr * 64 + m * 16 + fr;
;                 const float* src = islat ? rin_l + (size_t)R * DM : rin_c + (size_t)(R - TL) * DM;
;                 float* dst = islat ? rout_l + (size_t)R * DM : rout_c + (size_t)(R - TL) * DM;
;                 float ss = 0.f;
; #pragma unroll
;                 for (int bj = 0; bj < 2; ++bj) { const int c = u.pn * 256 + bj * 128 + wc * 32 + 8 * fq;
;                     const f32x4 xa = *(const f32x4*)(src + c) + gv[bj][0] * acc[ai][bj][m][0];
;                     const f32x4 xb = *(const f32x4*)(src + c + 4) + gv[bj][1] * acc[ai][bj][m][1];
;                     *(f32x4*)(dst + c) = xa; *(f32x4*)(dst + c + 4) = xb;
;                     ss += (xa[0] * xa[0] + xa[1] * xa[1]) + (xa[2] * xa[2] + xa[3] * xa[3]) + (xb[0] * xb[0] + xb[1] * xb[1]) + (xb[2] * xb[2] + xb[3] * xb[3]);
;                     const f32x4 ya = xa * sv[bj][0], yb = xb * sv[bj][1];
;                     u32x4 w; w.x = pk2(ya[0], ya[1]); w.y = pk2(ya[2], ya[3]); w.z = pk2(yb[0], yb[1]); w.w = pk2(yb[2], yb[3]);
;                     *(u32x4*)(Hn + (size_t)R * DM + c) = w; }
;                 ss += __shfl_xor(ss, 16); ss += __shfl_xor(ss, 32);
;                 if (fq == 0) stat[(size_t)R * 16 + u.pn * 4 + wc] = ss;
;             }
.LBB0_1233:
	v_cndmask_b32_e64 v118, v118, v114, s[42:43]
	v_ashrrev_i32_e32 v119, 31, v118
	v_lshlrev_b64 v[118:119], 12, v[118:119]
	v_lshl_add_u64 v[118:119], s[68:69], 0, v[118:119]
	v_lshl_add_u64 v[126:127], v[118:119], 0, v[188:189]
	v_lshl_add_u64 v[226:227], v[126:127], 0, v[242:243]
	global_load_dwordx4 v[214:217], v[226:227], off offset:-4096
	global_load_dwordx4 v[218:221], v[226:227], off
	v_lshlrev_b64 v[128:129], 11, v[114:115]
	v_lshl_add_u64 v[130:131], v[116:117], 0, v[188:189]
	v_lshl_add_u64 v[116:117], s[60:61], 0, v[128:129]
	v_lshl_add_u64 v[128:129], v[186:187], 1, v[116:117]
	s_waitcnt vmcnt(0)
	v_cndmask_b32_e64 v222, v218, v214, s[100:101]
	v_cndmask_b32_e64 v223, v219, v215, s[100:101]
	v_cndmask_b32_e64 v224, v220, v216, s[100:101]
	v_cndmask_b32_e64 v225, v221, v217, s[100:101]
	v_mov_b32_dpp v238, v222 quad_perm:[1,0,3,2] row_mask:0xf bank_mask:0xf
	v_mov_b32_dpp v239, v223 quad_perm:[1,0,3,2] row_mask:0xf bank_mask:0xf
	v_mov_b32_dpp v240, v224 quad_perm:[1,0,3,2] row_mask:0xf bank_mask:0xf
	v_mov_b32_dpp v241, v225 quad_perm:[1,0,3,2] row_mask:0xf bank_mask:0xf
	v_cndmask_b32_e64 v118, v214, v238, s[100:101]
	v_cndmask_b32_e64 v122, v238, v218, s[100:101]
	v_cndmask_b32_e64 v119, v215, v239, s[100:101]
	v_cndmask_b32_e64 v123, v239, v219, s[100:101]
	v_cndmask_b32_e64 v120, v216, v240, s[100:101]
	v_cndmask_b32_e64 v124, v240, v220, s[100:101]
	v_cndmask_b32_e64 v121, v217, v241, s[100:101]
	v_cndmask_b32_e64 v125, v241, v221, s[100:101]
	v_pk_fma_f32 v[112:113], v[112:113], v[96:97], v[120:121]
	v_pk_fma_f32 v[110:111], v[110:111], v[94:95], v[118:119]
	s_waitcnt vmcnt(0)
	v_pk_fma_f32 v[108:109], v[108:109], v[88:89], v[124:125]
	v_pk_fma_f32 v[106:107], v[106:107], v[86:87], v[122:123]
	v_pk_mul_f32 v[118:119], v[92:93], v[112:113]
	v_pk_mul_f32 v[116:117], v[90:91], v[110:111]
	v_pk_mul_f32 v[120:121], v[84:85], v[108:109]
	v_pk_mul_f32 v[122:123], v[82:83], v[106:107]
	v_cvt_pk_bf16_f32 v116, v116, v117
	v_cvt_pk_bf16_f32 v117, v118, v119
	v_cvt_pk_bf16_f32 v118, v122, v123
	v_cvt_pk_bf16_f32 v119, v120, v121
	v_cndmask_b32_e64 v222, v106, v110, s[100:101]
	v_cndmask_b32_e64 v223, v107, v111, s[100:101]
	v_cndmask_b32_e64 v224, v108, v112, s[100:101]
	v_cndmask_b32_e64 v225, v109, v113, s[100:101]
	v_mov_b32_dpp v238, v222 quad_perm:[1,0,3,2] row_mask:0xf bank_mask:0xf
	v_mov_b32_dpp v239, v223 quad_perm:[1,0,3,2] row_mask:0xf bank_mask:0xf
	v_mov_b32_dpp v240, v224 quad_perm:[1,0,3,2] row_mask:0xf bank_mask:0xf
	v_mov_b32_dpp v241, v225 quad_perm:[1,0,3,2] row_mask:0xf bank_mask:0xf
	v_cndmask_b32_e64 v214, v110, v238, s[100:101]
	v_cndmask_b32_e64 v218, v238, v106, s[100:101]
	v_cndmask_b32_e64 v215, v111, v239, s[100:101]
	v_cndmask_b32_e64 v219, v239, v107, s[100:101]
	v_cndmask_b32_e64 v216, v112, v240, s[100:101]
	v_cndmask_b32_e64 v220, v240, v108, s[100:101]
	v_cndmask_b32_e64 v217, v113, v241, s[100:101]
	v_cndmask_b32_e64 v221, v241, v109, s[100:101]
	v_lshl_add_u64 v[226:227], v[130:131], 0, v[242:243]
	global_store_dwordx4 v[226:227], v[214:217], off offset:-4096
	global_store_dwordx4 v[226:227], v[218:221], off
	global_store_dwordx4 v[128:129], v[116:119], off
	v_lshl_add_u64 v[226:227], v[126:127], 0, v[242:243]
	global_load_dwordx4 v[214:217], v[226:227], off offset:-3584
	global_load_dwordx4 v[218:221], v[226:227], off offset:512
	s_nop 0
	v_mul_f32_e32 v111, v111, v111
	v_mul_f32_e32 v113, v113, v113
	v_mul_f32_e32 v107, v107, v107
	v_fmac_f32_e32 v111, v110, v110
	v_fmac_f32_e32 v113, v112, v112
	v_mul_f32_e32 v109, v109, v109
	v_fmac_f32_e32 v107, v106, v106
	v_add_f32_e32 v106, v111, v113
	v_fmac_f32_e32 v109, v108, v108
	v_add_f32_e32 v106, v106, v107
	v_add_f32_e32 v106, v109, v106
	s_waitcnt vmcnt(0)
	v_cndmask_b32_e64 v222, v218, v214, s[100:101]
	v_cndmask_b32_e64 v223, v219, v215, s[100:101]
	v_cndmask_b32_e64 v224, v220, v216, s[100:101]
	v_cndmask_b32_e64 v225, v221, v217, s[100:101]
	v_mov_b32_dpp v238, v222 quad_perm:[1,0,3,2] row_mask:0xf bank_mask:0xf
	v_mov_b32_dpp v239, v223 quad_perm:[1,0,3,2] row_mask:0xf bank_mask:0xf
	v_mov_b32_dpp v240, v224 quad_perm:[1,0,3,2] row_mask:0xf bank_mask:0xf
	v_mov_b32_dpp v241, v225 quad_perm:[1,0,3,2] row_mask:0xf bank_mask:0xf
	v_cndmask_b32_e64 v116, v214, v238, s[100:101]
	v_cndmask_b32_e64 v120, v238, v218, s[100:101]
	v_cndmask_b32_e64 v117, v215, v239, s[100:101]
	v_cndmask_b32_e64 v121, v239, v219, s[100:101]
	v_cndmask_b32_e64 v118, v216, v240, s[100:101]
	v_cndmask_b32_e64 v122, v240, v220, s[100:101]
	v_cndmask_b32_e64 v119, v217, v241, s[100:101]
	v_cndmask_b32_e64 v123, v241, v221, s[100:101]
	v_pk_fma_f32 v[104:105], v[104:105], v[80:81], v[118:119]
	v_pk_fma_f32 v[102:103], v[102:103], v[78:79], v[116:117]
	s_waitcnt vmcnt(0)
	v_pk_fma_f32 v[98:99], v[98:99], v[74:75], v[120:121]
	v_mul_f32_e32 v107, v103, v103
	v_mul_f32_e32 v108, v105, v105
	v_pk_fma_f32 v[100:101], v[100:101], v[76:77], v[122:123]
	v_mul_f32_e32 v109, v99, v99
	v_fmac_f32_e32 v107, v102, v102
	v_fmac_f32_e32 v108, v104, v104
	v_mul_f32_e32 v110, v101, v101
	v_fmac_f32_e32 v109, v98, v98
	v_add_f32_e32 v107, v107, v108
	v_fmac_f32_e32 v110, v100, v100
	v_add_f32_e32 v107, v107, v109
	v_add_f32_e32 v107, v110, v107
	v_add_f32_e32 v110, v106, v107
	ds_bpermute_b32 v111, v200, v110
	v_cndmask_b32_e64 v222, v98, v102, s[100:101]
	v_cndmask_b32_e64 v223, v99, v103, s[100:101]
	v_cndmask_b32_e64 v224, v100, v104, s[100:101]
	v_cndmask_b32_e64 v225, v101, v105, s[100:101]
	v_mov_b32_dpp v238, v222 quad_perm:[1,0,3,2] row_mask:0xf bank_mask:0xf
	v_mov_b32_dpp v239, v223 quad_perm:[1,0,3,2] row_mask:0xf bank_mask:0xf
	v_mov_b32_dpp v240, v224 quad_perm:[1,0,3,2] row_mask:0xf bank_mask:0xf
	v_mov_b32_dpp v241, v225 quad_perm:[1,0,3,2] row_mask:0xf bank_mask:0xf
	v_cndmask_b32_e64 v214, v102, v238, s[100:101]
	v_cndmask_b32_e64 v218, v238, v98, s[100:101]
	v_cndmask_b32_e64 v215, v103, v239, s[100:101]
	v_cndmask_b32_e64 v219, v239, v99, s[100:101]
	v_cndmask_b32_e64 v216, v104, v240, s[100:101]
	v_cndmask_b32_e64 v220, v240, v100, s[100:101]
	v_cndmask_b32_e64 v217, v105, v241, s[100:101]
	v_cndmask_b32_e64 v221, v241, v101, s[100:101]
	v_lshl_add_u64 v[226:227], v[130:131], 0, v[242:243]
	global_store_dwordx4 v[226:227], v[214:217], off offset:-3584
	global_store_dwordx4 v[226:227], v[218:221], off offset:512
	v_pk_mul_f32 v[108:109], v[58:59], v[98:99]
	v_pk_mul_f32 v[104:105], v[64:65], v[104:105]
	v_pk_mul_f32 v[102:103], v[62:63], v[102:103]
	s_waitcnt lgkmcnt(0)
	v_add_f32_e32 v98, v110, v111
	ds_bpermute_b32 v99, v195, v98
	v_pk_mul_f32 v[106:107], v[60:61], v[100:101]
	v_cvt_pk_bf16_f32 v100, v102, v103
	v_cvt_pk_bf16_f32 v101, v104, v105
	v_cvt_pk_bf16_f32 v102, v108, v109
	v_cvt_pk_bf16_f32 v103, v106, v107
	global_store_dwordx4 v[128:129], v[100:103], off offset:256
	s_and_saveexec_b64 s[34:35], s[38:39]
	s_cbranch_execz .LBB0_1235
;     __device__ __forceinline__ void operator()(const f32x4 (&acc)[2][2][4][2], const pg8::Unit& u, int wr, int wc, int fr, int fq) const {
;     ...
;                 ss += __shfl_xor(ss, 16); ss += __shfl_xor(ss, 32);
;                 if (fq == 0) stat[(size_t)R * 16 + u.pn * 4 + wc] = ss;
	v_lshlrev_b64 v[100:101], 6, v[114:115]
	v_lshl_add_u64 v[100:101], s[62:63], 0, v[100:101]
	v_lshl_add_u64 v[100:101], s[24:25], 2, v[100:101]
	s_lshl_b32 s0, s56, 2
	v_lshl_add_u64 v[100:101], v[100:101], 0, s[0:1]
	s_waitcnt lgkmcnt(0)
	v_add_f32_e32 v98, v98, v99
	global_store_dword v[100:101], v98, off

; __device__ __forceinline__ unsigned pk2(float lo, float hi) { return pg8::cvt_pk_bf16(lo, hi); }
;     __device__ __forceinline__ void operator()(const f32x4 (&acc)[2][2][4][2], const pg8::Unit& u, int wr, int wc, int fr, int fq) const {
;     ...
;             for (int m = 0; m < 4; ++m) {
;                 const int R = rowbase + u.pm * 256 + ai * 128 + wr * 64 + m * 16 + fr;
;                 const float* src = islat ? rin_l + (size_t)R * DM : rin_c + (size_t)(R - TL) * DM;
;                 float* dst = islat ? rout_l + (size_t)R * DM : rout_c + (size_t)(R - TL) * DM;
;                 float ss = 0.f;
; #pragma unroll
;                 for (int bj = 0; bj < 2; ++bj) { const int c = u.pn * 256 + bj * 128 + wc * 32 + 8 * fq;
;                     const f32x4 xa = *(const f32x4*)(src + c) + gv[bj][0] * acc[ai][bj][m][0];
;                     const f32x4 xb = *(const f32x4*)(src + c + 4) + gv[bj][1] * acc[ai][bj][m][1];
;                     *(f32x4*)(dst + c) = xa; *(f32x4*)(dst + c + 4) = xb;
;                     ss += (xa[0] * xa[0] + xa[1] * xa[1]) + (xa[2] * xa[2] + xa[3] * xa[3]) + (xb[0] * xb[0] + xb[1] * xb[1]) + (xb[2] * xb[2] + xb[3] * xb[3]);
;                     const f32x4 ya = xa * sv[bj][0], yb = xb * sv[bj][1];
;                     u32x4 w; w.x = pk2(ya[0], ya[1]); w.y = pk2(ya[2], ya[3]); w.z = pk2(yb[0], yb[1]); w.w = pk2(yb[2], yb[3]);
;                     *(u32x4*)(Hn + (size_t)R * DM + c) = w; }
;                 ss += __shfl_xor(ss, 16); ss += __shfl_xor(ss, 32);
;                 if (fq == 0) stat[(size_t)R * 16 + u.pn * 4 + wc] = ss;
;             }
.LBB0_1239:
	v_cndmask_b32_e64 v102, v102, v98, s[42:43]
	v_ashrrev_i32_e32 v103, 31, v102
	v_lshlrev_b64 v[102:103], 12, v[102:103]
	v_lshl_add_u64 v[102:103], s[68:69], 0, v[102:103]
	v_lshl_add_u64 v[110:111], v[102:103], 0, v[188:189]
	v_lshl_add_u64 v[226:227], v[110:111], 0, v[242:243]
	global_load_dwordx4 v[214:217], v[226:227], off offset:-4096
	global_load_dwordx4 v[218:221], v[226:227], off
	v_lshlrev_b64 v[112:113], 11, v[98:99]
	v_lshl_add_u64 v[114:115], v[100:101], 0, v[188:189]
	v_lshl_add_u64 v[100:101], s[60:61], 0, v[112:113]
	v_lshl_add_u64 v[112:113], v[186:187], 1, v[100:101]
	s_waitcnt vmcnt(0)
	v_cndmask_b32_e64 v222, v218, v214, s[100:101]
	v_cndmask_b32_e64 v223, v219, v215, s[100:101]
	v_cndmask_b32_e64 v224, v220, v216, s[100:101]
	v_cndmask_b32_e64 v225, v221, v217, s[100:101]
	v_mov_b32_dpp v238, v222 quad_perm:[1,0,3,2] row_mask:0xf bank_mask:0xf
	v_mov_b32_dpp v239, v223 quad_perm:[1,0,3,2] row_mask:0xf bank_mask:0xf
	v_mov_b32_dpp v240, v224 quad_perm:[1,0,3,2] row_mask:0xf bank_mask:0xf
	v_mov_b32_dpp v241, v225 quad_perm:[1,0,3,2] row_mask:0xf bank_mask:0xf
	v_cndmask_b32_e64 v102, v214, v238, s[100:101]
	v_cndmask_b32_e64 v106, v238, v218, s[100:101]
	v_cndmask_b32_e64 v103, v215, v239, s[100:101]
	v_cndmask_b32_e64 v107, v239, v219, s[100:101]
	v_cndmask_b32_e64 v104, v216, v240, s[100:101]
	v_cndmask_b32_e64 v108, v240, v220, s[100:101]
	v_cndmask_b32_e64 v105, v217, v241, s[100:101]
	v_cndmask_b32_e64 v109, v241, v221, s[100:101]
	v_pk_fma_f32 v[72:73], v[72:73], v[96:97], v[104:105]
	v_pk_fma_f32 v[70:71], v[70:71], v[94:95], v[102:103]
	s_waitcnt vmcnt(0)
	v_pk_fma_f32 v[68:69], v[68:69], v[88:89], v[108:109]
	v_pk_fma_f32 v[66:67], v[66:67], v[86:87], v[106:107]
	v_pk_mul_f32 v[102:103], v[92:93], v[72:73]
	v_pk_mul_f32 v[100:101], v[90:91], v[70:71]
	v_pk_mul_f32 v[104:105], v[84:85], v[68:69]
	v_pk_mul_f32 v[106:107], v[82:83], v[66:67]
	v_cvt_pk_bf16_f32 v100, v100, v101
	v_cvt_pk_bf16_f32 v101, v102, v103
	v_cvt_pk_bf16_f32 v102, v106, v107
	v_cvt_pk_bf16_f32 v103, v104, v105
	v_cndmask_b32_e64 v222, v66, v70, s[100:101]
	v_cndmask_b32_e64 v223, v67, v71, s[100:101]
	v_cndmask_b32_e64 v224, v68, v72, s[100:101]
	v_cndmask_b32_e64 v225, v69, v73, s[100:101]
	v_mov_b32_dpp v238, v222 quad_perm:[1,0,3,2] row_mask:0xf bank_mask:0xf
	v_mov_b32_dpp v239, v223 quad_perm:[1,0,3,2] row_mask:0xf bank_mask:0xf
	v_mov_b32_dpp v240, v224 quad_perm:[1,0,3,2] row_mask:0xf bank_mask:0xf
	v_mov_b32_dpp v241, v225 quad_perm:[1,0,3,2] row_mask:0xf bank_mask:0xf
	v_cndmask_b32_e64 v214, v70, v238, s[100:101]
	v_cndmask_b32_e64 v218, v238, v66, s[100:101]
	v_cndmask_b32_e64 v215, v71, v239, s[100:101]
	v_cndmask_b32_e64 v219, v239, v67, s[100:101]
	v_cndmask_b32_e64 v216, v72, v240, s[100:101]
	v_cndmask_b32_e64 v220, v240, v68, s[100:101]
	v_cndmask_b32_e64 v217, v73, v241, s[100:101]
	v_cndmask_b32_e64 v221, v241, v69, s[100:101]
	v_lshl_add_u64 v[226:227], v[114:115], 0, v[242:243]
	global_store_dwordx4 v[226:227], v[214:217], off offset:-4096
	global_store_dwordx4 v[226:227], v[218:221], off
	global_store_dwordx4 v[112:113], v[100:103], off
	v_lshl_add_u64 v[226:227], v[110:111], 0, v[242:243]
	global_load_dwordx4 v[214:217], v[226:227], off offset:-3584
	global_load_dwordx4 v[218:221], v[226:227], off offset:512
	s_nop 0
	v_mul_f32_e32 v71, v71, v71
	v_mul_f32_e32 v73, v73, v73
	v_mul_f32_e32 v67, v67, v67
	v_fmac_f32_e32 v71, v70, v70
	v_fmac_f32_e32 v73, v72, v72
	v_mul_f32_e32 v69, v69, v69
	v_fmac_f32_e32 v67, v66, v66
	v_add_f32_e32 v66, v71, v73
	v_fmac_f32_e32 v69, v68, v68
	v_add_f32_e32 v66, v66, v67
	v_add_f32_e32 v66, v69, v66
	s_waitcnt vmcnt(0)
	v_cndmask_b32_e64 v222, v218, v214, s[100:101]
	v_cndmask_b32_e64 v223, v219, v215, s[100:101]
	v_cndmask_b32_e64 v224, v220, v216, s[100:101]
	v_cndmask_b32_e64 v225, v221, v217, s[100:101]
	v_mov_b32_dpp v238, v222 quad_perm:[1,0,3,2] row_mask:0xf bank_mask:0xf
	v_mov_b32_dpp v239, v223 quad_perm:[1,0,3,2] row_mask:0xf bank_mask:0xf
	v_mov_b32_dpp v240, v224 quad_perm:[1,0,3,2] row_mask:0xf bank_mask:0xf
	v_mov_b32_dpp v241, v225 quad_perm:[1,0,3,2] row_mask:0xf bank_mask:0xf
	v_cndmask_b32_e64 v100, v214, v238, s[100:101]
	v_cndmask_b32_e64 v104, v238, v218, s[100:101]
	v_cndmask_b32_e64 v101, v215, v239, s[100:101]
	v_cndmask_b32_e64 v105, v239, v219, s[100:101]
	v_cndmask_b32_e64 v102, v216, v240, s[100:101]
	v_cndmask_b32_e64 v106, v240, v220, s[100:101]
	v_cndmask_b32_e64 v103, v217, v241, s[100:101]
	v_cndmask_b32_e64 v107, v241, v221, s[100:101]
	v_pk_fma_f32 v[56:57], v[56:57], v[80:81], v[102:103]
	v_pk_fma_f32 v[54:55], v[54:55], v[78:79], v[100:101]
	s_waitcnt vmcnt(0)
	v_pk_fma_f32 v[50:51], v[50:51], v[74:75], v[104:105]
	v_mul_f32_e32 v67, v55, v55
	v_mul_f32_e32 v68, v57, v57
	v_pk_fma_f32 v[52:53], v[52:53], v[76:77], v[106:107]
	v_mul_f32_e32 v69, v51, v51
	v_fmac_f32_e32 v67, v54, v54
	v_fmac_f32_e32 v68, v56, v56
	v_mul_f32_e32 v70, v53, v53
	v_fmac_f32_e32 v69, v50, v50
	v_add_f32_e32 v67, v67, v68
	v_fmac_f32_e32 v70, v52, v52
	v_add_f32_e32 v67, v67, v69
	v_add_f32_e32 v67, v70, v67
	v_add_f32_e32 v70, v66, v67
	ds_bpermute_b32 v71, v200, v70
	v_cndmask_b32_e64 v222, v50, v54, s[100:101]
	v_cndmask_b32_e64 v223, v51, v55, s[100:101]
	v_cndmask_b32_e64 v224, v52, v56, s[100:101]
	v_cndmask_b32_e64 v225, v53, v57, s[100:101]
	v_mov_b32_dpp v238, v222 quad_perm:[1,0,3,2] row_mask:0xf bank_mask:0xf
	v_mov_b32_dpp v239, v223 quad_perm:[1,0,3,2] row_mask:0xf bank_mask:0xf
	v_mov_b32_dpp v240, v224 quad_perm:[1,0,3,2] row_mask:0xf bank_mask:0xf
	v_mov_b32_dpp v241, v225 quad_perm:[1,0,3,2] row_mask:0xf bank_mask:0xf
	v_cndmask_b32_e64 v214, v54, v238, s[100:101]
	v_cndmask_b32_e64 v218, v238, v50, s[100:101]
	v_cndmask_b32_e64 v215, v55, v239, s[100:101]
	v_cndmask_b32_e64 v219, v239, v51, s[100:101]
	v_cndmask_b32_e64 v216, v56, v240, s[100:101]
	v_cndmask_b32_e64 v220, v240, v52, s[100:101]
	v_cndmask_b32_e64 v217, v57, v241, s[100:101]
	v_cndmask_b32_e64 v221, v241, v53, s[100:101]
	v_lshl_add_u64 v[226:227], v[114:115], 0, v[242:243]
	global_store_dwordx4 v[226:227], v[214:217], off offset:-3584
	global_store_dwordx4 v[226:227], v[218:221], off offset:512
	v_pk_mul_f32 v[68:69], v[58:59], v[50:51]
	v_pk_mul_f32 v[56:57], v[64:65], v[56:57]
	v_pk_mul_f32 v[54:55], v[62:63], v[54:55]
	s_waitcnt lgkmcnt(0)
	v_add_f32_e32 v50, v70, v71
	ds_bpermute_b32 v51, v195, v50
	v_pk_mul_f32 v[66:67], v[60:61], v[52:53]
	v_cvt_pk_bf16_f32 v52, v54, v55
	v_cvt_pk_bf16_f32 v53, v56, v57
	v_cvt_pk_bf16_f32 v54, v68, v69
	v_cvt_pk_bf16_f32 v55, v66, v67
	global_store_dwordx4 v[112:113], v[52:55], off offset:256
	s_and_saveexec_b64 s[34:35], s[38:39]
	s_cbranch_execz .LBB0_1241
	v_lshlrev_b64 v[52:53], 6, v[98:99]
	v_lshl_add_u64 v[52:53], s[62:63], 0, v[52:53]
	v_lshl_add_u64 v[52:53], s[24:25], 2, v[52:53]
	s_lshl_b32 s0, s56, 2
	v_lshl_add_u64 v[52:53], v[52:53], 0, s[0:1]
	s_waitcnt lgkmcnt(0)
	v_add_f32_e32 v50, v50, v51
	global_store_dword v[52:53], v50, off

; __device__ __forceinline__ unsigned pk2(float lo, float hi) { return pg8::cvt_pk_bf16(lo, hi); }
;     __device__ __forceinline__ void operator()(const f32x4 (&acc)[2][2][4][2], const pg8::Unit& u, int wr, int wc, int fr, int fq) const {
;     ...
;             for (int m = 0; m < 4; ++m) {
;                 const int R = rowbase + u.pm * 256 + ai * 128 + wr * 64 + m * 16 + fr;
;                 const float* src = islat ? rin_l + (size_t)R * DM : rin_c + (size_t)(R - TL) * DM;
;                 float* dst = islat ? rout_l + (size_t)R * DM : rout_c + (size_t)(R - TL) * DM;
;                 float ss = 0.f;
; #pragma unroll
;                 for (int bj = 0; bj < 2; ++bj) { const int c = u.pn * 256 + bj * 128 + wc * 32 + 8 * fq;
;                     const f32x4 xa = *(const f32x4*)(src + c) + gv[bj][0] * acc[ai][bj][m][0];
;                     const f32x4 xb = *(const f32x4*)(src + c + 4) + gv[bj][1] * acc[ai][bj][m][1];
;                     *(f32x4*)(dst + c) = xa; *(f32x4*)(dst + c + 4) = xb;
;                     ss += (xa[0] * xa[0] + xa[1] * xa[1]) + (xa[2] * xa[2] + xa[3] * xa[3]) + (xb[0] * xb[0] + xb[1] * xb[1]) + (xb[2] * xb[2] + xb[3] * xb[3]);
;                     const f32x4 ya = xa * sv[bj][0], yb = xb * sv[bj][1];
;                     u32x4 w; w.x = pk2(ya[0], ya[1]); w.y = pk2(ya[2], ya[3]); w.z = pk2(yb[0], yb[1]); w.w = pk2(yb[2], yb[3]);
;                     *(u32x4*)(Hn + (size_t)R * DM + c) = w; }
;                 ss += __shfl_xor(ss, 16); ss += __shfl_xor(ss, 32);
;                 if (fq == 0) stat[(size_t)R * 16 + u.pn * 4 + wc] = ss;
;             }
.LBB0_1245:
	v_cndmask_b32_e64 v54, v54, v50, s[42:43]
	v_ashrrev_i32_e32 v55, 31, v54
	v_lshlrev_b64 v[54:55], 12, v[54:55]
	v_lshl_add_u64 v[54:55], s[68:69], 0, v[54:55]
	v_lshl_add_u64 v[70:71], v[54:55], 0, v[188:189]
	v_lshl_add_u64 v[226:227], v[70:71], 0, v[242:243]
	global_load_dwordx4 v[214:217], v[226:227], off offset:-4096
	global_load_dwordx4 v[218:221], v[226:227], off
	v_lshlrev_b64 v[72:73], 11, v[50:51]
	v_lshl_add_u64 v[98:99], v[52:53], 0, v[188:189]
	v_lshl_add_u64 v[52:53], s[60:61], 0, v[72:73]
	v_lshl_add_u64 v[72:73], v[186:187], 1, v[52:53]
	s_waitcnt vmcnt(0)
	v_cndmask_b32_e64 v222, v218, v214, s[100:101]
	v_cndmask_b32_e64 v223, v219, v215, s[100:101]
	v_cndmask_b32_e64 v224, v220, v216, s[100:101]
	v_cndmask_b32_e64 v225, v221, v217, s[100:101]
	v_mov_b32_dpp v238, v222 quad_perm:[1,0,3,2] row_mask:0xf bank_mask:0xf
	v_mov_b32_dpp v239, v223 quad_perm:[1,0,3,2] row_mask:0xf bank_mask:0xf
	v_mov_b32_dpp v240, v224 quad_perm:[1,0,3,2] row_mask:0xf bank_mask:0xf
	v_mov_b32_dpp v241, v225 quad_perm:[1,0,3,2] row_mask:0xf bank_mask:0xf
	v_cndmask_b32_e64 v54, v214, v238, s[100:101]
	v_cndmask_b32_e64 v66, v238, v218, s[100:101]
	v_cndmask_b32_e64 v55, v215, v239, s[100:101]
	v_cndmask_b32_e64 v67, v239, v219, s[100:101]
	v_cndmask_b32_e64 v56, v216, v240, s[100:101]
	v_cndmask_b32_e64 v68, v240, v220, s[100:101]
	v_cndmask_b32_e64 v57, v217, v241, s[100:101]
	v_cndmask_b32_e64 v69, v241, v221, s[100:101]
	v_pk_fma_f32 v[48:49], v[48:49], v[96:97], v[56:57]
	v_pk_fma_f32 v[46:47], v[46:47], v[94:95], v[54:55]
	s_waitcnt vmcnt(0)
	v_pk_fma_f32 v[44:45], v[44:45], v[88:89], v[68:69]
	v_pk_fma_f32 v[42:43], v[42:43], v[86:87], v[66:67]
	v_pk_mul_f32 v[54:55], v[92:93], v[48:49]
	v_pk_mul_f32 v[52:53], v[90:91], v[46:47]
	v_pk_mul_f32 v[56:57], v[84:85], v[44:45]
	v_pk_mul_f32 v[66:67], v[82:83], v[42:43]
	v_cvt_pk_bf16_f32 v52, v52, v53
	v_cvt_pk_bf16_f32 v53, v54, v55
	v_cvt_pk_bf16_f32 v54, v66, v67
	v_cvt_pk_bf16_f32 v55, v56, v57
	v_cndmask_b32_e64 v222, v42, v46, s[100:101]
	v_cndmask_b32_e64 v223, v43, v47, s[100:101]
	v_cndmask_b32_e64 v224, v44, v48, s[100:101]
	v_cndmask_b32_e64 v225, v45, v49, s[100:101]
	v_mov_b32_dpp v238, v222 quad_perm:[1,0,3,2] row_mask:0xf bank_mask:0xf
	v_mov_b32_dpp v239, v223 quad_perm:[1,0,3,2] row_mask:0xf bank_mask:0xf
	v_mov_b32_dpp v240, v224 quad_perm:[1,0,3,2] row_mask:0xf bank_mask:0xf
	v_mov_b32_dpp v241, v225 quad_perm:[1,0,3,2] row_mask:0xf bank_mask:0xf
	v_cndmask_b32_e64 v214, v46, v238, s[100:101]
	v_cndmask_b32_e64 v218, v238, v42, s[100:101]
	v_cndmask_b32_e64 v215, v47, v239, s[100:101]
	v_cndmask_b32_e64 v219, v239, v43, s[100:101]
	v_cndmask_b32_e64 v216, v48, v240, s[100:101]
	v_cndmask_b32_e64 v220, v240, v44, s[100:101]
	v_cndmask_b32_e64 v217, v49, v241, s[100:101]
	v_cndmask_b32_e64 v221, v241, v45, s[100:101]
	v_lshl_add_u64 v[226:227], v[98:99], 0, v[242:243]
	global_store_dwordx4 v[226:227], v[214:217], off offset:-4096
	global_store_dwordx4 v[226:227], v[218:221], off
	global_store_dwordx4 v[72:73], v[52:55], off
	v_lshl_add_u64 v[226:227], v[70:71], 0, v[242:243]
	global_load_dwordx4 v[214:217], v[226:227], off offset:-3584
	global_load_dwordx4 v[218:221], v[226:227], off offset:512
	s_nop 0
	v_mul_f32_e32 v47, v47, v47
	v_mul_f32_e32 v49, v49, v49
	v_mul_f32_e32 v43, v43, v43
	v_fmac_f32_e32 v47, v46, v46
	v_fmac_f32_e32 v49, v48, v48
	v_mul_f32_e32 v45, v45, v45
	v_fmac_f32_e32 v43, v42, v42
	v_add_f32_e32 v42, v47, v49
	v_fmac_f32_e32 v45, v44, v44
	v_add_f32_e32 v42, v42, v43
	v_add_f32_e32 v42, v45, v42
	s_waitcnt vmcnt(0)
	v_cndmask_b32_e64 v222, v218, v214, s[100:101]
	v_cndmask_b32_e64 v223, v219, v215, s[100:101]
	v_cndmask_b32_e64 v224, v220, v216, s[100:101]
	v_cndmask_b32_e64 v225, v221, v217, s[100:101]
	v_mov_b32_dpp v238, v222 quad_perm:[1,0,3,2] row_mask:0xf bank_mask:0xf
	v_mov_b32_dpp v239, v223 quad_perm:[1,0,3,2] row_mask:0xf bank_mask:0xf
	v_mov_b32_dpp v240, v224 quad_perm:[1,0,3,2] row_mask:0xf bank_mask:0xf
	v_mov_b32_dpp v241, v225 quad_perm:[1,0,3,2] row_mask:0xf bank_mask:0xf
	v_cndmask_b32_e64 v52, v214, v238, s[100:101]
	v_cndmask_b32_e64 v66, v238, v218, s[100:101]
	v_cndmask_b32_e64 v53, v215, v239, s[100:101]
	v_cndmask_b32_e64 v67, v239, v219, s[100:101]
	v_cndmask_b32_e64 v54, v216, v240, s[100:101]
	v_cndmask_b32_e64 v68, v240, v220, s[100:101]
	v_cndmask_b32_e64 v55, v217, v241, s[100:101]
	v_cndmask_b32_e64 v69, v241, v221, s[100:101]
	v_pk_fma_f32 v[40:41], v[40:41], v[80:81], v[54:55]
	v_pk_fma_f32 v[38:39], v[38:39], v[78:79], v[52:53]
	s_waitcnt vmcnt(0)
	v_pk_fma_f32 v[34:35], v[34:35], v[74:75], v[66:67]
	v_mul_f32_e32 v43, v39, v39
	v_mul_f32_e32 v44, v41, v41
	v_pk_fma_f32 v[36:37], v[36:37], v[76:77], v[68:69]
	v_mul_f32_e32 v45, v35, v35
	v_fmac_f32_e32 v43, v38, v38
	v_fmac_f32_e32 v44, v40, v40
	v_mul_f32_e32 v46, v37, v37
	v_fmac_f32_e32 v45, v34, v34
	v_add_f32_e32 v43, v43, v44
	v_fmac_f32_e32 v46, v36, v36
	v_add_f32_e32 v43, v43, v45
	v_add_f32_e32 v43, v46, v43
	v_add_f32_e32 v46, v42, v43
	ds_bpermute_b32 v47, v200, v46
	v_cndmask_b32_e64 v222, v34, v38, s[100:101]
	v_cndmask_b32_e64 v223, v35, v39, s[100:101]
	v_cndmask_b32_e64 v224, v36, v40, s[100:101]
	v_cndmask_b32_e64 v225, v37, v41, s[100:101]
	v_mov_b32_dpp v238, v222 quad_perm:[1,0,3,2] row_mask:0xf bank_mask:0xf
	v_mov_b32_dpp v239, v223 quad_perm:[1,0,3,2] row_mask:0xf bank_mask:0xf
	v_mov_b32_dpp v240, v224 quad_perm:[1,0,3,2] row_mask:0xf bank_mask:0xf
	v_mov_b32_dpp v241, v225 quad_perm:[1,0,3,2] row_mask:0xf bank_mask:0xf
	v_cndmask_b32_e64 v214, v38, v238, s[100:101]
	v_cndmask_b32_e64 v218, v238, v34, s[100:101]
	v_cndmask_b32_e64 v215, v39, v239, s[100:101]
	v_cndmask_b32_e64 v219, v239, v35, s[100:101]
	v_cndmask_b32_e64 v216, v40, v240, s[100:101]
	v_cndmask_b32_e64 v220, v240, v36, s[100:101]
	v_cndmask_b32_e64 v217, v41, v241, s[100:101]
	v_cndmask_b32_e64 v221, v241, v37, s[100:101]
	v_lshl_add_u64 v[226:227], v[98:99], 0, v[242:243]
	global_store_dwordx4 v[226:227], v[214:217], off offset:-3584
	global_store_dwordx4 v[226:227], v[218:221], off offset:512
	v_pk_mul_f32 v[44:45], v[58:59], v[34:35]
	v_pk_mul_f32 v[40:41], v[64:65], v[40:41]
	v_pk_mul_f32 v[38:39], v[62:63], v[38:39]
	s_waitcnt lgkmcnt(0)
	v_add_f32_e32 v34, v46, v47
	ds_bpermute_b32 v35, v195, v34
	v_pk_mul_f32 v[42:43], v[60:61], v[36:37]
	v_cvt_pk_bf16_f32 v36, v38, v39
	v_cvt_pk_bf16_f32 v37, v40, v41
	v_cvt_pk_bf16_f32 v38, v44, v45
	v_cvt_pk_bf16_f32 v39, v42, v43
	global_store_dwordx4 v[72:73], v[36:39], off offset:256
	s_and_saveexec_b64 s[34:35], s[38:39]
	s_cbranch_execz .LBB0_1247
	v_lshlrev_b64 v[36:37], 6, v[50:51]
	v_lshl_add_u64 v[36:37], s[62:63], 0, v[36:37]
	v_lshl_add_u64 v[36:37], s[24:25], 2, v[36:37]
	s_lshl_b32 s0, s56, 2
	v_lshl_add_u64 v[36:37], v[36:37], 0, s[0:1]
	s_waitcnt lgkmcnt(0)
	v_add_f32_e32 v34, v34, v35
	global_store_dword v[36:37], v34, off

; __device__ __forceinline__ unsigned pk2(float lo, float hi) { return pg8::cvt_pk_bf16(lo, hi); }
;     __device__ __forceinline__ void operator()(const f32x4 (&acc)[2][2][4][2], const pg8::Unit& u, int wr, int wc, int fr, int fq) const {
;     ...
;             for (int m = 0; m < 4; ++m) {
;                 const int R = rowbase + u.pm * 256 + ai * 128 + wr * 64 + m * 16 + fr;
;                 const float* src = islat ? rin_l + (size_t)R * DM : rin_c + (size_t)(R - TL) * DM;
;                 float* dst = islat ? rout_l + (size_t)R * DM : rout_c + (size_t)(R - TL) * DM;
;                 float ss = 0.f;
; #pragma unroll
;                 for (int bj = 0; bj < 2; ++bj) { const int c = u.pn * 256 + bj * 128 + wc * 32 + 8 * fq;
;                     const f32x4 xa = *(const f32x4*)(src + c) + gv[bj][0] * acc[ai][bj][m][0];
;                     const f32x4 xb = *(const f32x4*)(src + c + 4) + gv[bj][1] * acc[ai][bj][m][1];
;                     *(f32x4*)(dst + c) = xa; *(f32x4*)(dst + c + 4) = xb;
;                     ss += (xa[0] * xa[0] + xa[1] * xa[1]) + (xa[2] * xa[2] + xa[3] * xa[3]) + (xb[0] * xb[0] + xb[1] * xb[1]) + (xb[2] * xb[2] + xb[3] * xb[3]);
;                     const f32x4 ya = xa * sv[bj][0], yb = xb * sv[bj][1];
;                     u32x4 w; w.x = pk2(ya[0], ya[1]); w.y = pk2(ya[2], ya[3]); w.z = pk2(yb[0], yb[1]); w.w = pk2(yb[2], yb[3]);
;                     *(u32x4*)(Hn + (size_t)R * DM + c) = w; }
;                 ss += __shfl_xor(ss, 16); ss += __shfl_xor(ss, 32);
;                 if (fq == 0) stat[(size_t)R * 16 + u.pn * 4 + wc] = ss;
;             }
.LBB0_1251:
	v_cndmask_b32_e64 v38, v38, v34, s[42:43]
	v_ashrrev_i32_e32 v39, 31, v38
	v_lshlrev_b64 v[38:39], 12, v[38:39]
	v_lshl_add_u64 v[38:39], s[68:69], 0, v[38:39]
	v_lshl_add_u64 v[46:47], v[38:39], 0, v[188:189]
	v_lshl_add_u64 v[226:227], v[46:47], 0, v[242:243]
	global_load_dwordx4 v[214:217], v[226:227], off offset:-4096
	global_load_dwordx4 v[218:221], v[226:227], off
	v_lshlrev_b64 v[48:49], 11, v[34:35]
	v_lshl_add_u64 v[50:51], v[36:37], 0, v[188:189]
	v_lshl_add_u64 v[36:37], s[60:61], 0, v[48:49]
	v_lshl_add_u64 v[48:49], v[186:187], 1, v[36:37]
	s_waitcnt vmcnt(0)
	v_cndmask_b32_e64 v222, v218, v214, s[100:101]
	v_cndmask_b32_e64 v223, v219, v215, s[100:101]
	v_cndmask_b32_e64 v224, v220, v216, s[100:101]
	v_cndmask_b32_e64 v225, v221, v217, s[100:101]
	v_mov_b32_dpp v238, v222 quad_perm:[1,0,3,2] row_mask:0xf bank_mask:0xf
	v_mov_b32_dpp v239, v223 quad_perm:[1,0,3,2] row_mask:0xf bank_mask:0xf
	v_mov_b32_dpp v240, v224 quad_perm:[1,0,3,2] row_mask:0xf bank_mask:0xf
	v_mov_b32_dpp v241, v225 quad_perm:[1,0,3,2] row_mask:0xf bank_mask:0xf
	v_cndmask_b32_e64 v38, v214, v238, s[100:101]
	v_cndmask_b32_e64 v42, v238, v218, s[100:101]
	v_cndmask_b32_e64 v39, v215, v239, s[100:101]
	v_cndmask_b32_e64 v43, v239, v219, s[100:101]
	v_cndmask_b32_e64 v40, v216, v240, s[100:101]
	v_cndmask_b32_e64 v44, v240, v220, s[100:101]
	v_cndmask_b32_e64 v41, v217, v241, s[100:101]
	v_cndmask_b32_e64 v45, v241, v221, s[100:101]
	v_pk_fma_f32 v[32:33], v[32:33], v[96:97], v[40:41]
	v_pk_fma_f32 v[30:31], v[30:31], v[94:95], v[38:39]
	s_waitcnt vmcnt(0)
	v_pk_fma_f32 v[28:29], v[28:29], v[88:89], v[44:45]
	v_pk_fma_f32 v[26:27], v[26:27], v[86:87], v[42:43]
	v_pk_mul_f32 v[38:39], v[92:93], v[32:33]
	v_pk_mul_f32 v[36:37], v[90:91], v[30:31]
	v_pk_mul_f32 v[40:41], v[84:85], v[28:29]
	v_pk_mul_f32 v[42:43], v[82:83], v[26:27]
	v_cvt_pk_bf16_f32 v36, v36, v37
	v_cvt_pk_bf16_f32 v37, v38, v39
	v_cvt_pk_bf16_f32 v38, v42, v43
	v_cvt_pk_bf16_f32 v39, v40, v41
	v_cndmask_b32_e64 v222, v26, v30, s[100:101]
	v_cndmask_b32_e64 v223, v27, v31, s[100:101]
	v_cndmask_b32_e64 v224, v28, v32, s[100:101]
	v_cndmask_b32_e64 v225, v29, v33, s[100:101]
	v_mov_b32_dpp v238, v222 quad_perm:[1,0,3,2] row_mask:0xf bank_mask:0xf
	v_mov_b32_dpp v239, v223 quad_perm:[1,0,3,2] row_mask:0xf bank_mask:0xf
	v_mov_b32_dpp v240, v224 quad_perm:[1,0,3,2] row_mask:0xf bank_mask:0xf
	v_mov_b32_dpp v241, v225 quad_perm:[1,0,3,2] row_mask:0xf bank_mask:0xf
	v_cndmask_b32_e64 v214, v30, v238, s[100:101]
	v_cndmask_b32_e64 v218, v238, v26, s[100:101]
	v_cndmask_b32_e64 v215, v31, v239, s[100:101]
	v_cndmask_b32_e64 v219, v239, v27, s[100:101]
	v_cndmask_b32_e64 v216, v32, v240, s[100:101]
	v_cndmask_b32_e64 v220, v240, v28, s[100:101]
	v_cndmask_b32_e64 v217, v33, v241, s[100:101]
	v_cndmask_b32_e64 v221, v241, v29, s[100:101]
	v_lshl_add_u64 v[226:227], v[50:51], 0, v[242:243]
	global_store_dwordx4 v[226:227], v[214:217], off offset:-4096
	global_store_dwordx4 v[226:227], v[218:221], off
	global_store_dwordx4 v[48:49], v[36:39], off
	v_lshl_add_u64 v[226:227], v[46:47], 0, v[242:243]
	global_load_dwordx4 v[214:217], v[226:227], off offset:-3584
	global_load_dwordx4 v[218:221], v[226:227], off offset:512
	s_nop 0
	v_mul_f32_e32 v31, v31, v31
	v_mul_f32_e32 v33, v33, v33
	v_mul_f32_e32 v27, v27, v27
	v_fmac_f32_e32 v31, v30, v30
	v_fmac_f32_e32 v33, v32, v32
	v_mul_f32_e32 v29, v29, v29
	v_fmac_f32_e32 v27, v26, v26
	v_add_f32_e32 v26, v31, v33
	v_fmac_f32_e32 v29, v28, v28
	v_add_f32_e32 v26, v26, v27
	v_add_f32_e32 v26, v29, v26
	s_waitcnt vmcnt(0)
	v_cndmask_b32_e64 v222, v218, v214, s[100:101]
	v_cndmask_b32_e64 v223, v219, v215, s[100:101]
	v_cndmask_b32_e64 v224, v220, v216, s[100:101]
	v_cndmask_b32_e64 v225, v221, v217, s[100:101]
	v_mov_b32_dpp v238, v222 quad_perm:[1,0,3,2] row_mask:0xf bank_mask:0xf
	v_mov_b32_dpp v239, v223 quad_perm:[1,0,3,2] row_mask:0xf bank_mask:0xf
	v_mov_b32_dpp v240, v224 quad_perm:[1,0,3,2] row_mask:0xf bank_mask:0xf
	v_mov_b32_dpp v241, v225 quad_perm:[1,0,3,2] row_mask:0xf bank_mask:0xf
	v_cndmask_b32_e64 v36, v214, v238, s[100:101]
	v_cndmask_b32_e64 v40, v238, v218, s[100:101]
	v_cndmask_b32_e64 v37, v215, v239, s[100:101]
	v_cndmask_b32_e64 v41, v239, v219, s[100:101]
	v_cndmask_b32_e64 v38, v216, v240, s[100:101]
	v_cndmask_b32_e64 v42, v240, v220, s[100:101]
	v_cndmask_b32_e64 v39, v217, v241, s[100:101]
	v_cndmask_b32_e64 v43, v241, v221, s[100:101]
	v_pk_fma_f32 v[24:25], v[24:25], v[80:81], v[38:39]
	v_pk_fma_f32 v[22:23], v[22:23], v[78:79], v[36:37]
	s_waitcnt vmcnt(0)
	v_pk_fma_f32 v[18:19], v[18:19], v[74:75], v[40:41]
	v_mul_f32_e32 v27, v23, v23
	v_mul_f32_e32 v28, v25, v25
	v_pk_fma_f32 v[20:21], v[20:21], v[76:77], v[42:43]
	v_mul_f32_e32 v29, v19, v19
	v_fmac_f32_e32 v27, v22, v22
	v_fmac_f32_e32 v28, v24, v24
	v_mul_f32_e32 v30, v21, v21
	v_fmac_f32_e32 v29, v18, v18
	v_add_f32_e32 v27, v27, v28
	v_fmac_f32_e32 v30, v20, v20
	v_add_f32_e32 v27, v27, v29
	v_add_f32_e32 v27, v30, v27
	v_add_f32_e32 v30, v26, v27
	ds_bpermute_b32 v31, v200, v30
	v_cndmask_b32_e64 v222, v18, v22, s[100:101]
	v_cndmask_b32_e64 v223, v19, v23, s[100:101]
	v_cndmask_b32_e64 v224, v20, v24, s[100:101]
	v_cndmask_b32_e64 v225, v21, v25, s[100:101]
	v_mov_b32_dpp v238, v222 quad_perm:[1,0,3,2] row_mask:0xf bank_mask:0xf
	v_mov_b32_dpp v239, v223 quad_perm:[1,0,3,2] row_mask:0xf bank_mask:0xf
	v_mov_b32_dpp v240, v224 quad_perm:[1,0,3,2] row_mask:0xf bank_mask:0xf
	v_mov_b32_dpp v241, v225 quad_perm:[1,0,3,2] row_mask:0xf bank_mask:0xf
	v_cndmask_b32_e64 v214, v22, v238, s[100:101]
	v_cndmask_b32_e64 v218, v238, v18, s[100:101]
	v_cndmask_b32_e64 v215, v23, v239, s[100:101]
	v_cndmask_b32_e64 v219, v239, v19, s[100:101]
	v_cndmask_b32_e64 v216, v24, v240, s[100:101]
	v_cndmask_b32_e64 v220, v240, v20, s[100:101]
	v_cndmask_b32_e64 v217, v25, v241, s[100:101]
	v_cndmask_b32_e64 v221, v241, v21, s[100:101]
	v_lshl_add_u64 v[226:227], v[50:51], 0, v[242:243]
	global_store_dwordx4 v[226:227], v[214:217], off offset:-3584
	global_store_dwordx4 v[226:227], v[218:221], off offset:512
	v_pk_mul_f32 v[28:29], v[58:59], v[18:19]
	v_pk_mul_f32 v[24:25], v[64:65], v[24:25]
	v_pk_mul_f32 v[22:23], v[62:63], v[22:23]
	s_waitcnt lgkmcnt(0)
	v_add_f32_e32 v18, v30, v31
	ds_bpermute_b32 v19, v195, v18
	v_pk_mul_f32 v[26:27], v[60:61], v[20:21]
	v_cvt_pk_bf16_f32 v20, v22, v23
	v_cvt_pk_bf16_f32 v21, v24, v25
	v_cvt_pk_bf16_f32 v22, v28, v29
	v_cvt_pk_bf16_f32 v23, v26, v27
	global_store_dwordx4 v[48:49], v[20:23], off offset:256
	s_and_saveexec_b64 s[34:35], s[38:39]
	s_cbranch_execz .LBB0_1253
	v_lshlrev_b64 v[20:21], 6, v[34:35]
	v_lshl_add_u64 v[20:21], s[62:63], 0, v[20:21]
	v_lshl_add_u64 v[20:21], s[24:25], 2, v[20:21]
	s_lshl_b32 s0, s56, 2
	v_lshl_add_u64 v[20:21], v[20:21], 0, s[0:1]
	s_waitcnt lgkmcnt(0)
	v_add_f32_e32 v18, v18, v19
	global_store_dword v[20:21], v18, off

; __device__ __forceinline__ unsigned pk2(float lo, float hi) { return pg8::cvt_pk_bf16(lo, hi); }
;     __device__ __forceinline__ void operator()(const f32x4 (&acc)[2][2][4][2], const pg8::Unit& u, int wr, int wc, int fr, int fq) const {
;     ...
;             for (int m = 0; m < 4; ++m) {
;                 const int R = rowbase + u.pm * 256 + ai * 128 + wr * 64 + m * 16 + fr;
;                 const float* src = islat ? rin_l + (size_t)R * DM : rin_c + (size_t)(R - TL) * DM;
;                 float* dst = islat ? rout_l + (size_t)R * DM : rout_c + (size_t)(R - TL) * DM;
;                 float ss = 0.f;
; #pragma unroll
;                 for (int bj = 0; bj < 2; ++bj) { const int c = u.pn * 256 + bj * 128 + wc * 32 + 8 * fq;
;                     const f32x4 xa = *(const f32x4*)(src + c) + gv[bj][0] * acc[ai][bj][m][0];
;                     const f32x4 xb = *(const f32x4*)(src + c + 4) + gv[bj][1] * acc[ai][bj][m][1];
;                     *(f32x4*)(dst + c) = xa; *(f32x4*)(dst + c + 4) = xb;
;                     ss += (xa[0] * xa[0] + xa[1] * xa[1]) + (xa[2] * xa[2] + xa[3] * xa[3]) + (xb[0] * xb[0] + xb[1] * xb[1]) + (xb[2] * xb[2] + xb[3] * xb[3]);
;                     const f32x4 ya = xa * sv[bj][0], yb = xb * sv[bj][1];
;                     u32x4 w; w.x = pk2(ya[0], ya[1]); w.y = pk2(ya[2], ya[3]); w.z = pk2(yb[0], yb[1]); w.w = pk2(yb[2], yb[3]);
;                     *(u32x4*)(Hn + (size_t)R * DM + c) = w; }
;                 ss += __shfl_xor(ss, 16); ss += __shfl_xor(ss, 32);
;                 if (fq == 0) stat[(size_t)R * 16 + u.pn * 4 + wc] = ss;
;             }
.LBB0_1257:
	v_cndmask_b32_e64 v22, v22, v18, s[42:43]
	v_ashrrev_i32_e32 v23, 31, v22
	v_lshlrev_b64 v[22:23], 12, v[22:23]
	v_lshl_add_u64 v[22:23], s[68:69], 0, v[22:23]
	v_lshl_add_u64 v[30:31], v[22:23], 0, v[188:189]
	v_lshl_add_u64 v[226:227], v[30:31], 0, v[242:243]
	global_load_dwordx4 v[214:217], v[226:227], off offset:-4096
	global_load_dwordx4 v[218:221], v[226:227], off
	v_lshlrev_b64 v[32:33], 11, v[18:19]
	v_lshl_add_u64 v[34:35], v[20:21], 0, v[188:189]
	v_lshl_add_u64 v[20:21], s[60:61], 0, v[32:33]
	v_lshl_add_u64 v[32:33], v[186:187], 1, v[20:21]
	s_waitcnt vmcnt(0)
	v_cndmask_b32_e64 v222, v218, v214, s[100:101]
	v_cndmask_b32_e64 v223, v219, v215, s[100:101]
	v_cndmask_b32_e64 v224, v220, v216, s[100:101]
	v_cndmask_b32_e64 v225, v221, v217, s[100:101]
	v_mov_b32_dpp v238, v222 quad_perm:[1,0,3,2] row_mask:0xf bank_mask:0xf
	v_mov_b32_dpp v239, v223 quad_perm:[1,0,3,2] row_mask:0xf bank_mask:0xf
	v_mov_b32_dpp v240, v224 quad_perm:[1,0,3,2] row_mask:0xf bank_mask:0xf
	v_mov_b32_dpp v241, v225 quad_perm:[1,0,3,2] row_mask:0xf bank_mask:0xf
	v_cndmask_b32_e64 v22, v214, v238, s[100:101]
	v_cndmask_b32_e64 v26, v238, v218, s[100:101]
	v_cndmask_b32_e64 v23, v215, v239, s[100:101]
	v_cndmask_b32_e64 v27, v239, v219, s[100:101]
	v_cndmask_b32_e64 v24, v216, v240, s[100:101]
	v_cndmask_b32_e64 v28, v240, v220, s[100:101]
	v_cndmask_b32_e64 v25, v217, v241, s[100:101]
	v_cndmask_b32_e64 v29, v241, v221, s[100:101]
	v_pk_fma_f32 v[16:17], v[16:17], v[96:97], v[24:25]
	v_pk_fma_f32 v[14:15], v[14:15], v[94:95], v[22:23]
	s_waitcnt vmcnt(0)
	v_pk_fma_f32 v[12:13], v[12:13], v[88:89], v[28:29]
	v_pk_fma_f32 v[10:11], v[10:11], v[86:87], v[26:27]
	v_pk_mul_f32 v[22:23], v[92:93], v[16:17]
	v_pk_mul_f32 v[20:21], v[90:91], v[14:15]
	v_pk_mul_f32 v[24:25], v[84:85], v[12:13]
	v_pk_mul_f32 v[26:27], v[82:83], v[10:11]
	v_cvt_pk_bf16_f32 v20, v20, v21
	v_cvt_pk_bf16_f32 v21, v22, v23
	v_cvt_pk_bf16_f32 v22, v26, v27
	v_cvt_pk_bf16_f32 v23, v24, v25
	v_cndmask_b32_e64 v222, v10, v14, s[100:101]
	v_cndmask_b32_e64 v223, v11, v15, s[100:101]
	v_cndmask_b32_e64 v224, v12, v16, s[100:101]
	v_cndmask_b32_e64 v225, v13, v17, s[100:101]
	v_mov_b32_dpp v238, v222 quad_perm:[1,0,3,2] row_mask:0xf bank_mask:0xf
	v_mov_b32_dpp v239, v223 quad_perm:[1,0,3,2] row_mask:0xf bank_mask:0xf
	v_mov_b32_dpp v240, v224 quad_perm:[1,0,3,2] row_mask:0xf bank_mask:0xf
	v_mov_b32_dpp v241, v225 quad_perm:[1,0,3,2] row_mask:0xf bank_mask:0xf
	v_cndmask_b32_e64 v214, v14, v238, s[100:101]
	v_cndmask_b32_e64 v218, v238, v10, s[100:101]
	v_cndmask_b32_e64 v215, v15, v239, s[100:101]
	v_cndmask_b32_e64 v219, v239, v11, s[100:101]
	v_cndmask_b32_e64 v216, v16, v240, s[100:101]
	v_cndmask_b32_e64 v220, v240, v12, s[100:101]
	v_cndmask_b32_e64 v217, v17, v241, s[100:101]
	v_cndmask_b32_e64 v221, v241, v13, s[100:101]
	v_lshl_add_u64 v[226:227], v[34:35], 0, v[242:243]
	global_store_dwordx4 v[226:227], v[214:217], off offset:-4096
	global_store_dwordx4 v[226:227], v[218:221], off
	global_store_dwordx4 v[32:33], v[20:23], off
	v_lshl_add_u64 v[226:227], v[30:31], 0, v[242:243]
	global_load_dwordx4 v[214:217], v[226:227], off offset:-3584
	global_load_dwordx4 v[218:221], v[226:227], off offset:512
	s_nop 0
	v_mul_f32_e32 v15, v15, v15
	v_mul_f32_e32 v17, v17, v17
	v_mul_f32_e32 v11, v11, v11
	v_fmac_f32_e32 v15, v14, v14
	v_fmac_f32_e32 v17, v16, v16
	v_mul_f32_e32 v13, v13, v13
	v_fmac_f32_e32 v11, v10, v10
	v_add_f32_e32 v10, v15, v17
	v_fmac_f32_e32 v13, v12, v12
	v_add_f32_e32 v10, v10, v11
	v_add_f32_e32 v10, v13, v10
	s_waitcnt vmcnt(0)
	v_cndmask_b32_e64 v222, v218, v214, s[100:101]
	v_cndmask_b32_e64 v223, v219, v215, s[100:101]
	v_cndmask_b32_e64 v224, v220, v216, s[100:101]
	v_cndmask_b32_e64 v225, v221, v217, s[100:101]
	v_mov_b32_dpp v238, v222 quad_perm:[1,0,3,2] row_mask:0xf bank_mask:0xf
	v_mov_b32_dpp v239, v223 quad_perm:[1,0,3,2] row_mask:0xf bank_mask:0xf
	v_mov_b32_dpp v240, v224 quad_perm:[1,0,3,2] row_mask:0xf bank_mask:0xf
	v_mov_b32_dpp v241, v225 quad_perm:[1,0,3,2] row_mask:0xf bank_mask:0xf
	v_cndmask_b32_e64 v20, v214, v238, s[100:101]
	v_cndmask_b32_e64 v24, v238, v218, s[100:101]
	v_cndmask_b32_e64 v21, v215, v239, s[100:101]
	v_cndmask_b32_e64 v25, v239, v219, s[100:101]
	v_cndmask_b32_e64 v22, v216, v240, s[100:101]
	v_cndmask_b32_e64 v26, v240, v220, s[100:101]
	v_cndmask_b32_e64 v23, v217, v241, s[100:101]
	v_cndmask_b32_e64 v27, v241, v221, s[100:101]
	v_pk_fma_f32 v[8:9], v[8:9], v[80:81], v[22:23]
	v_pk_fma_f32 v[6:7], v[6:7], v[78:79], v[20:21]
	s_waitcnt vmcnt(0)
	v_pk_fma_f32 v[2:3], v[2:3], v[74:75], v[24:25]
	v_mul_f32_e32 v11, v7, v7
	v_mul_f32_e32 v12, v9, v9
	v_pk_fma_f32 v[4:5], v[4:5], v[76:77], v[26:27]
	v_mul_f32_e32 v13, v3, v3
	v_fmac_f32_e32 v11, v6, v6
	v_fmac_f32_e32 v12, v8, v8
	v_mul_f32_e32 v14, v5, v5
	v_fmac_f32_e32 v13, v2, v2
	v_add_f32_e32 v11, v11, v12
	v_fmac_f32_e32 v14, v4, v4
	v_add_f32_e32 v11, v11, v13
	v_add_f32_e32 v11, v14, v11
	v_add_f32_e32 v14, v10, v11
	ds_bpermute_b32 v15, v200, v14
	v_cndmask_b32_e64 v222, v2, v6, s[100:101]
	v_cndmask_b32_e64 v223, v3, v7, s[100:101]
	v_cndmask_b32_e64 v224, v4, v8, s[100:101]
	v_cndmask_b32_e64 v225, v5, v9, s[100:101]
	v_mov_b32_dpp v238, v222 quad_perm:[1,0,3,2] row_mask:0xf bank_mask:0xf
	v_mov_b32_dpp v239, v223 quad_perm:[1,0,3,2] row_mask:0xf bank_mask:0xf
	v_mov_b32_dpp v240, v224 quad_perm:[1,0,3,2] row_mask:0xf bank_mask:0xf
	v_mov_b32_dpp v241, v225 quad_perm:[1,0,3,2] row_mask:0xf bank_mask:0xf
	v_cndmask_b32_e64 v214, v6, v238, s[100:101]
	v_cndmask_b32_e64 v218, v238, v2, s[100:101]
	v_cndmask_b32_e64 v215, v7, v239, s[100:101]
	v_cndmask_b32_e64 v219, v239, v3, s[100:101]
	v_cndmask_b32_e64 v216, v8, v240, s[100:101]
	v_cndmask_b32_e64 v220, v240, v4, s[100:101]
	v_cndmask_b32_e64 v217, v9, v241, s[100:101]
	v_cndmask_b32_e64 v221, v241, v5, s[100:101]
	v_lshl_add_u64 v[226:227], v[34:35], 0, v[242:243]
	global_store_dwordx4 v[226:227], v[214:217], off offset:-3584
	global_store_dwordx4 v[226:227], v[218:221], off offset:512
	v_pk_mul_f32 v[12:13], v[58:59], v[2:3]
	v_pk_mul_f32 v[8:9], v[64:65], v[8:9]
	v_pk_mul_f32 v[6:7], v[62:63], v[6:7]
	s_waitcnt lgkmcnt(0)
	v_add_f32_e32 v2, v14, v15
	ds_bpermute_b32 v3, v195, v2
	v_pk_mul_f32 v[10:11], v[60:61], v[4:5]
	v_cvt_pk_bf16_f32 v4, v6, v7
	v_cvt_pk_bf16_f32 v5, v8, v9
	v_cvt_pk_bf16_f32 v6, v12, v13
	v_cvt_pk_bf16_f32 v7, v10, v11
	global_store_dwordx4 v[32:33], v[4:7], off offset:256
	s_and_saveexec_b64 s[34:35], s[38:39]
	s_cbranch_execz .LBB0_1259
	v_lshlrev_b64 v[4:5], 6, v[18:19]
	v_lshl_add_u64 v[4:5], s[62:63], 0, v[4:5]
	v_lshl_add_u64 v[4:5], s[24:25], 2, v[4:5]
	s_lshl_b32 s0, s56, 2
	v_lshl_add_u64 v[4:5], v[4:5], 0, s[0:1]
	s_waitcnt lgkmcnt(0)
	v_add_f32_e32 v2, v2, v3
	global_store_dword v[4:5], v2, off
